# waitcnt placement: closing vmcnt(8)+lgkmcnt(0) merged into one s_waitcnt with the priority raise in front of it (nothing between the closing wait and the barrier), on top of the handover variant
# baseline (speedup 1.0000x reference)
.LBB0_297:
	s_add_u32 s0, s36, 0xfff80080
	s_addc_u32 s6, s37, -1
	s_add_i32 s49, 0, 0x10000
	s_cmp_eq_u32 s55, 28
	s_cselect_b32 s35, s25, s6
	s_cselect_b32 s34, s33, s0
	v_add_u32_e32 v156, s49, v159
	s_cselect_b32 s31, s40, s39
	s_cselect_b32 s30, s50, s38
	s_add_i32 s0, 0, 0x14000
	ds_read_b128 v[144:147], v156
	ds_read_b128 v[148:151], v156 offset:1024
	ds_read_b128 v[152:155], v156 offset:2048
	ds_read_b128 v[164:167], v156 offset:3072
	v_add_u32_e32 v156, s0, v159
	ds_read_b128 v[168:171], v156
	ds_read_b128 v[172:175], v156 offset:1024
	ds_read_b128 v[176:179], v156 offset:2048
	ds_read_b128 v[180:183], v156 offset:3072
	v_lshl_add_u64 v[156:157], s[36:37], 0, v[140:141]
	s_add_i32 m0, s47, 0xc000
	ds_read_b128 v[184:187], v163
	ds_read_b128 v[188:191], v163 offset:1024
	ds_read_b128 v[192:195], v163 offset:2048
	ds_read_b128 v[200:203], v163 offset:3072
	ds_read_b128 v[204:207], v163 offset:4096
	ds_read_b128 v[208:211], v163 offset:5120
	ds_read_b128 v[212:215], v163 offset:6144
	ds_read_b128 v[216:219], v163 offset:7168
	global_load_lds_dwordx4 v[156:157], off
	v_lshl_add_u64 v[156:157], s[36:37], 0, v[142:143]
	s_add_i32 m0, s47, 0xe000
	s_nop 0
	global_load_lds_dwordx4 v[156:157], off
	s_setprio 1
	s_waitcnt vmcnt(8) lgkmcnt(0)
	s_barrier
	v_mfma_f32_16x16x32_bf16 v[128:131], v[144:147], v[184:187], v[128:131]
	v_mfma_f32_16x16x32_bf16 v[124:127], v[152:155], v[184:187], v[124:127]
	v_mfma_f32_16x16x32_bf16 v[112:115], v[144:147], v[192:195], v[112:115]
	v_mfma_f32_16x16x32_bf16 v[108:111], v[152:155], v[192:195], v[108:111]
	v_mfma_f32_16x16x32_bf16 v[96:99], v[144:147], v[204:207], v[96:99]
	v_mfma_f32_16x16x32_bf16 v[92:95], v[152:155], v[204:207], v[92:95]
	v_mfma_f32_16x16x32_bf16 v[80:83], v[144:147], v[212:215], v[80:83]
	v_mfma_f32_16x16x32_bf16 v[76:79], v[152:155], v[212:215], v[76:79]
	v_mfma_f32_16x16x32_bf16 v[128:131], v[148:151], v[188:191], v[128:131]
	v_mfma_f32_16x16x32_bf16 v[124:127], v[164:167], v[188:191], v[124:127]
	v_mfma_f32_16x16x32_bf16 v[112:115], v[148:151], v[200:203], v[112:115]
	v_mfma_f32_16x16x32_bf16 v[108:111], v[164:167], v[200:203], v[108:111]
	v_mfma_f32_16x16x32_bf16 v[96:99], v[148:151], v[208:211], v[96:99]
	v_mfma_f32_16x16x32_bf16 v[92:95], v[164:167], v[208:211], v[92:95]
	v_mfma_f32_16x16x32_bf16 v[80:83], v[148:151], v[216:219], v[80:83]
	v_mfma_f32_16x16x32_bf16 v[76:79], v[164:167], v[216:219], v[76:79]
	s_setprio 0
	s_setprio 1
	v_mfma_f32_16x16x32_bf16 v[120:123], v[168:171], v[184:187], v[120:123]
	v_mfma_f32_16x16x32_bf16 v[116:119], v[176:179], v[184:187], v[116:119]
	v_mfma_f32_16x16x32_bf16 v[104:107], v[168:171], v[192:195], v[104:107]
	v_mfma_f32_16x16x32_bf16 v[100:103], v[176:179], v[192:195], v[100:103]
	v_mfma_f32_16x16x32_bf16 v[88:91], v[168:171], v[204:207], v[88:91]
	v_mfma_f32_16x16x32_bf16 v[84:87], v[176:179], v[204:207], v[84:87]
	v_mfma_f32_16x16x32_bf16 v[72:75], v[168:171], v[212:215], v[72:75]
	v_mfma_f32_16x16x32_bf16 v[68:71], v[176:179], v[212:215], v[68:71]
	v_mfma_f32_16x16x32_bf16 v[120:123], v[172:175], v[188:191], v[120:123]
	v_mfma_f32_16x16x32_bf16 v[116:119], v[180:183], v[188:191], v[116:119]
	v_mfma_f32_16x16x32_bf16 v[104:107], v[172:175], v[200:203], v[104:107]
	v_mfma_f32_16x16x32_bf16 v[100:103], v[180:183], v[200:203], v[100:103]
	v_mfma_f32_16x16x32_bf16 v[88:91], v[172:175], v[208:211], v[88:91]
	v_mfma_f32_16x16x32_bf16 v[84:87], v[180:183], v[208:211], v[84:87]
	v_mfma_f32_16x16x32_bf16 v[72:75], v[172:175], v[216:219], v[72:75]
	v_mfma_f32_16x16x32_bf16 v[68:71], v[180:183], v[216:219], v[68:71]
	s_barrier
	s_setprio 0
	s_add_i32 s6, s49, s46
	v_lshl_add_u64 v[156:157], s[30:31], 0, v[136:137]
	s_mov_b32 m0, s6
	ds_read_b128 v[184:187], v163 offset:16384
	ds_read_b128 v[188:191], v163 offset:17408
	ds_read_b128 v[192:195], v163 offset:18432
	ds_read_b128 v[200:203], v163 offset:19456
	ds_read_b128 v[204:207], v163 offset:20480
	ds_read_b128 v[208:211], v163 offset:21504
	ds_read_b128 v[212:215], v163 offset:22528
	ds_read_b128 v[216:219], v163 offset:23552
	global_load_lds_dwordx4 v[156:157], off
	s_add_i32 m0, s6, 0x2000
	s_add_u32 s66, s30, 0x80000
	v_lshl_add_u64 v[220:221], s[30:31], 0, v[132:133]
	s_addc_u32 s67, s31, 0
	s_add_i32 s0, s0, s46
	global_load_lds_dwordx4 v[220:221], off
	v_lshl_add_u64 v[222:223], s[66:67], 0, v[136:137]
	s_mov_b32 m0, s0
	v_lshl_add_u64 v[224:225], s[34:35], 0, v[134:135]
	global_load_lds_dwordx4 v[222:223], off
	v_lshl_add_u64 v[222:223], s[66:67], 0, v[132:133]
	s_add_i32 m0, s0, 0x2000
	s_nop 0
	global_load_lds_dwordx4 v[222:223], off
	v_lshl_add_u64 v[222:223], s[34:35], 0, v[138:139]
	s_mov_b32 m0, s47
	s_nop 0
	global_load_lds_dwordx4 v[222:223], off
	s_mov_b32 m0, s52
	s_nop 0
	global_load_lds_dwordx4 v[224:225], off
	s_setprio 1
	s_waitcnt vmcnt(8) lgkmcnt(0)
	s_barrier
	v_mfma_f32_16x16x32_bf16 v[64:67], v[144:147], v[184:187], v[64:67]
	v_mfma_f32_16x16x32_bf16 v[60:63], v[152:155], v[184:187], v[60:63]
	v_mfma_f32_16x16x32_bf16 v[48:51], v[144:147], v[192:195], v[48:51]
	v_mfma_f32_16x16x32_bf16 v[44:47], v[152:155], v[192:195], v[44:47]
	v_mfma_f32_16x16x32_bf16 v[32:35], v[144:147], v[204:207], v[32:35]
	v_mfma_f32_16x16x32_bf16 v[28:31], v[152:155], v[204:207], v[28:31]
	v_mfma_f32_16x16x32_bf16 v[16:19], v[144:147], v[212:215], v[16:19]
	v_mfma_f32_16x16x32_bf16 v[12:15], v[152:155], v[212:215], v[12:15]
	v_mfma_f32_16x16x32_bf16 v[64:67], v[148:151], v[188:191], v[64:67]
	v_mfma_f32_16x16x32_bf16 v[60:63], v[164:167], v[188:191], v[60:63]
	v_mfma_f32_16x16x32_bf16 v[48:51], v[148:151], v[200:203], v[48:51]
	v_mfma_f32_16x16x32_bf16 v[44:47], v[164:167], v[200:203], v[44:47]
	v_mfma_f32_16x16x32_bf16 v[32:35], v[148:151], v[208:211], v[32:35]
	v_mfma_f32_16x16x32_bf16 v[28:31], v[164:167], v[208:211], v[28:31]
	v_mfma_f32_16x16x32_bf16 v[16:19], v[148:151], v[216:219], v[16:19]
	v_mfma_f32_16x16x32_bf16 v[12:15], v[164:167], v[216:219], v[12:15]
	s_setprio 0
	s_setprio 1
	v_mfma_f32_16x16x32_bf16 v[56:59], v[168:171], v[184:187], v[56:59]
	v_mfma_f32_16x16x32_bf16 v[52:55], v[176:179], v[184:187], v[52:55]
	v_mfma_f32_16x16x32_bf16 v[40:43], v[168:171], v[192:195], v[40:43]
	v_mfma_f32_16x16x32_bf16 v[36:39], v[176:179], v[192:195], v[36:39]
	v_mfma_f32_16x16x32_bf16 v[24:27], v[168:171], v[204:207], v[24:27]
	v_mfma_f32_16x16x32_bf16 v[20:23], v[176:179], v[204:207], v[20:23]
	v_mfma_f32_16x16x32_bf16 v[8:11], v[168:171], v[212:215], v[8:11]
	v_mfma_f32_16x16x32_bf16 v[4:7], v[176:179], v[212:215], v[4:7]
	v_mfma_f32_16x16x32_bf16 v[56:59], v[172:175], v[188:191], v[56:59]
	v_mfma_f32_16x16x32_bf16 v[52:55], v[180:183], v[188:191], v[52:55]
	v_mfma_f32_16x16x32_bf16 v[40:43], v[172:175], v[200:203], v[40:43]
	v_mfma_f32_16x16x32_bf16 v[36:39], v[180:183], v[200:203], v[36:39]
	v_mfma_f32_16x16x32_bf16 v[24:27], v[172:175], v[208:211], v[24:27]
	v_mfma_f32_16x16x32_bf16 v[20:23], v[180:183], v[208:211], v[20:23]
	v_mfma_f32_16x16x32_bf16 v[8:11], v[172:175], v[216:219], v[8:11]
	v_mfma_f32_16x16x32_bf16 v[4:7], v[180:183], v[216:219], v[4:7]
	s_barrier
	s_setprio 0
	s_add_i32 s0, 0, 0x18000
	v_add_u32_e32 v158, s0, v159
	s_add_i32 s6, 0, 0x1c000
	ds_read_b128 v[144:147], v158
	ds_read_b128 v[148:151], v158 offset:1024
	ds_read_b128 v[152:155], v158 offset:2048
	ds_read_b128 v[164:167], v158 offset:3072
	v_add_u32_e32 v158, s6, v159
	ds_read_b128 v[168:171], v158
	ds_read_b128 v[172:175], v158 offset:1024
	ds_read_b128 v[176:179], v158 offset:2048
	ds_read_b128 v[180:183], v158 offset:3072
	s_add_u32 s34, s34, 0x80000
	s_addc_u32 s35, s35, 0
	s_mov_b32 m0, s53
	v_lshl_add_u64 v[226:227], s[34:35], 0, v[138:139]
	ds_read_b128 v[184:187], v163 offset:32768
	ds_read_b128 v[188:191], v163 offset:33792
	ds_read_b128 v[192:195], v163 offset:34816
	ds_read_b128 v[200:203], v163 offset:35840
	ds_read_b128 v[204:207], v163 offset:36864
	ds_read_b128 v[208:211], v163 offset:37888
	ds_read_b128 v[212:215], v163 offset:38912
	ds_read_b128 v[216:219], v163 offset:39936
	global_load_lds_dwordx4 v[226:227], off
	v_lshl_add_u64 v[226:227], s[34:35], 0, v[134:135]
	s_mov_b32 m0, s60
	s_nop 0
	global_load_lds_dwordx4 v[226:227], off
	s_setprio 1
	s_waitcnt vmcnt(8) lgkmcnt(0)
	s_barrier
	v_mfma_f32_16x16x32_bf16 v[128:131], v[144:147], v[184:187], v[128:131]
	v_mfma_f32_16x16x32_bf16 v[124:127], v[152:155], v[184:187], v[124:127]
	v_mfma_f32_16x16x32_bf16 v[112:115], v[144:147], v[192:195], v[112:115]
	v_mfma_f32_16x16x32_bf16 v[108:111], v[152:155], v[192:195], v[108:111]
	v_mfma_f32_16x16x32_bf16 v[96:99], v[144:147], v[204:207], v[96:99]
	v_mfma_f32_16x16x32_bf16 v[92:95], v[152:155], v[204:207], v[92:95]
	v_mfma_f32_16x16x32_bf16 v[80:83], v[144:147], v[212:215], v[80:83]
	v_mfma_f32_16x16x32_bf16 v[76:79], v[152:155], v[212:215], v[76:79]
	v_mfma_f32_16x16x32_bf16 v[128:131], v[148:151], v[188:191], v[128:131]
	v_mfma_f32_16x16x32_bf16 v[124:127], v[164:167], v[188:191], v[124:127]
	v_mfma_f32_16x16x32_bf16 v[112:115], v[148:151], v[200:203], v[112:115]
	v_mfma_f32_16x16x32_bf16 v[108:111], v[164:167], v[200:203], v[108:111]
	v_mfma_f32_16x16x32_bf16 v[96:99], v[148:151], v[208:211], v[96:99]
	v_mfma_f32_16x16x32_bf16 v[92:95], v[164:167], v[208:211], v[92:95]
	v_mfma_f32_16x16x32_bf16 v[80:83], v[148:151], v[216:219], v[80:83]
	v_mfma_f32_16x16x32_bf16 v[76:79], v[164:167], v[216:219], v[76:79]
	s_setprio 0
	s_setprio 1
	v_mfma_f32_16x16x32_bf16 v[120:123], v[168:171], v[184:187], v[120:123]
	v_mfma_f32_16x16x32_bf16 v[116:119], v[176:179], v[184:187], v[116:119]
	v_mfma_f32_16x16x32_bf16 v[104:107], v[168:171], v[192:195], v[104:107]
	v_mfma_f32_16x16x32_bf16 v[100:103], v[176:179], v[192:195], v[100:103]
	v_mfma_f32_16x16x32_bf16 v[88:91], v[168:171], v[204:207], v[88:91]
	v_mfma_f32_16x16x32_bf16 v[84:87], v[176:179], v[204:207], v[84:87]
	v_mfma_f32_16x16x32_bf16 v[72:75], v[168:171], v[212:215], v[72:75]
	v_mfma_f32_16x16x32_bf16 v[68:71], v[176:179], v[212:215], v[68:71]
	v_mfma_f32_16x16x32_bf16 v[120:123], v[172:175], v[188:191], v[120:123]
	v_mfma_f32_16x16x32_bf16 v[116:119], v[180:183], v[188:191], v[116:119]
	v_mfma_f32_16x16x32_bf16 v[104:107], v[172:175], v[200:203], v[104:107]
	v_mfma_f32_16x16x32_bf16 v[100:103], v[180:183], v[200:203], v[100:103]
	v_mfma_f32_16x16x32_bf16 v[88:91], v[172:175], v[208:211], v[88:91]
	v_mfma_f32_16x16x32_bf16 v[84:87], v[180:183], v[208:211], v[84:87]
	v_mfma_f32_16x16x32_bf16 v[72:75], v[172:175], v[216:219], v[72:75]
	v_mfma_f32_16x16x32_bf16 v[68:71], v[180:183], v[216:219], v[68:71]
	s_barrier
	s_setprio 0
	s_add_i32 s0, s0, s46
	v_lshl_add_u64 v[156:157], v[156:157], 0, s[90:91]
	s_mov_b32 m0, s0
	ds_read_b128 v[184:187], v163 offset:49152
	ds_read_b128 v[188:191], v163 offset:50176
	ds_read_b128 v[192:195], v163 offset:51200
	ds_read_b128 v[200:203], v163 offset:52224
	ds_read_b128 v[204:207], v163 offset:53248
	ds_read_b128 v[208:211], v163 offset:54272
	ds_read_b128 v[212:215], v163 offset:55296
	ds_read_b128 v[216:219], v163 offset:56320
	global_load_lds_dwordx4 v[156:157], off
	s_add_i32 m0, s0, 0x2000
	s_add_u32 s30, s30, 0x80080
	v_lshl_add_u64 v[156:157], v[220:221], 0, s[90:91]
	s_addc_u32 s31, s31, 0
	s_add_i32 s0, s6, s46
	global_load_lds_dwordx4 v[156:157], off
	v_lshl_add_u64 v[156:157], s[30:31], 0, v[136:137]
	s_mov_b32 m0, s0
	s_nop 0
	global_load_lds_dwordx4 v[156:157], off
	v_lshl_add_u64 v[156:157], s[30:31], 0, v[132:133]
	s_add_i32 m0, s0, 0x2000
	s_nop 0
	global_load_lds_dwordx4 v[156:157], off
	v_lshl_add_u64 v[156:157], v[222:223], 0, s[90:91]
	s_mov_b32 m0, s62
	s_nop 0
	global_load_lds_dwordx4 v[156:157], off
	v_lshl_add_u64 v[156:157], v[224:225], 0, s[90:91]
	s_mov_b32 m0, s51
	s_nop 0
	global_load_lds_dwordx4 v[156:157], off
	s_setprio 1
	s_waitcnt vmcnt(8) lgkmcnt(0)
	s_barrier
	v_mfma_f32_16x16x32_bf16 v[64:67], v[144:147], v[184:187], v[64:67]
	v_mfma_f32_16x16x32_bf16 v[60:63], v[152:155], v[184:187], v[60:63]
	v_mfma_f32_16x16x32_bf16 v[48:51], v[144:147], v[192:195], v[48:51]
	v_mfma_f32_16x16x32_bf16 v[44:47], v[152:155], v[192:195], v[44:47]
	v_mfma_f32_16x16x32_bf16 v[32:35], v[144:147], v[204:207], v[32:35]
	v_mfma_f32_16x16x32_bf16 v[28:31], v[152:155], v[204:207], v[28:31]
	v_mfma_f32_16x16x32_bf16 v[16:19], v[144:147], v[212:215], v[16:19]
	v_mfma_f32_16x16x32_bf16 v[12:15], v[152:155], v[212:215], v[12:15]
	v_mfma_f32_16x16x32_bf16 v[64:67], v[148:151], v[188:191], v[64:67]
	v_mfma_f32_16x16x32_bf16 v[60:63], v[164:167], v[188:191], v[60:63]
	v_mfma_f32_16x16x32_bf16 v[48:51], v[148:151], v[200:203], v[48:51]
	v_mfma_f32_16x16x32_bf16 v[44:47], v[164:167], v[200:203], v[44:47]
	v_mfma_f32_16x16x32_bf16 v[32:35], v[148:151], v[208:211], v[32:35]
	v_mfma_f32_16x16x32_bf16 v[28:31], v[164:167], v[208:211], v[28:31]
	v_mfma_f32_16x16x32_bf16 v[16:19], v[148:151], v[216:219], v[16:19]
	v_mfma_f32_16x16x32_bf16 v[12:15], v[164:167], v[216:219], v[12:15]
	s_setprio 0
	s_setprio 1
	v_mfma_f32_16x16x32_bf16 v[56:59], v[168:171], v[184:187], v[56:59]
	v_mfma_f32_16x16x32_bf16 v[52:55], v[176:179], v[184:187], v[52:55]
	v_mfma_f32_16x16x32_bf16 v[40:43], v[168:171], v[192:195], v[40:43]
	v_mfma_f32_16x16x32_bf16 v[36:39], v[176:179], v[192:195], v[36:39]
	v_mfma_f32_16x16x32_bf16 v[24:27], v[168:171], v[204:207], v[24:27]
	v_mfma_f32_16x16x32_bf16 v[20:23], v[176:179], v[204:207], v[20:23]
	v_mfma_f32_16x16x32_bf16 v[8:11], v[168:171], v[212:215], v[8:11]
	v_mfma_f32_16x16x32_bf16 v[4:7], v[176:179], v[212:215], v[4:7]
	v_mfma_f32_16x16x32_bf16 v[56:59], v[172:175], v[188:191], v[56:59]
	v_mfma_f32_16x16x32_bf16 v[52:55], v[180:183], v[188:191], v[52:55]
	v_mfma_f32_16x16x32_bf16 v[40:43], v[172:175], v[200:203], v[40:43]
	v_mfma_f32_16x16x32_bf16 v[36:39], v[180:183], v[200:203], v[36:39]
	v_mfma_f32_16x16x32_bf16 v[24:27], v[172:175], v[208:211], v[24:27]
	v_mfma_f32_16x16x32_bf16 v[20:23], v[180:183], v[208:211], v[20:23]
	v_mfma_f32_16x16x32_bf16 v[8:11], v[172:175], v[216:219], v[8:11]
	v_mfma_f32_16x16x32_bf16 v[4:7], v[180:183], v[216:219], v[4:7]
	s_barrier
	s_setprio 0
	s_add_i32 s55, s55, 2
	s_add_u32 s36, s36, 0x100
	s_addc_u32 s37, s37, 0
	s_add_u32 s38, s38, 0x100
	s_addc_u32 s39, s39, 0
	s_cmp_gt_u32 s55, 29
	s_cbranch_scc0 .LBB0_297
	s_and_b64 vcc, exec, s[22:23]
	s_cbranch_vccz .LBB0_300
	s_barrier

.LBB0_336:
	s_add_u32 s0, s36, 0xfff80080
	s_addc_u32 s6, s37, -1
	s_add_i32 s49, 0, 0x10000
	s_cmp_eq_u32 s50, 28
	s_cselect_b32 s35, s24, s6
	s_cselect_b32 s34, s25, s0
	v_add_u32_e32 v156, s49, v159
	s_cselect_b32 s31, s33, s39
	s_cselect_b32 s30, s40, s38
	s_add_i32 s0, 0, 0x14000
	ds_read_b128 v[144:147], v156
	ds_read_b128 v[148:151], v156 offset:1024
	ds_read_b128 v[152:155], v156 offset:2048
	ds_read_b128 v[164:167], v156 offset:3072
	v_add_u32_e32 v156, s0, v159
	ds_read_b128 v[168:171], v156
	ds_read_b128 v[172:175], v156 offset:1024
	ds_read_b128 v[176:179], v156 offset:2048
	ds_read_b128 v[180:183], v156 offset:3072
	v_lshl_add_u64 v[156:157], s[36:37], 0, v[140:141]
	s_add_i32 m0, s45, 0xc000
	ds_read_b128 v[184:187], v163
	ds_read_b128 v[188:191], v163 offset:1024
	ds_read_b128 v[192:195], v163 offset:2048
	ds_read_b128 v[200:203], v163 offset:3072
	ds_read_b128 v[204:207], v163 offset:4096
	ds_read_b128 v[208:211], v163 offset:5120
	ds_read_b128 v[212:215], v163 offset:6144
	ds_read_b128 v[216:219], v163 offset:7168
	global_load_lds_dwordx4 v[156:157], off
	v_lshl_add_u64 v[156:157], s[36:37], 0, v[142:143]
	s_add_i32 m0, s45, 0xe000
	s_nop 0
	global_load_lds_dwordx4 v[156:157], off
	s_setprio 1
	s_waitcnt vmcnt(8) lgkmcnt(0)
	s_barrier
	v_mfma_f32_16x16x32_bf16 v[128:131], v[144:147], v[184:187], v[128:131]
	v_mfma_f32_16x16x32_bf16 v[124:127], v[152:155], v[184:187], v[124:127]
	v_mfma_f32_16x16x32_bf16 v[112:115], v[144:147], v[192:195], v[112:115]
	v_mfma_f32_16x16x32_bf16 v[108:111], v[152:155], v[192:195], v[108:111]
	v_mfma_f32_16x16x32_bf16 v[96:99], v[144:147], v[204:207], v[96:99]
	v_mfma_f32_16x16x32_bf16 v[92:95], v[152:155], v[204:207], v[92:95]
	v_mfma_f32_16x16x32_bf16 v[80:83], v[144:147], v[212:215], v[80:83]
	v_mfma_f32_16x16x32_bf16 v[76:79], v[152:155], v[212:215], v[76:79]
	v_mfma_f32_16x16x32_bf16 v[128:131], v[148:151], v[188:191], v[128:131]
	v_mfma_f32_16x16x32_bf16 v[124:127], v[164:167], v[188:191], v[124:127]
	v_mfma_f32_16x16x32_bf16 v[112:115], v[148:151], v[200:203], v[112:115]
	v_mfma_f32_16x16x32_bf16 v[108:111], v[164:167], v[200:203], v[108:111]
	v_mfma_f32_16x16x32_bf16 v[96:99], v[148:151], v[208:211], v[96:99]
	v_mfma_f32_16x16x32_bf16 v[92:95], v[164:167], v[208:211], v[92:95]
	v_mfma_f32_16x16x32_bf16 v[80:83], v[148:151], v[216:219], v[80:83]
	v_mfma_f32_16x16x32_bf16 v[76:79], v[164:167], v[216:219], v[76:79]
	s_setprio 0
	s_setprio 1
	v_mfma_f32_16x16x32_bf16 v[120:123], v[168:171], v[184:187], v[120:123]
	v_mfma_f32_16x16x32_bf16 v[116:119], v[176:179], v[184:187], v[116:119]
	v_mfma_f32_16x16x32_bf16 v[104:107], v[168:171], v[192:195], v[104:107]
	v_mfma_f32_16x16x32_bf16 v[100:103], v[176:179], v[192:195], v[100:103]
	v_mfma_f32_16x16x32_bf16 v[88:91], v[168:171], v[204:207], v[88:91]
	v_mfma_f32_16x16x32_bf16 v[84:87], v[176:179], v[204:207], v[84:87]
	v_mfma_f32_16x16x32_bf16 v[72:75], v[168:171], v[212:215], v[72:75]
	v_mfma_f32_16x16x32_bf16 v[68:71], v[176:179], v[212:215], v[68:71]
	v_mfma_f32_16x16x32_bf16 v[120:123], v[172:175], v[188:191], v[120:123]
	v_mfma_f32_16x16x32_bf16 v[116:119], v[180:183], v[188:191], v[116:119]
	v_mfma_f32_16x16x32_bf16 v[104:107], v[172:175], v[200:203], v[104:107]
	v_mfma_f32_16x16x32_bf16 v[100:103], v[180:183], v[200:203], v[100:103]
	v_mfma_f32_16x16x32_bf16 v[88:91], v[172:175], v[208:211], v[88:91]
	v_mfma_f32_16x16x32_bf16 v[84:87], v[180:183], v[208:211], v[84:87]
	v_mfma_f32_16x16x32_bf16 v[72:75], v[172:175], v[216:219], v[72:75]
	v_mfma_f32_16x16x32_bf16 v[68:71], v[180:183], v[216:219], v[68:71]
	s_barrier
	s_setprio 0
	s_add_i32 s6, s49, s47
	v_lshl_add_u64 v[156:157], s[30:31], 0, v[136:137]
	s_mov_b32 m0, s6
	ds_read_b128 v[184:187], v163 offset:16384
	ds_read_b128 v[188:191], v163 offset:17408
	ds_read_b128 v[192:195], v163 offset:18432
	ds_read_b128 v[200:203], v163 offset:19456
	ds_read_b128 v[204:207], v163 offset:20480
	ds_read_b128 v[208:211], v163 offset:21504
	ds_read_b128 v[212:215], v163 offset:22528
	ds_read_b128 v[216:219], v163 offset:23552
	global_load_lds_dwordx4 v[156:157], off
	s_add_i32 m0, s6, 0x2000
	s_add_u32 s54, s30, 0x80000
	v_lshl_add_u64 v[220:221], s[30:31], 0, v[132:133]
	s_addc_u32 s55, s31, 0
	s_add_i32 s0, s0, s47
	global_load_lds_dwordx4 v[220:221], off
	v_lshl_add_u64 v[222:223], s[54:55], 0, v[136:137]
	s_mov_b32 m0, s0
	v_lshl_add_u64 v[224:225], s[34:35], 0, v[134:135]
	global_load_lds_dwordx4 v[222:223], off
	v_lshl_add_u64 v[222:223], s[54:55], 0, v[132:133]
	s_add_i32 m0, s0, 0x2000
	s_nop 0
	global_load_lds_dwordx4 v[222:223], off
	v_lshl_add_u64 v[222:223], s[34:35], 0, v[138:139]
	s_mov_b32 m0, s45
	s_nop 0
	global_load_lds_dwordx4 v[222:223], off
	s_mov_b32 m0, s61
	s_nop 0
	global_load_lds_dwordx4 v[224:225], off
	s_setprio 1
	s_waitcnt vmcnt(8) lgkmcnt(0)
	s_barrier
	v_mfma_f32_16x16x32_bf16 v[64:67], v[144:147], v[184:187], v[64:67]
	v_mfma_f32_16x16x32_bf16 v[60:63], v[152:155], v[184:187], v[60:63]
	v_mfma_f32_16x16x32_bf16 v[48:51], v[144:147], v[192:195], v[48:51]
	v_mfma_f32_16x16x32_bf16 v[44:47], v[152:155], v[192:195], v[44:47]
	v_mfma_f32_16x16x32_bf16 v[32:35], v[144:147], v[204:207], v[32:35]
	v_mfma_f32_16x16x32_bf16 v[28:31], v[152:155], v[204:207], v[28:31]
	v_mfma_f32_16x16x32_bf16 v[16:19], v[144:147], v[212:215], v[16:19]
	v_mfma_f32_16x16x32_bf16 v[12:15], v[152:155], v[212:215], v[12:15]
	v_mfma_f32_16x16x32_bf16 v[64:67], v[148:151], v[188:191], v[64:67]
	v_mfma_f32_16x16x32_bf16 v[60:63], v[164:167], v[188:191], v[60:63]
	v_mfma_f32_16x16x32_bf16 v[48:51], v[148:151], v[200:203], v[48:51]
	v_mfma_f32_16x16x32_bf16 v[44:47], v[164:167], v[200:203], v[44:47]
	v_mfma_f32_16x16x32_bf16 v[32:35], v[148:151], v[208:211], v[32:35]
	v_mfma_f32_16x16x32_bf16 v[28:31], v[164:167], v[208:211], v[28:31]
	v_mfma_f32_16x16x32_bf16 v[16:19], v[148:151], v[216:219], v[16:19]
	v_mfma_f32_16x16x32_bf16 v[12:15], v[164:167], v[216:219], v[12:15]
	s_setprio 0
	s_setprio 1
	v_mfma_f32_16x16x32_bf16 v[56:59], v[168:171], v[184:187], v[56:59]
	v_mfma_f32_16x16x32_bf16 v[52:55], v[176:179], v[184:187], v[52:55]
	v_mfma_f32_16x16x32_bf16 v[40:43], v[168:171], v[192:195], v[40:43]
	v_mfma_f32_16x16x32_bf16 v[36:39], v[176:179], v[192:195], v[36:39]
	v_mfma_f32_16x16x32_bf16 v[24:27], v[168:171], v[204:207], v[24:27]
	v_mfma_f32_16x16x32_bf16 v[20:23], v[176:179], v[204:207], v[20:23]
	v_mfma_f32_16x16x32_bf16 v[8:11], v[168:171], v[212:215], v[8:11]
	v_mfma_f32_16x16x32_bf16 v[4:7], v[176:179], v[212:215], v[4:7]
	v_mfma_f32_16x16x32_bf16 v[56:59], v[172:175], v[188:191], v[56:59]
	v_mfma_f32_16x16x32_bf16 v[52:55], v[180:183], v[188:191], v[52:55]
	v_mfma_f32_16x16x32_bf16 v[40:43], v[172:175], v[200:203], v[40:43]
	v_mfma_f32_16x16x32_bf16 v[36:39], v[180:183], v[200:203], v[36:39]
	v_mfma_f32_16x16x32_bf16 v[24:27], v[172:175], v[208:211], v[24:27]
	v_mfma_f32_16x16x32_bf16 v[20:23], v[180:183], v[208:211], v[20:23]
	v_mfma_f32_16x16x32_bf16 v[8:11], v[172:175], v[216:219], v[8:11]
	v_mfma_f32_16x16x32_bf16 v[4:7], v[180:183], v[216:219], v[4:7]
	s_barrier
	s_setprio 0
	s_add_i32 s0, 0, 0x18000
	v_add_u32_e32 v158, s0, v159
	s_add_i32 s6, 0, 0x1c000
	ds_read_b128 v[144:147], v158
	ds_read_b128 v[148:151], v158 offset:1024
	ds_read_b128 v[152:155], v158 offset:2048
	ds_read_b128 v[164:167], v158 offset:3072
	v_add_u32_e32 v158, s6, v159
	ds_read_b128 v[168:171], v158
	ds_read_b128 v[172:175], v158 offset:1024
	ds_read_b128 v[176:179], v158 offset:2048
	ds_read_b128 v[180:183], v158 offset:3072
	s_add_u32 s34, s34, 0x80000
	s_addc_u32 s35, s35, 0
	s_mov_b32 m0, s62
	v_lshl_add_u64 v[226:227], s[34:35], 0, v[138:139]
	ds_read_b128 v[184:187], v163 offset:32768
	ds_read_b128 v[188:191], v163 offset:33792
	ds_read_b128 v[192:195], v163 offset:34816
	ds_read_b128 v[200:203], v163 offset:35840
	ds_read_b128 v[204:207], v163 offset:36864
	ds_read_b128 v[208:211], v163 offset:37888
	ds_read_b128 v[212:215], v163 offset:38912
	ds_read_b128 v[216:219], v163 offset:39936
	global_load_lds_dwordx4 v[226:227], off
	v_lshl_add_u64 v[226:227], s[34:35], 0, v[134:135]
	s_mov_b32 m0, s63
	s_nop 0
	global_load_lds_dwordx4 v[226:227], off
	s_setprio 1
	s_waitcnt vmcnt(8) lgkmcnt(0)
	s_barrier
	v_mfma_f32_16x16x32_bf16 v[128:131], v[144:147], v[184:187], v[128:131]
	v_mfma_f32_16x16x32_bf16 v[124:127], v[152:155], v[184:187], v[124:127]
	v_mfma_f32_16x16x32_bf16 v[112:115], v[144:147], v[192:195], v[112:115]
	v_mfma_f32_16x16x32_bf16 v[108:111], v[152:155], v[192:195], v[108:111]
	v_mfma_f32_16x16x32_bf16 v[96:99], v[144:147], v[204:207], v[96:99]
	v_mfma_f32_16x16x32_bf16 v[92:95], v[152:155], v[204:207], v[92:95]
	v_mfma_f32_16x16x32_bf16 v[80:83], v[144:147], v[212:215], v[80:83]
	v_mfma_f32_16x16x32_bf16 v[76:79], v[152:155], v[212:215], v[76:79]
	v_mfma_f32_16x16x32_bf16 v[128:131], v[148:151], v[188:191], v[128:131]
	v_mfma_f32_16x16x32_bf16 v[124:127], v[164:167], v[188:191], v[124:127]
	v_mfma_f32_16x16x32_bf16 v[112:115], v[148:151], v[200:203], v[112:115]
	v_mfma_f32_16x16x32_bf16 v[108:111], v[164:167], v[200:203], v[108:111]
	v_mfma_f32_16x16x32_bf16 v[96:99], v[148:151], v[208:211], v[96:99]
	v_mfma_f32_16x16x32_bf16 v[92:95], v[164:167], v[208:211], v[92:95]
	v_mfma_f32_16x16x32_bf16 v[80:83], v[148:151], v[216:219], v[80:83]
	v_mfma_f32_16x16x32_bf16 v[76:79], v[164:167], v[216:219], v[76:79]
	s_setprio 0
	s_setprio 1
	v_mfma_f32_16x16x32_bf16 v[120:123], v[168:171], v[184:187], v[120:123]
	v_mfma_f32_16x16x32_bf16 v[116:119], v[176:179], v[184:187], v[116:119]
	v_mfma_f32_16x16x32_bf16 v[104:107], v[168:171], v[192:195], v[104:107]
	v_mfma_f32_16x16x32_bf16 v[100:103], v[176:179], v[192:195], v[100:103]
	v_mfma_f32_16x16x32_bf16 v[88:91], v[168:171], v[204:207], v[88:91]
	v_mfma_f32_16x16x32_bf16 v[84:87], v[176:179], v[204:207], v[84:87]
	v_mfma_f32_16x16x32_bf16 v[72:75], v[168:171], v[212:215], v[72:75]
	v_mfma_f32_16x16x32_bf16 v[68:71], v[176:179], v[212:215], v[68:71]
	v_mfma_f32_16x16x32_bf16 v[120:123], v[172:175], v[188:191], v[120:123]
	v_mfma_f32_16x16x32_bf16 v[116:119], v[180:183], v[188:191], v[116:119]
	v_mfma_f32_16x16x32_bf16 v[104:107], v[172:175], v[200:203], v[104:107]
	v_mfma_f32_16x16x32_bf16 v[100:103], v[180:183], v[200:203], v[100:103]
	v_mfma_f32_16x16x32_bf16 v[88:91], v[172:175], v[208:211], v[88:91]
	v_mfma_f32_16x16x32_bf16 v[84:87], v[180:183], v[208:211], v[84:87]
	v_mfma_f32_16x16x32_bf16 v[72:75], v[172:175], v[216:219], v[72:75]
	v_mfma_f32_16x16x32_bf16 v[68:71], v[180:183], v[216:219], v[68:71]
	s_barrier
	s_setprio 0
	s_add_i32 s0, s0, s47
	v_lshl_add_u64 v[156:157], v[156:157], 0, s[90:91]
	s_mov_b32 m0, s0
	ds_read_b128 v[184:187], v163 offset:49152
	ds_read_b128 v[188:191], v163 offset:50176
	ds_read_b128 v[192:195], v163 offset:51200
	ds_read_b128 v[200:203], v163 offset:52224
	ds_read_b128 v[204:207], v163 offset:53248
	ds_read_b128 v[208:211], v163 offset:54272
	ds_read_b128 v[212:215], v163 offset:55296
	ds_read_b128 v[216:219], v163 offset:56320
	global_load_lds_dwordx4 v[156:157], off
	s_add_i32 m0, s0, 0x2000
	s_add_u32 s30, s30, 0x80080
	v_lshl_add_u64 v[156:157], v[220:221], 0, s[90:91]
	s_addc_u32 s31, s31, 0
	s_add_i32 s0, s6, s47
	global_load_lds_dwordx4 v[156:157], off
	v_lshl_add_u64 v[156:157], s[30:31], 0, v[136:137]
	s_mov_b32 m0, s0
	s_nop 0
	global_load_lds_dwordx4 v[156:157], off
	v_lshl_add_u64 v[156:157], s[30:31], 0, v[132:133]
	s_add_i32 m0, s0, 0x2000
	s_nop 0
	global_load_lds_dwordx4 v[156:157], off
	v_lshl_add_u64 v[156:157], v[222:223], 0, s[90:91]
	s_mov_b32 m0, s51
	s_nop 0
	global_load_lds_dwordx4 v[156:157], off
	v_lshl_add_u64 v[156:157], v[224:225], 0, s[90:91]
	s_mov_b32 m0, s4
	s_nop 0
	global_load_lds_dwordx4 v[156:157], off
	s_setprio 1
	s_waitcnt vmcnt(8) lgkmcnt(0)
	s_barrier
	v_mfma_f32_16x16x32_bf16 v[64:67], v[144:147], v[184:187], v[64:67]
	v_mfma_f32_16x16x32_bf16 v[60:63], v[152:155], v[184:187], v[60:63]
	v_mfma_f32_16x16x32_bf16 v[48:51], v[144:147], v[192:195], v[48:51]
	v_mfma_f32_16x16x32_bf16 v[44:47], v[152:155], v[192:195], v[44:47]
	v_mfma_f32_16x16x32_bf16 v[32:35], v[144:147], v[204:207], v[32:35]
	v_mfma_f32_16x16x32_bf16 v[28:31], v[152:155], v[204:207], v[28:31]
	v_mfma_f32_16x16x32_bf16 v[16:19], v[144:147], v[212:215], v[16:19]
	v_mfma_f32_16x16x32_bf16 v[12:15], v[152:155], v[212:215], v[12:15]
	v_mfma_f32_16x16x32_bf16 v[64:67], v[148:151], v[188:191], v[64:67]
	v_mfma_f32_16x16x32_bf16 v[60:63], v[164:167], v[188:191], v[60:63]
	v_mfma_f32_16x16x32_bf16 v[48:51], v[148:151], v[200:203], v[48:51]
	v_mfma_f32_16x16x32_bf16 v[44:47], v[164:167], v[200:203], v[44:47]
	v_mfma_f32_16x16x32_bf16 v[32:35], v[148:151], v[208:211], v[32:35]
	v_mfma_f32_16x16x32_bf16 v[28:31], v[164:167], v[208:211], v[28:31]
	v_mfma_f32_16x16x32_bf16 v[16:19], v[148:151], v[216:219], v[16:19]
	v_mfma_f32_16x16x32_bf16 v[12:15], v[164:167], v[216:219], v[12:15]
	s_setprio 0
	s_setprio 1
	v_mfma_f32_16x16x32_bf16 v[56:59], v[168:171], v[184:187], v[56:59]
	v_mfma_f32_16x16x32_bf16 v[52:55], v[176:179], v[184:187], v[52:55]
	v_mfma_f32_16x16x32_bf16 v[40:43], v[168:171], v[192:195], v[40:43]
	v_mfma_f32_16x16x32_bf16 v[36:39], v[176:179], v[192:195], v[36:39]
	v_mfma_f32_16x16x32_bf16 v[24:27], v[168:171], v[204:207], v[24:27]
	v_mfma_f32_16x16x32_bf16 v[20:23], v[176:179], v[204:207], v[20:23]
	v_mfma_f32_16x16x32_bf16 v[8:11], v[168:171], v[212:215], v[8:11]
	v_mfma_f32_16x16x32_bf16 v[4:7], v[176:179], v[212:215], v[4:7]
	v_mfma_f32_16x16x32_bf16 v[56:59], v[172:175], v[188:191], v[56:59]
	v_mfma_f32_16x16x32_bf16 v[52:55], v[180:183], v[188:191], v[52:55]
	v_mfma_f32_16x16x32_bf16 v[40:43], v[172:175], v[200:203], v[40:43]
	v_mfma_f32_16x16x32_bf16 v[36:39], v[180:183], v[200:203], v[36:39]
	v_mfma_f32_16x16x32_bf16 v[24:27], v[172:175], v[208:211], v[24:27]
	v_mfma_f32_16x16x32_bf16 v[20:23], v[180:183], v[208:211], v[20:23]
	v_mfma_f32_16x16x32_bf16 v[8:11], v[172:175], v[216:219], v[8:11]
	v_mfma_f32_16x16x32_bf16 v[4:7], v[180:183], v[216:219], v[4:7]
	s_barrier
	s_setprio 0
	s_add_i32 s50, s50, 2
	s_add_u32 s36, s36, 0x100
	s_addc_u32 s37, s37, 0
	s_add_u32 s38, s38, 0x100
	s_addc_u32 s39, s39, 0
	s_cmp_gt_u32 s50, 29
	s_cbranch_scc0 .LBB0_336
	s_and_b64 vcc, exec, s[22:23]
	s_cbranch_vccz .LBB0_339
	s_barrier

.LBB0_747:
	s_add_i32 s0, s6, 2
	s_add_u32 s25, s66, 0xfffc0080
	s_addc_u32 s29, s67, -1
	s_add_i32 s33, 0, 0x10000
	s_cmp_eq_u32 s13, s6
	s_cselect_b32 s35, s45, s29
	s_cselect_b32 s34, s44, s25
	v_add_u32_e32 v3, s33, v237
	s_cselect_b32 s31, s61, s24
	s_cselect_b32 s30, s60, s15
	s_add_i32 s6, 0, 0x14000
	ds_read_b128 v[146:149], v3
	ds_read_b128 v[150:153], v3 offset:1024
	ds_read_b128 v[154:157], v3 offset:2048
	ds_read_b128 v[158:161], v3 offset:3072
	v_add_u32_e32 v3, s6, v237
	ds_read_b128 v[162:165], v3
	ds_read_b128 v[166:169], v3 offset:1024
	ds_read_b128 v[170:173], v3 offset:2048
	ds_read_b128 v[174:177], v3 offset:3072
	v_lshl_add_u64 v[4:5], s[66:67], 0, v[142:143]
	s_add_i32 m0, s52, 0xc000
	ds_read_b128 v[178:181], v249
	ds_read_b128 v[182:185], v249 offset:1024
	ds_read_b128 v[186:189], v249 offset:2048
	ds_read_b128 v[190:193], v249 offset:3072
	ds_read_b128 v[200:203], v249 offset:4096
	ds_read_b128 v[204:207], v249 offset:5120
	ds_read_b128 v[208:211], v249 offset:6144
	ds_read_b128 v[212:215], v249 offset:7168
	global_load_lds_dwordx4 v[4:5], off
	v_lshl_add_u64 v[4:5], s[66:67], 0, v[144:145]
	s_add_i32 m0, s52, 0xe000
	s_nop 0
	global_load_lds_dwordx4 v[4:5], off
	s_setprio 1
	s_waitcnt vmcnt(8) lgkmcnt(0)
	s_barrier
	v_mfma_f32_16x16x32_bf16 v[130:133], v[146:149], v[178:181], v[130:133]
	v_mfma_f32_16x16x32_bf16 v[126:129], v[154:157], v[178:181], v[126:129]
	v_mfma_f32_16x16x32_bf16 v[122:125], v[146:149], v[186:189], v[122:125]
	v_mfma_f32_16x16x32_bf16 v[118:121], v[154:157], v[186:189], v[118:121]
	v_mfma_f32_16x16x32_bf16 v[114:117], v[146:149], v[200:203], v[114:117]
	v_mfma_f32_16x16x32_bf16 v[110:113], v[154:157], v[200:203], v[110:113]
	v_mfma_f32_16x16x32_bf16 v[106:109], v[146:149], v[208:211], v[106:109]
	v_mfma_f32_16x16x32_bf16 v[102:105], v[154:157], v[208:211], v[102:105]
	v_mfma_f32_16x16x32_bf16 v[130:133], v[150:153], v[182:185], v[130:133]
	v_mfma_f32_16x16x32_bf16 v[126:129], v[158:161], v[182:185], v[126:129]
	v_mfma_f32_16x16x32_bf16 v[122:125], v[150:153], v[190:193], v[122:125]
	v_mfma_f32_16x16x32_bf16 v[118:121], v[158:161], v[190:193], v[118:121]
	v_mfma_f32_16x16x32_bf16 v[114:117], v[150:153], v[204:207], v[114:117]
	v_mfma_f32_16x16x32_bf16 v[110:113], v[158:161], v[204:207], v[110:113]
	v_mfma_f32_16x16x32_bf16 v[106:109], v[150:153], v[212:215], v[106:109]
	v_mfma_f32_16x16x32_bf16 v[102:105], v[158:161], v[212:215], v[102:105]
	s_setprio 0
	s_setprio 1
	v_mfma_f32_16x16x32_bf16 v[98:101], v[162:165], v[178:181], v[98:101]
	v_mfma_f32_16x16x32_bf16 v[94:97], v[170:173], v[178:181], v[94:97]
	v_mfma_f32_16x16x32_bf16 v[90:93], v[162:165], v[186:189], v[90:93]
	v_mfma_f32_16x16x32_bf16 v[86:89], v[170:173], v[186:189], v[86:89]
	v_mfma_f32_16x16x32_bf16 v[82:85], v[162:165], v[200:203], v[82:85]
	v_mfma_f32_16x16x32_bf16 v[78:81], v[170:173], v[200:203], v[78:81]
	v_mfma_f32_16x16x32_bf16 v[74:77], v[162:165], v[208:211], v[74:77]
	v_mfma_f32_16x16x32_bf16 v[70:73], v[170:173], v[208:211], v[70:73]
	v_mfma_f32_16x16x32_bf16 v[98:101], v[166:169], v[182:185], v[98:101]
	v_mfma_f32_16x16x32_bf16 v[94:97], v[174:177], v[182:185], v[94:97]
	v_mfma_f32_16x16x32_bf16 v[90:93], v[166:169], v[190:193], v[90:93]
	v_mfma_f32_16x16x32_bf16 v[86:89], v[174:177], v[190:193], v[86:89]
	v_mfma_f32_16x16x32_bf16 v[82:85], v[166:169], v[204:207], v[82:85]
	v_mfma_f32_16x16x32_bf16 v[78:81], v[174:177], v[204:207], v[78:81]
	v_mfma_f32_16x16x32_bf16 v[74:77], v[166:169], v[212:215], v[74:77]
	v_mfma_f32_16x16x32_bf16 v[70:73], v[174:177], v[212:215], v[70:73]
	s_barrier
	s_setprio 0
	s_add_i32 s25, s33, s47
	v_lshl_add_u64 v[194:195], s[30:31], 0, v[136:137]
	s_mov_b32 m0, s25
	ds_read_b128 v[178:181], v249 offset:16384
	ds_read_b128 v[182:185], v249 offset:17408
	ds_read_b128 v[186:189], v249 offset:18432
	ds_read_b128 v[190:193], v249 offset:19456
	ds_read_b128 v[200:203], v249 offset:20480
	ds_read_b128 v[204:207], v249 offset:21504
	ds_read_b128 v[208:211], v249 offset:22528
	ds_read_b128 v[212:215], v249 offset:23552
	global_load_lds_dwordx4 v[194:195], off
	s_add_i32 m0, s25, 0x2000
	s_add_u32 s36, s30, 0x40000
	v_lshl_add_u64 v[216:217], s[30:31], 0, v[140:141]
	s_addc_u32 s37, s31, 0
	s_add_i32 s6, s6, s47
	global_load_lds_dwordx4 v[216:217], off
	v_lshl_add_u64 v[4:5], s[36:37], 0, v[136:137]
	s_mov_b32 m0, s6
	v_lshl_add_u64 v[218:219], s[34:35], 0, v[134:135]
	global_load_lds_dwordx4 v[4:5], off
	v_lshl_add_u64 v[4:5], s[36:37], 0, v[140:141]
	s_add_i32 m0, s6, 0x2000
	v_lshl_add_u64 v[220:221], s[34:35], 0, v[138:139]
	global_load_lds_dwordx4 v[4:5], off
	s_mov_b32 m0, s52
	s_nop 0
	global_load_lds_dwordx4 v[218:219], off
	s_mov_b32 m0, s53
	s_nop 0
	global_load_lds_dwordx4 v[220:221], off
	s_setprio 1
	s_waitcnt vmcnt(8) lgkmcnt(0)
	s_barrier
	v_mfma_f32_16x16x32_bf16 v[66:69], v[146:149], v[178:181], v[66:69]
	v_mfma_f32_16x16x32_bf16 v[62:65], v[154:157], v[178:181], v[62:65]
	v_mfma_f32_16x16x32_bf16 v[58:61], v[146:149], v[186:189], v[58:61]
	v_mfma_f32_16x16x32_bf16 v[54:57], v[154:157], v[186:189], v[54:57]
	v_mfma_f32_16x16x32_bf16 v[50:53], v[146:149], v[200:203], v[50:53]
	v_mfma_f32_16x16x32_bf16 v[46:49], v[154:157], v[200:203], v[46:49]
	v_mfma_f32_16x16x32_bf16 v[42:45], v[146:149], v[208:211], v[42:45]
	v_mfma_f32_16x16x32_bf16 v[38:41], v[154:157], v[208:211], v[38:41]
	v_mfma_f32_16x16x32_bf16 v[66:69], v[150:153], v[182:185], v[66:69]
	v_mfma_f32_16x16x32_bf16 v[62:65], v[158:161], v[182:185], v[62:65]
	v_mfma_f32_16x16x32_bf16 v[58:61], v[150:153], v[190:193], v[58:61]
	v_mfma_f32_16x16x32_bf16 v[54:57], v[158:161], v[190:193], v[54:57]
	v_mfma_f32_16x16x32_bf16 v[50:53], v[150:153], v[204:207], v[50:53]
	v_mfma_f32_16x16x32_bf16 v[46:49], v[158:161], v[204:207], v[46:49]
	v_mfma_f32_16x16x32_bf16 v[42:45], v[150:153], v[212:215], v[42:45]
	v_mfma_f32_16x16x32_bf16 v[38:41], v[158:161], v[212:215], v[38:41]
	s_setprio 0
	s_setprio 1
	v_mfma_f32_16x16x32_bf16 v[34:37], v[162:165], v[178:181], v[34:37]
	v_mfma_f32_16x16x32_bf16 v[30:33], v[170:173], v[178:181], v[30:33]
	v_mfma_f32_16x16x32_bf16 v[26:29], v[162:165], v[186:189], v[26:29]
	v_mfma_f32_16x16x32_bf16 v[22:25], v[170:173], v[186:189], v[22:25]
	v_mfma_f32_16x16x32_bf16 v[18:21], v[162:165], v[200:203], v[18:21]
	v_mfma_f32_16x16x32_bf16 v[14:17], v[170:173], v[200:203], v[14:17]
	v_mfma_f32_16x16x32_bf16 v[10:13], v[162:165], v[208:211], v[10:13]
	v_mfma_f32_16x16x32_bf16 v[4:7], v[170:173], v[208:211], v[6:9]
	v_mfma_f32_16x16x32_bf16 v[34:37], v[166:169], v[182:185], v[34:37]
	v_mfma_f32_16x16x32_bf16 v[30:33], v[174:177], v[182:185], v[30:33]
	v_mfma_f32_16x16x32_bf16 v[26:29], v[166:169], v[190:193], v[26:29]
	v_mfma_f32_16x16x32_bf16 v[22:25], v[174:177], v[190:193], v[22:25]
	v_mfma_f32_16x16x32_bf16 v[18:21], v[166:169], v[204:207], v[18:21]
	v_mfma_f32_16x16x32_bf16 v[14:17], v[174:177], v[204:207], v[14:17]
	v_mfma_f32_16x16x32_bf16 v[10:13], v[166:169], v[212:215], v[10:13]
	v_mfma_f32_16x16x32_bf16 v[4:7], v[174:177], v[212:215], v[4:7]
	s_barrier
	s_setprio 0
	s_add_i32 s6, 0, 0x18000
	v_add_u32_e32 v3, s6, v237
	s_add_i32 s25, 0, 0x1c000
	ds_read_b128 v[146:149], v3
	ds_read_b128 v[150:153], v3 offset:1024
	ds_read_b128 v[154:157], v3 offset:2048
	ds_read_b128 v[158:161], v3 offset:3072
	v_add_u32_e32 v3, s25, v237
	ds_read_b128 v[162:165], v3
	ds_read_b128 v[166:169], v3 offset:1024
	ds_read_b128 v[170:173], v3 offset:2048
	ds_read_b128 v[174:177], v3 offset:3072
	s_add_u32 s34, s34, 0x40000
	s_addc_u32 s35, s35, 0
	s_mov_b32 m0, s59
	v_lshl_add_u64 v[8:9], s[34:35], 0, v[134:135]
	ds_read_b128 v[178:181], v249 offset:32768
	ds_read_b128 v[182:185], v249 offset:33792
	ds_read_b128 v[186:189], v249 offset:34816
	ds_read_b128 v[190:193], v249 offset:35840
	ds_read_b128 v[200:203], v249 offset:36864
	ds_read_b128 v[204:207], v249 offset:37888
	ds_read_b128 v[208:211], v249 offset:38912
	ds_read_b128 v[212:215], v249 offset:39936
	global_load_lds_dwordx4 v[8:9], off
	v_lshl_add_u64 v[8:9], s[34:35], 0, v[138:139]
	s_mov_b32 m0, s63
	s_nop 0
	global_load_lds_dwordx4 v[8:9], off
	s_setprio 1
	s_waitcnt vmcnt(8) lgkmcnt(0)
	s_barrier
	v_mfma_f32_16x16x32_bf16 v[130:133], v[146:149], v[178:181], v[130:133]
	v_mfma_f32_16x16x32_bf16 v[126:129], v[154:157], v[178:181], v[126:129]
	v_mfma_f32_16x16x32_bf16 v[122:125], v[146:149], v[186:189], v[122:125]
	v_mfma_f32_16x16x32_bf16 v[118:121], v[154:157], v[186:189], v[118:121]
	v_mfma_f32_16x16x32_bf16 v[114:117], v[146:149], v[200:203], v[114:117]
	v_mfma_f32_16x16x32_bf16 v[110:113], v[154:157], v[200:203], v[110:113]
	v_mfma_f32_16x16x32_bf16 v[106:109], v[146:149], v[208:211], v[106:109]
	v_mfma_f32_16x16x32_bf16 v[102:105], v[154:157], v[208:211], v[102:105]
	v_mfma_f32_16x16x32_bf16 v[130:133], v[150:153], v[182:185], v[130:133]
	v_mfma_f32_16x16x32_bf16 v[126:129], v[158:161], v[182:185], v[126:129]
	v_mfma_f32_16x16x32_bf16 v[122:125], v[150:153], v[190:193], v[122:125]
	v_mfma_f32_16x16x32_bf16 v[118:121], v[158:161], v[190:193], v[118:121]
	v_mfma_f32_16x16x32_bf16 v[114:117], v[150:153], v[204:207], v[114:117]
	v_mfma_f32_16x16x32_bf16 v[110:113], v[158:161], v[204:207], v[110:113]
	v_mfma_f32_16x16x32_bf16 v[106:109], v[150:153], v[212:215], v[106:109]
	v_mfma_f32_16x16x32_bf16 v[102:105], v[158:161], v[212:215], v[102:105]
	s_setprio 0
	s_setprio 1
	v_mfma_f32_16x16x32_bf16 v[98:101], v[162:165], v[178:181], v[98:101]
	v_mfma_f32_16x16x32_bf16 v[94:97], v[170:173], v[178:181], v[94:97]
	v_mfma_f32_16x16x32_bf16 v[90:93], v[162:165], v[186:189], v[90:93]
	v_mfma_f32_16x16x32_bf16 v[86:89], v[170:173], v[186:189], v[86:89]
	v_mfma_f32_16x16x32_bf16 v[82:85], v[162:165], v[200:203], v[82:85]
	v_mfma_f32_16x16x32_bf16 v[78:81], v[170:173], v[200:203], v[78:81]
	v_mfma_f32_16x16x32_bf16 v[74:77], v[162:165], v[208:211], v[74:77]
	v_mfma_f32_16x16x32_bf16 v[70:73], v[170:173], v[208:211], v[70:73]
	v_mfma_f32_16x16x32_bf16 v[98:101], v[166:169], v[182:185], v[98:101]
	v_mfma_f32_16x16x32_bf16 v[94:97], v[174:177], v[182:185], v[94:97]
	v_mfma_f32_16x16x32_bf16 v[90:93], v[166:169], v[190:193], v[90:93]
	v_mfma_f32_16x16x32_bf16 v[86:89], v[174:177], v[190:193], v[86:89]
	v_mfma_f32_16x16x32_bf16 v[82:85], v[166:169], v[204:207], v[82:85]
	v_mfma_f32_16x16x32_bf16 v[78:81], v[174:177], v[204:207], v[78:81]
	v_mfma_f32_16x16x32_bf16 v[74:77], v[166:169], v[212:215], v[74:77]
	v_mfma_f32_16x16x32_bf16 v[70:73], v[174:177], v[212:215], v[70:73]
	s_barrier
	s_setprio 0
	s_add_i32 s6, s6, s47
	v_lshl_add_u64 v[8:9], v[194:195], 0, s[90:91]
	s_mov_b32 m0, s6
	ds_read_b128 v[178:181], v249 offset:49152
	ds_read_b128 v[182:185], v249 offset:50176
	ds_read_b128 v[186:189], v249 offset:51200
	ds_read_b128 v[190:193], v249 offset:52224
	ds_read_b128 v[200:203], v249 offset:53248
	ds_read_b128 v[204:207], v249 offset:54272
	ds_read_b128 v[208:211], v249 offset:55296
	ds_read_b128 v[212:215], v249 offset:56320
	global_load_lds_dwordx4 v[8:9], off
	s_add_i32 m0, s6, 0x2000
	s_add_u32 s30, s30, 0x40080
	v_lshl_add_u64 v[8:9], v[216:217], 0, s[90:91]
	s_addc_u32 s31, s31, 0
	s_add_i32 s6, s25, s47
	global_load_lds_dwordx4 v[8:9], off
	v_lshl_add_u64 v[8:9], s[30:31], 0, v[136:137]
	s_mov_b32 m0, s6
	s_nop 0
	global_load_lds_dwordx4 v[8:9], off
	v_lshl_add_u64 v[8:9], s[30:31], 0, v[140:141]
	s_add_i32 m0, s6, 0x2000
	s_nop 0
	global_load_lds_dwordx4 v[8:9], off
	v_lshl_add_u64 v[8:9], v[218:219], 0, s[90:91]
	s_mov_b32 m0, s80
	s_nop 0
	global_load_lds_dwordx4 v[8:9], off
	v_lshl_add_u64 v[8:9], v[220:221], 0, s[90:91]
	s_mov_b32 m0, s81
	s_nop 0
	global_load_lds_dwordx4 v[8:9], off
	s_setprio 1
	s_waitcnt vmcnt(8) lgkmcnt(0)
	s_barrier
	v_mfma_f32_16x16x32_bf16 v[66:69], v[146:149], v[178:181], v[66:69]
	v_mfma_f32_16x16x32_bf16 v[62:65], v[154:157], v[178:181], v[62:65]
	v_mfma_f32_16x16x32_bf16 v[58:61], v[146:149], v[186:189], v[58:61]
	v_mfma_f32_16x16x32_bf16 v[54:57], v[154:157], v[186:189], v[54:57]
	v_mfma_f32_16x16x32_bf16 v[50:53], v[146:149], v[200:203], v[50:53]
	v_mfma_f32_16x16x32_bf16 v[46:49], v[154:157], v[200:203], v[46:49]
	v_mfma_f32_16x16x32_bf16 v[42:45], v[146:149], v[208:211], v[42:45]
	v_mfma_f32_16x16x32_bf16 v[38:41], v[154:157], v[208:211], v[38:41]
	v_mfma_f32_16x16x32_bf16 v[66:69], v[150:153], v[182:185], v[66:69]
	v_mfma_f32_16x16x32_bf16 v[62:65], v[158:161], v[182:185], v[62:65]
	v_mfma_f32_16x16x32_bf16 v[58:61], v[150:153], v[190:193], v[58:61]
	v_mfma_f32_16x16x32_bf16 v[54:57], v[158:161], v[190:193], v[54:57]
	v_mfma_f32_16x16x32_bf16 v[50:53], v[150:153], v[204:207], v[50:53]
	v_mfma_f32_16x16x32_bf16 v[46:49], v[158:161], v[204:207], v[46:49]
	v_mfma_f32_16x16x32_bf16 v[42:45], v[150:153], v[212:215], v[42:45]
	v_mfma_f32_16x16x32_bf16 v[38:41], v[158:161], v[212:215], v[38:41]
	s_setprio 0
	s_setprio 1
	v_mfma_f32_16x16x32_bf16 v[34:37], v[162:165], v[178:181], v[34:37]
	v_mfma_f32_16x16x32_bf16 v[30:33], v[170:173], v[178:181], v[30:33]
	v_mfma_f32_16x16x32_bf16 v[26:29], v[162:165], v[186:189], v[26:29]
	v_mfma_f32_16x16x32_bf16 v[22:25], v[170:173], v[186:189], v[22:25]
	v_mfma_f32_16x16x32_bf16 v[18:21], v[162:165], v[200:203], v[18:21]
	v_mfma_f32_16x16x32_bf16 v[14:17], v[170:173], v[200:203], v[14:17]
	v_mfma_f32_16x16x32_bf16 v[8:11], v[162:165], v[208:211], v[10:13]
	v_mfma_f32_16x16x32_bf16 v[4:7], v[170:173], v[208:211], v[4:7]
	v_mfma_f32_16x16x32_bf16 v[34:37], v[166:169], v[182:185], v[34:37]
	v_mfma_f32_16x16x32_bf16 v[30:33], v[174:177], v[182:185], v[30:33]
	v_mfma_f32_16x16x32_bf16 v[26:29], v[166:169], v[190:193], v[26:29]
	v_mfma_f32_16x16x32_bf16 v[22:25], v[174:177], v[190:193], v[22:25]
	v_mfma_f32_16x16x32_bf16 v[18:21], v[166:169], v[204:207], v[18:21]
	v_mfma_f32_16x16x32_bf16 v[14:17], v[174:177], v[204:207], v[14:17]
	v_mfma_f32_16x16x32_bf16 v[10:13], v[166:169], v[212:215], v[8:11]
	v_mfma_f32_16x16x32_bf16 v[6:9], v[174:177], v[212:215], v[4:7]
	s_barrier
	s_setprio 0
	s_add_u32 s66, s66, 0x100
	s_addc_u32 s67, s67, 0
	s_add_u32 s15, s15, 0x100
	s_addc_u32 s24, s24, 0
	s_cmp_ge_i32 s0, s1
	s_mov_b32 s6, s0
	s_cbranch_scc0 .LBB0_747

.LBB0_967:
	s_add_u32 s0, s36, 0xfff80080
	s_addc_u32 s6, s37, -1
	s_add_i32 s49, 0, 0x10000
	s_cmp_eq_u32 s55, 28
	s_cselect_b32 s35, s65, s6
	s_cselect_b32 s34, s64, s0
	s_cselect_b32 s31, s67, s39
	s_cselect_b32 s30, s66, s38
	s_add_i32 s0, 0, 0x14000
	v_add_u32_e32 v144, s49, v3
	v_add_u32_e32 v160, s0, v3
	ds_read_b128 v[124:127], v144
	ds_read_b128 v[128:131], v144 offset:1024
	ds_read_b128 v[140:143], v144 offset:2048
	ds_read_b128 v[144:147], v144 offset:3072
	ds_read_b128 v[148:151], v160
	ds_read_b128 v[152:155], v160 offset:1024
	ds_read_b128 v[156:159], v160 offset:2048
	ds_read_b128 v[160:163], v160 offset:3072
	v_lshl_add_u64 v[198:199], s[36:37], 0, v[212:213]
	s_add_i32 m0, s4, 0xc000
	ds_read_b128 v[164:167], v250
	ds_read_b128 v[168:171], v250 offset:1024
	ds_read_b128 v[172:175], v250 offset:2048
	ds_read_b128 v[176:179], v250 offset:3072
	ds_read_b128 v[180:183], v250 offset:4096
	ds_read_b128 v[184:187], v250 offset:5120
	ds_read_b128 v[188:191], v250 offset:6144
	ds_read_b128 v[192:195], v250 offset:7168
	global_load_lds_dwordx4 v[198:199], off
	v_lshl_add_u64 v[198:199], s[36:37], 0, v[214:215]
	s_add_i32 m0, s4, 0xe000
	s_nop 0
	global_load_lds_dwordx4 v[198:199], off
	s_setprio 1
	s_waitcnt vmcnt(8) lgkmcnt(0)
	s_barrier
	v_mfma_f32_16x16x32_bf16 v[136:139], v[124:127], v[164:167], v[136:139]
	v_mfma_f32_16x16x32_bf16 v[132:135], v[140:143], v[164:167], v[132:135]
	v_mfma_f32_16x16x32_bf16 v[112:115], v[124:127], v[172:175], v[112:115]
	v_mfma_f32_16x16x32_bf16 v[108:111], v[140:143], v[172:175], v[108:111]
	v_mfma_f32_16x16x32_bf16 v[96:99], v[124:127], v[180:183], v[96:99]
	v_mfma_f32_16x16x32_bf16 v[92:95], v[140:143], v[180:183], v[92:95]
	v_mfma_f32_16x16x32_bf16 v[80:83], v[124:127], v[188:191], v[80:83]
	v_mfma_f32_16x16x32_bf16 v[76:79], v[140:143], v[188:191], v[76:79]
	v_mfma_f32_16x16x32_bf16 v[136:139], v[128:131], v[168:171], v[136:139]
	v_mfma_f32_16x16x32_bf16 v[132:135], v[144:147], v[168:171], v[132:135]
	v_mfma_f32_16x16x32_bf16 v[112:115], v[128:131], v[176:179], v[112:115]
	v_mfma_f32_16x16x32_bf16 v[108:111], v[144:147], v[176:179], v[108:111]
	v_mfma_f32_16x16x32_bf16 v[96:99], v[128:131], v[184:187], v[96:99]
	v_mfma_f32_16x16x32_bf16 v[92:95], v[144:147], v[184:187], v[92:95]
	v_mfma_f32_16x16x32_bf16 v[80:83], v[128:131], v[192:195], v[80:83]
	v_mfma_f32_16x16x32_bf16 v[76:79], v[144:147], v[192:195], v[76:79]
	s_setprio 0
	s_setprio 1
	v_mfma_f32_16x16x32_bf16 v[120:123], v[148:151], v[164:167], v[120:123]
	v_mfma_f32_16x16x32_bf16 v[116:119], v[156:159], v[164:167], v[116:119]
	v_mfma_f32_16x16x32_bf16 v[104:107], v[148:151], v[172:175], v[104:107]
	v_mfma_f32_16x16x32_bf16 v[100:103], v[156:159], v[172:175], v[100:103]
	v_mfma_f32_16x16x32_bf16 v[88:91], v[148:151], v[180:183], v[88:91]
	v_mfma_f32_16x16x32_bf16 v[84:87], v[156:159], v[180:183], v[84:87]
	v_mfma_f32_16x16x32_bf16 v[72:75], v[148:151], v[188:191], v[72:75]
	v_mfma_f32_16x16x32_bf16 v[68:71], v[156:159], v[188:191], v[68:71]
	v_mfma_f32_16x16x32_bf16 v[120:123], v[152:155], v[168:171], v[120:123]
	v_mfma_f32_16x16x32_bf16 v[116:119], v[160:163], v[168:171], v[116:119]
	v_mfma_f32_16x16x32_bf16 v[104:107], v[152:155], v[176:179], v[104:107]
	v_mfma_f32_16x16x32_bf16 v[100:103], v[160:163], v[176:179], v[100:103]
	v_mfma_f32_16x16x32_bf16 v[88:91], v[152:155], v[184:187], v[88:91]
	v_mfma_f32_16x16x32_bf16 v[84:87], v[160:163], v[184:187], v[84:87]
	v_mfma_f32_16x16x32_bf16 v[72:75], v[152:155], v[192:195], v[72:75]
	v_mfma_f32_16x16x32_bf16 v[68:71], v[160:163], v[192:195], v[68:71]
	s_barrier
	s_setprio 0
	s_add_i32 s6, s49, s1
	v_lshl_add_u64 v[198:199], s[30:31], 0, v[204:205]
	s_mov_b32 m0, s6
	ds_read_b128 v[164:167], v250 offset:16384
	ds_read_b128 v[168:171], v250 offset:17408
	ds_read_b128 v[172:175], v250 offset:18432
	ds_read_b128 v[176:179], v250 offset:19456
	ds_read_b128 v[180:183], v250 offset:20480
	ds_read_b128 v[184:187], v250 offset:21504
	ds_read_b128 v[188:191], v250 offset:22528
	ds_read_b128 v[192:195], v250 offset:23552
	global_load_lds_dwordx4 v[198:199], off
	s_add_i32 m0, s6, 0x2000
	s_add_u32 s68, s30, 0x80000
	v_lshl_add_u64 v[216:217], s[30:31], 0, v[200:201]
	s_addc_u32 s69, s31, 0
	s_add_i32 s0, s0, s1
	global_load_lds_dwordx4 v[216:217], off
	v_lshl_add_u64 v[218:219], s[68:69], 0, v[204:205]
	s_mov_b32 m0, s0
	v_lshl_add_u64 v[220:221], s[34:35], 0, v[202:203]
	global_load_lds_dwordx4 v[218:219], off
	v_lshl_add_u64 v[218:219], s[68:69], 0, v[200:201]
	s_add_i32 m0, s0, 0x2000
	s_nop 0
	global_load_lds_dwordx4 v[218:219], off
	v_lshl_add_u64 v[218:219], s[34:35], 0, v[206:207]
	s_mov_b32 m0, s4
	s_nop 0
	global_load_lds_dwordx4 v[218:219], off
	s_mov_b32 m0, s24
	s_nop 0
	global_load_lds_dwordx4 v[220:221], off
	s_setprio 1
	s_waitcnt vmcnt(8) lgkmcnt(0)
	s_barrier
	v_mfma_f32_16x16x32_bf16 v[64:67], v[124:127], v[164:167], v[64:67]
	v_mfma_f32_16x16x32_bf16 v[60:63], v[140:143], v[164:167], v[60:63]
	v_mfma_f32_16x16x32_bf16 v[48:51], v[124:127], v[172:175], v[48:51]
	v_mfma_f32_16x16x32_bf16 v[44:47], v[140:143], v[172:175], v[44:47]
	v_mfma_f32_16x16x32_bf16 v[32:35], v[124:127], v[180:183], v[32:35]
	v_mfma_f32_16x16x32_bf16 v[28:31], v[140:143], v[180:183], v[28:31]
	v_mfma_f32_16x16x32_bf16 v[16:19], v[124:127], v[188:191], v[16:19]
	v_mfma_f32_16x16x32_bf16 v[12:15], v[140:143], v[188:191], v[12:15]
	v_mfma_f32_16x16x32_bf16 v[64:67], v[128:131], v[168:171], v[64:67]
	v_mfma_f32_16x16x32_bf16 v[60:63], v[144:147], v[168:171], v[60:63]
	v_mfma_f32_16x16x32_bf16 v[48:51], v[128:131], v[176:179], v[48:51]
	v_mfma_f32_16x16x32_bf16 v[44:47], v[144:147], v[176:179], v[44:47]
	v_mfma_f32_16x16x32_bf16 v[32:35], v[128:131], v[184:187], v[32:35]
	v_mfma_f32_16x16x32_bf16 v[28:31], v[144:147], v[184:187], v[28:31]
	v_mfma_f32_16x16x32_bf16 v[16:19], v[128:131], v[192:195], v[16:19]
	v_mfma_f32_16x16x32_bf16 v[12:15], v[144:147], v[192:195], v[12:15]
	s_setprio 0
	s_setprio 1
	v_mfma_f32_16x16x32_bf16 v[56:59], v[148:151], v[164:167], v[56:59]
	v_mfma_f32_16x16x32_bf16 v[52:55], v[156:159], v[164:167], v[52:55]
	v_mfma_f32_16x16x32_bf16 v[40:43], v[148:151], v[172:175], v[40:43]
	v_mfma_f32_16x16x32_bf16 v[36:39], v[156:159], v[172:175], v[36:39]
	v_mfma_f32_16x16x32_bf16 v[24:27], v[148:151], v[180:183], v[24:27]
	v_mfma_f32_16x16x32_bf16 v[20:23], v[156:159], v[180:183], v[20:23]
	v_mfma_f32_16x16x32_bf16 v[8:11], v[148:151], v[188:191], v[8:11]
	v_mfma_f32_16x16x32_bf16 v[4:7], v[156:159], v[188:191], v[4:7]
	v_mfma_f32_16x16x32_bf16 v[56:59], v[152:155], v[168:171], v[56:59]
	v_mfma_f32_16x16x32_bf16 v[52:55], v[160:163], v[168:171], v[52:55]
	v_mfma_f32_16x16x32_bf16 v[40:43], v[152:155], v[176:179], v[40:43]
	v_mfma_f32_16x16x32_bf16 v[36:39], v[160:163], v[176:179], v[36:39]
	v_mfma_f32_16x16x32_bf16 v[24:27], v[152:155], v[184:187], v[24:27]
	v_mfma_f32_16x16x32_bf16 v[20:23], v[160:163], v[184:187], v[20:23]
	v_mfma_f32_16x16x32_bf16 v[8:11], v[152:155], v[192:195], v[8:11]
	v_mfma_f32_16x16x32_bf16 v[4:7], v[160:163], v[192:195], v[4:7]
	s_barrier
	s_setprio 0
	s_add_i32 s0, 0, 0x18000
	s_add_i32 s6, 0, 0x1c000
	v_add_u32_e32 v144, s0, v3
	v_add_u32_e32 v160, s6, v3
	ds_read_b128 v[124:127], v144
	ds_read_b128 v[128:131], v144 offset:1024
	ds_read_b128 v[140:143], v144 offset:2048
	ds_read_b128 v[144:147], v144 offset:3072
	ds_read_b128 v[148:151], v160
	ds_read_b128 v[152:155], v160 offset:1024
	ds_read_b128 v[156:159], v160 offset:2048
	ds_read_b128 v[160:163], v160 offset:3072
	s_add_u32 s34, s34, 0x80000
	s_addc_u32 s35, s35, 0
	s_mov_b32 m0, s25
	v_lshl_add_u64 v[222:223], s[34:35], 0, v[206:207]
	ds_read_b128 v[164:167], v250 offset:32768
	ds_read_b128 v[168:171], v250 offset:33792
	ds_read_b128 v[172:175], v250 offset:34816
	ds_read_b128 v[176:179], v250 offset:35840
	ds_read_b128 v[180:183], v250 offset:36864
	ds_read_b128 v[184:187], v250 offset:37888
	ds_read_b128 v[188:191], v250 offset:38912
	ds_read_b128 v[192:195], v250 offset:39936
	global_load_lds_dwordx4 v[222:223], off
	v_lshl_add_u64 v[222:223], s[34:35], 0, v[202:203]
	s_mov_b32 m0, s29
	s_nop 0
	global_load_lds_dwordx4 v[222:223], off
	s_setprio 1
	s_waitcnt vmcnt(8) lgkmcnt(0)
	s_barrier
	v_mfma_f32_16x16x32_bf16 v[136:139], v[124:127], v[164:167], v[136:139]
	v_mfma_f32_16x16x32_bf16 v[132:135], v[140:143], v[164:167], v[132:135]
	v_mfma_f32_16x16x32_bf16 v[112:115], v[124:127], v[172:175], v[112:115]
	v_mfma_f32_16x16x32_bf16 v[108:111], v[140:143], v[172:175], v[108:111]
	v_mfma_f32_16x16x32_bf16 v[96:99], v[124:127], v[180:183], v[96:99]
	v_mfma_f32_16x16x32_bf16 v[92:95], v[140:143], v[180:183], v[92:95]
	v_mfma_f32_16x16x32_bf16 v[80:83], v[124:127], v[188:191], v[80:83]
	v_mfma_f32_16x16x32_bf16 v[76:79], v[140:143], v[188:191], v[76:79]
	v_mfma_f32_16x16x32_bf16 v[136:139], v[128:131], v[168:171], v[136:139]
	v_mfma_f32_16x16x32_bf16 v[132:135], v[144:147], v[168:171], v[132:135]
	v_mfma_f32_16x16x32_bf16 v[112:115], v[128:131], v[176:179], v[112:115]
	v_mfma_f32_16x16x32_bf16 v[108:111], v[144:147], v[176:179], v[108:111]
	v_mfma_f32_16x16x32_bf16 v[96:99], v[128:131], v[184:187], v[96:99]
	v_mfma_f32_16x16x32_bf16 v[92:95], v[144:147], v[184:187], v[92:95]
	v_mfma_f32_16x16x32_bf16 v[80:83], v[128:131], v[192:195], v[80:83]
	v_mfma_f32_16x16x32_bf16 v[76:79], v[144:147], v[192:195], v[76:79]
	s_setprio 0
	s_setprio 1
	v_mfma_f32_16x16x32_bf16 v[120:123], v[148:151], v[164:167], v[120:123]
	v_mfma_f32_16x16x32_bf16 v[116:119], v[156:159], v[164:167], v[116:119]
	v_mfma_f32_16x16x32_bf16 v[104:107], v[148:151], v[172:175], v[104:107]
	v_mfma_f32_16x16x32_bf16 v[100:103], v[156:159], v[172:175], v[100:103]
	v_mfma_f32_16x16x32_bf16 v[88:91], v[148:151], v[180:183], v[88:91]
	v_mfma_f32_16x16x32_bf16 v[84:87], v[156:159], v[180:183], v[84:87]
	v_mfma_f32_16x16x32_bf16 v[72:75], v[148:151], v[188:191], v[72:75]
	v_mfma_f32_16x16x32_bf16 v[68:71], v[156:159], v[188:191], v[68:71]
	v_mfma_f32_16x16x32_bf16 v[120:123], v[152:155], v[168:171], v[120:123]
	v_mfma_f32_16x16x32_bf16 v[116:119], v[160:163], v[168:171], v[116:119]
	v_mfma_f32_16x16x32_bf16 v[104:107], v[152:155], v[176:179], v[104:107]
	v_mfma_f32_16x16x32_bf16 v[100:103], v[160:163], v[176:179], v[100:103]
	v_mfma_f32_16x16x32_bf16 v[88:91], v[152:155], v[184:187], v[88:91]
	v_mfma_f32_16x16x32_bf16 v[84:87], v[160:163], v[184:187], v[84:87]
	v_mfma_f32_16x16x32_bf16 v[72:75], v[152:155], v[192:195], v[72:75]
	v_mfma_f32_16x16x32_bf16 v[68:71], v[160:163], v[192:195], v[68:71]
	s_barrier
	s_setprio 0
	s_add_i32 s0, s0, s1
	v_lshl_add_u64 v[198:199], v[198:199], 0, s[90:91]
	s_mov_b32 m0, s0
	ds_read_b128 v[164:167], v250 offset:49152
	ds_read_b128 v[168:171], v250 offset:50176
	ds_read_b128 v[172:175], v250 offset:51200
	ds_read_b128 v[176:179], v250 offset:52224
	ds_read_b128 v[180:183], v250 offset:53248
	ds_read_b128 v[184:187], v250 offset:54272
	ds_read_b128 v[188:191], v250 offset:55296
	ds_read_b128 v[192:195], v250 offset:56320
	global_load_lds_dwordx4 v[198:199], off
	s_add_i32 m0, s0, 0x2000
	s_add_u32 s30, s30, 0x80080
	v_lshl_add_u64 v[198:199], v[216:217], 0, s[90:91]
	s_addc_u32 s31, s31, 0
	s_add_i32 s0, s6, s1
	global_load_lds_dwordx4 v[198:199], off
	v_lshl_add_u64 v[198:199], s[30:31], 0, v[204:205]
	s_mov_b32 m0, s0
	s_nop 0
	global_load_lds_dwordx4 v[198:199], off
	v_lshl_add_u64 v[198:199], s[30:31], 0, v[200:201]
	s_add_i32 m0, s0, 0x2000
	s_nop 0
	global_load_lds_dwordx4 v[198:199], off
	v_lshl_add_u64 v[198:199], v[218:219], 0, s[90:91]
	s_mov_b32 m0, s33
	s_nop 0
	global_load_lds_dwordx4 v[198:199], off
	v_lshl_add_u64 v[198:199], v[220:221], 0, s[90:91]
	s_mov_b32 m0, s40
	s_nop 0
	global_load_lds_dwordx4 v[198:199], off
	s_setprio 1
	s_waitcnt vmcnt(8) lgkmcnt(0)
	s_barrier
	v_mfma_f32_16x16x32_bf16 v[64:67], v[124:127], v[164:167], v[64:67]
	v_mfma_f32_16x16x32_bf16 v[60:63], v[140:143], v[164:167], v[60:63]
	v_mfma_f32_16x16x32_bf16 v[48:51], v[124:127], v[172:175], v[48:51]
	v_mfma_f32_16x16x32_bf16 v[44:47], v[140:143], v[172:175], v[44:47]
	v_mfma_f32_16x16x32_bf16 v[32:35], v[124:127], v[180:183], v[32:35]
	v_mfma_f32_16x16x32_bf16 v[28:31], v[140:143], v[180:183], v[28:31]
	v_mfma_f32_16x16x32_bf16 v[16:19], v[124:127], v[188:191], v[16:19]
	v_mfma_f32_16x16x32_bf16 v[12:15], v[140:143], v[188:191], v[12:15]
	v_mfma_f32_16x16x32_bf16 v[64:67], v[128:131], v[168:171], v[64:67]
	v_mfma_f32_16x16x32_bf16 v[60:63], v[144:147], v[168:171], v[60:63]
	v_mfma_f32_16x16x32_bf16 v[48:51], v[128:131], v[176:179], v[48:51]
	v_mfma_f32_16x16x32_bf16 v[44:47], v[144:147], v[176:179], v[44:47]
	v_mfma_f32_16x16x32_bf16 v[32:35], v[128:131], v[184:187], v[32:35]
	v_mfma_f32_16x16x32_bf16 v[28:31], v[144:147], v[184:187], v[28:31]
	v_mfma_f32_16x16x32_bf16 v[16:19], v[128:131], v[192:195], v[16:19]
	v_mfma_f32_16x16x32_bf16 v[12:15], v[144:147], v[192:195], v[12:15]
	s_setprio 0
	s_setprio 1
	v_mfma_f32_16x16x32_bf16 v[56:59], v[148:151], v[164:167], v[56:59]
	v_mfma_f32_16x16x32_bf16 v[52:55], v[156:159], v[164:167], v[52:55]
	v_mfma_f32_16x16x32_bf16 v[40:43], v[148:151], v[172:175], v[40:43]
	v_mfma_f32_16x16x32_bf16 v[36:39], v[156:159], v[172:175], v[36:39]
	v_mfma_f32_16x16x32_bf16 v[24:27], v[148:151], v[180:183], v[24:27]
	v_mfma_f32_16x16x32_bf16 v[20:23], v[156:159], v[180:183], v[20:23]
	v_mfma_f32_16x16x32_bf16 v[8:11], v[148:151], v[188:191], v[8:11]
	v_mfma_f32_16x16x32_bf16 v[4:7], v[156:159], v[188:191], v[4:7]
	v_mfma_f32_16x16x32_bf16 v[56:59], v[152:155], v[168:171], v[56:59]
	v_mfma_f32_16x16x32_bf16 v[52:55], v[160:163], v[168:171], v[52:55]
	v_mfma_f32_16x16x32_bf16 v[40:43], v[152:155], v[176:179], v[40:43]
	v_mfma_f32_16x16x32_bf16 v[36:39], v[160:163], v[176:179], v[36:39]
	v_mfma_f32_16x16x32_bf16 v[24:27], v[152:155], v[184:187], v[24:27]
	v_mfma_f32_16x16x32_bf16 v[20:23], v[160:163], v[184:187], v[20:23]
	v_mfma_f32_16x16x32_bf16 v[8:11], v[152:155], v[192:195], v[8:11]
	v_mfma_f32_16x16x32_bf16 v[4:7], v[160:163], v[192:195], v[4:7]
	s_barrier
	s_setprio 0
	s_add_i32 s55, s55, 2
	s_add_u32 s36, s36, 0x100
	s_addc_u32 s37, s37, 0
	s_add_u32 s38, s38, 0x100
	s_addc_u32 s39, s39, 0
	s_cmp_gt_u32 s55, 29
	s_cbranch_scc0 .LBB0_967
	s_and_b64 vcc, exec, s[44:45]
	s_cbranch_vccz .LBB0_970
	s_barrier

.LBB0_1017:
	s_add_u32 s0, s68, s30
	s_addc_u32 s6, s69, 0
	s_add_u32 s31, s0, 0x100
	s_addc_u32 s38, s6, 0
	s_and_b64 s[34:35], s[36:37], exec
	s_cselect_b32 vcc_hi, s65, s38
	s_cselect_b32 vcc_lo, s64, s31
	s_add_u32 s30, s74, s30
	s_addc_u32 s31, s75, 0
	s_add_u32 s34, s30, 0x100
	s_addc_u32 s35, s31, 0
	s_add_i32 s78, 0, 0x10000
	s_and_b64 s[30:31], s[36:37], exec
	s_cselect_b32 s53, s67, s35
	s_cselect_b32 s52, s66, s34
	s_add_i32 s37, 0, 0x14000
	s_add_u32 s34, s0, 0x80080
	s_addc_u32 s35, s6, 0
	s_add_i32 s73, s78, s1
	s_add_i32 m0, s4, 0xc000
	s_add_i32 s83, s4, 0xe000
	s_add_i32 s6, s73, 0x2000
	s_add_u32 s30, s52, 0x80000
	v_add_u32_e32 v144, s78, v3
	v_add_u32_e32 v160, s37, v3
	s_addc_u32 s31, s53, 0
	s_add_i32 s49, s37, s1
	ds_read_b128 v[132:135], v144
	ds_read_b128 v[136:139], v144 offset:1024
	ds_read_b128 v[140:143], v144 offset:2048
	ds_read_b128 v[144:147], v144 offset:3072
	ds_read_b128 v[148:151], v160
	ds_read_b128 v[152:155], v160 offset:1024
	ds_read_b128 v[156:159], v160 offset:2048
	ds_read_b128 v[160:163], v160 offset:3072
	s_add_i32 s63, s49, 0x2000
	s_add_i32 s54, 0, 0x18000
	s_add_i32 s61, 0, 0x1c000
	s_add_u32 s38, vcc_lo, 0x80000
	s_addc_u32 s39, vcc_hi, 0
	s_add_i32 s0, s54, s1
	s_add_i32 s45, s0, 0x2000
	s_add_u32 s36, s52, 0x80080
	s_addc_u32 s37, s53, 0
	s_add_i32 s82, s61, s1
	s_add_i32 s78, s82, 0x2000
	v_lshl_add_u64 v[198:199], s[34:35], 0, v[206:207]
	ds_read_b128 v[164:167], v236
	ds_read_b128 v[168:171], v236 offset:1024
	ds_read_b128 v[172:175], v236 offset:2048
	ds_read_b128 v[176:179], v236 offset:3072
	ds_read_b128 v[180:183], v236 offset:4096
	ds_read_b128 v[184:187], v236 offset:5120
	ds_read_b128 v[188:191], v236 offset:6144
	ds_read_b128 v[192:195], v236 offset:7168
	global_load_lds_dwordx4 v[198:199], off
	v_lshl_add_u64 v[198:199], s[34:35], 0, v[202:203]
	s_mov_b32 m0, s83
	s_nop 0
	global_load_lds_dwordx4 v[198:199], off
	s_setprio 1
	s_waitcnt vmcnt(8) lgkmcnt(0)
	s_barrier
	v_mfma_f32_16x16x32_bf16 v[128:131], v[132:135], v[164:167], v[128:131]
	v_mfma_f32_16x16x32_bf16 v[124:127], v[140:143], v[164:167], v[124:127]
	v_mfma_f32_16x16x32_bf16 v[112:115], v[132:135], v[172:175], v[112:115]
	v_mfma_f32_16x16x32_bf16 v[108:111], v[140:143], v[172:175], v[108:111]
	v_mfma_f32_16x16x32_bf16 v[96:99], v[132:135], v[180:183], v[96:99]
	v_mfma_f32_16x16x32_bf16 v[92:95], v[140:143], v[180:183], v[92:95]
	v_mfma_f32_16x16x32_bf16 v[80:83], v[132:135], v[188:191], v[80:83]
	v_mfma_f32_16x16x32_bf16 v[76:79], v[140:143], v[188:191], v[76:79]
	v_mfma_f32_16x16x32_bf16 v[128:131], v[136:139], v[168:171], v[128:131]
	v_mfma_f32_16x16x32_bf16 v[124:127], v[144:147], v[168:171], v[124:127]
	v_mfma_f32_16x16x32_bf16 v[112:115], v[136:139], v[176:179], v[112:115]
	v_mfma_f32_16x16x32_bf16 v[108:111], v[144:147], v[176:179], v[108:111]
	v_mfma_f32_16x16x32_bf16 v[96:99], v[136:139], v[184:187], v[96:99]
	v_mfma_f32_16x16x32_bf16 v[92:95], v[144:147], v[184:187], v[92:95]
	v_mfma_f32_16x16x32_bf16 v[80:83], v[136:139], v[192:195], v[80:83]
	v_mfma_f32_16x16x32_bf16 v[76:79], v[144:147], v[192:195], v[76:79]
	s_setprio 0
	s_setprio 1
	v_mfma_f32_16x16x32_bf16 v[120:123], v[148:151], v[164:167], v[120:123]
	v_mfma_f32_16x16x32_bf16 v[116:119], v[156:159], v[164:167], v[116:119]
	v_mfma_f32_16x16x32_bf16 v[104:107], v[148:151], v[172:175], v[104:107]
	v_mfma_f32_16x16x32_bf16 v[100:103], v[156:159], v[172:175], v[100:103]
	v_mfma_f32_16x16x32_bf16 v[88:91], v[148:151], v[180:183], v[88:91]
	v_mfma_f32_16x16x32_bf16 v[84:87], v[156:159], v[180:183], v[84:87]
	v_mfma_f32_16x16x32_bf16 v[72:75], v[148:151], v[188:191], v[72:75]
	v_mfma_f32_16x16x32_bf16 v[68:71], v[156:159], v[188:191], v[68:71]
	v_mfma_f32_16x16x32_bf16 v[120:123], v[152:155], v[168:171], v[120:123]
	v_mfma_f32_16x16x32_bf16 v[116:119], v[160:163], v[168:171], v[116:119]
	v_mfma_f32_16x16x32_bf16 v[104:107], v[152:155], v[176:179], v[104:107]
	v_mfma_f32_16x16x32_bf16 v[100:103], v[160:163], v[176:179], v[100:103]
	v_mfma_f32_16x16x32_bf16 v[88:91], v[152:155], v[184:187], v[88:91]
	v_mfma_f32_16x16x32_bf16 v[84:87], v[160:163], v[184:187], v[84:87]
	v_mfma_f32_16x16x32_bf16 v[72:75], v[152:155], v[192:195], v[72:75]
	v_mfma_f32_16x16x32_bf16 v[68:71], v[160:163], v[192:195], v[68:71]
	s_barrier
	s_setprio 0
	s_mov_b32 m0, s73
	v_lshl_add_u64 v[198:199], s[52:53], 0, v[204:205]
	ds_read_b128 v[164:167], v236 offset:16384
	ds_read_b128 v[168:171], v236 offset:17408
	ds_read_b128 v[172:175], v236 offset:18432
	ds_read_b128 v[176:179], v236 offset:19456
	ds_read_b128 v[180:183], v236 offset:20480
	ds_read_b128 v[184:187], v236 offset:21504
	ds_read_b128 v[188:191], v236 offset:22528
	ds_read_b128 v[192:195], v236 offset:23552
	global_load_lds_dwordx4 v[198:199], off
	v_lshl_add_u64 v[212:213], s[52:53], 0, v[200:201]
	s_mov_b32 m0, s6
	v_lshl_add_u64 v[214:215], s[30:31], 0, v[204:205]
	global_load_lds_dwordx4 v[212:213], off
	s_mov_b32 m0, s49
	v_lshl_add_u64 v[216:217], vcc, 0, v[202:203]
	global_load_lds_dwordx4 v[214:215], off
	v_lshl_add_u64 v[214:215], s[30:31], 0, v[200:201]
	s_mov_b32 m0, s63
	s_nop 0
	global_load_lds_dwordx4 v[214:215], off
	v_lshl_add_u64 v[214:215], vcc, 0, v[206:207]
	s_mov_b32 m0, s4
	s_nop 0
	global_load_lds_dwordx4 v[214:215], off
	s_mov_b32 m0, s24
	s_nop 0
	global_load_lds_dwordx4 v[216:217], off
	s_setprio 1
	s_waitcnt vmcnt(8) lgkmcnt(0)
	s_barrier
	v_mfma_f32_16x16x32_bf16 v[64:67], v[132:135], v[164:167], v[64:67]
	v_mfma_f32_16x16x32_bf16 v[60:63], v[140:143], v[164:167], v[60:63]
	v_mfma_f32_16x16x32_bf16 v[48:51], v[132:135], v[172:175], v[48:51]
	v_mfma_f32_16x16x32_bf16 v[44:47], v[140:143], v[172:175], v[44:47]
	v_mfma_f32_16x16x32_bf16 v[32:35], v[132:135], v[180:183], v[32:35]
	v_mfma_f32_16x16x32_bf16 v[28:31], v[140:143], v[180:183], v[28:31]
	v_mfma_f32_16x16x32_bf16 v[16:19], v[132:135], v[188:191], v[16:19]
	v_mfma_f32_16x16x32_bf16 v[12:15], v[140:143], v[188:191], v[12:15]
	v_mfma_f32_16x16x32_bf16 v[64:67], v[136:139], v[168:171], v[64:67]
	v_mfma_f32_16x16x32_bf16 v[60:63], v[144:147], v[168:171], v[60:63]
	v_mfma_f32_16x16x32_bf16 v[48:51], v[136:139], v[176:179], v[48:51]
	v_mfma_f32_16x16x32_bf16 v[44:47], v[144:147], v[176:179], v[44:47]
	v_mfma_f32_16x16x32_bf16 v[32:35], v[136:139], v[184:187], v[32:35]
	v_mfma_f32_16x16x32_bf16 v[28:31], v[144:147], v[184:187], v[28:31]
	v_mfma_f32_16x16x32_bf16 v[16:19], v[136:139], v[192:195], v[16:19]
	v_mfma_f32_16x16x32_bf16 v[12:15], v[144:147], v[192:195], v[12:15]
	s_setprio 0
	s_setprio 1
	v_mfma_f32_16x16x32_bf16 v[56:59], v[148:151], v[164:167], v[56:59]
	v_mfma_f32_16x16x32_bf16 v[52:55], v[156:159], v[164:167], v[52:55]
	v_mfma_f32_16x16x32_bf16 v[40:43], v[148:151], v[172:175], v[40:43]
	v_mfma_f32_16x16x32_bf16 v[36:39], v[156:159], v[172:175], v[36:39]
	v_mfma_f32_16x16x32_bf16 v[24:27], v[148:151], v[180:183], v[24:27]
	v_mfma_f32_16x16x32_bf16 v[20:23], v[156:159], v[180:183], v[20:23]
	v_mfma_f32_16x16x32_bf16 v[8:11], v[148:151], v[188:191], v[8:11]
	v_mfma_f32_16x16x32_bf16 v[4:7], v[156:159], v[188:191], v[4:7]
	v_mfma_f32_16x16x32_bf16 v[56:59], v[152:155], v[168:171], v[56:59]
	v_mfma_f32_16x16x32_bf16 v[52:55], v[160:163], v[168:171], v[52:55]
	v_mfma_f32_16x16x32_bf16 v[40:43], v[152:155], v[176:179], v[40:43]
	v_mfma_f32_16x16x32_bf16 v[36:39], v[160:163], v[176:179], v[36:39]
	v_mfma_f32_16x16x32_bf16 v[24:27], v[152:155], v[184:187], v[24:27]
	v_mfma_f32_16x16x32_bf16 v[20:23], v[160:163], v[184:187], v[20:23]
	v_mfma_f32_16x16x32_bf16 v[8:11], v[152:155], v[192:195], v[8:11]
	v_mfma_f32_16x16x32_bf16 v[4:7], v[160:163], v[192:195], v[4:7]
	s_barrier
	s_setprio 0
	v_add_u32_e32 v144, s54, v3
	v_add_u32_e32 v160, s61, v3
	ds_read_b128 v[132:135], v144
	ds_read_b128 v[136:139], v144 offset:1024
	ds_read_b128 v[140:143], v144 offset:2048
	ds_read_b128 v[144:147], v144 offset:3072
	ds_read_b128 v[148:151], v160
	ds_read_b128 v[152:155], v160 offset:1024
	ds_read_b128 v[156:159], v160 offset:2048
	ds_read_b128 v[160:163], v160 offset:3072
	s_mov_b32 m0, s25
	v_lshl_add_u64 v[218:219], s[38:39], 0, v[206:207]
	ds_read_b128 v[164:167], v236 offset:32768
	ds_read_b128 v[168:171], v236 offset:33792
	ds_read_b128 v[172:175], v236 offset:34816
	ds_read_b128 v[176:179], v236 offset:35840
	ds_read_b128 v[180:183], v236 offset:36864
	ds_read_b128 v[184:187], v236 offset:37888
	ds_read_b128 v[188:191], v236 offset:38912
	ds_read_b128 v[192:195], v236 offset:39936
	global_load_lds_dwordx4 v[218:219], off
	v_lshl_add_u64 v[218:219], s[38:39], 0, v[202:203]
	s_mov_b32 m0, s33
	s_nop 0
	global_load_lds_dwordx4 v[218:219], off
	s_setprio 1
	s_waitcnt vmcnt(8) lgkmcnt(0)
	s_barrier
	v_mfma_f32_16x16x32_bf16 v[128:131], v[132:135], v[164:167], v[128:131]
	v_mfma_f32_16x16x32_bf16 v[124:127], v[140:143], v[164:167], v[124:127]
	v_mfma_f32_16x16x32_bf16 v[112:115], v[132:135], v[172:175], v[112:115]
	v_mfma_f32_16x16x32_bf16 v[108:111], v[140:143], v[172:175], v[108:111]
	v_mfma_f32_16x16x32_bf16 v[96:99], v[132:135], v[180:183], v[96:99]
	v_mfma_f32_16x16x32_bf16 v[92:95], v[140:143], v[180:183], v[92:95]
	v_mfma_f32_16x16x32_bf16 v[80:83], v[132:135], v[188:191], v[80:83]
	v_mfma_f32_16x16x32_bf16 v[76:79], v[140:143], v[188:191], v[76:79]
	v_mfma_f32_16x16x32_bf16 v[128:131], v[136:139], v[168:171], v[128:131]
	v_mfma_f32_16x16x32_bf16 v[124:127], v[144:147], v[168:171], v[124:127]
	v_mfma_f32_16x16x32_bf16 v[112:115], v[136:139], v[176:179], v[112:115]
	v_mfma_f32_16x16x32_bf16 v[108:111], v[144:147], v[176:179], v[108:111]
	v_mfma_f32_16x16x32_bf16 v[96:99], v[136:139], v[184:187], v[96:99]
	v_mfma_f32_16x16x32_bf16 v[92:95], v[144:147], v[184:187], v[92:95]
	v_mfma_f32_16x16x32_bf16 v[80:83], v[136:139], v[192:195], v[80:83]
	v_mfma_f32_16x16x32_bf16 v[76:79], v[144:147], v[192:195], v[76:79]
	s_setprio 0
	s_setprio 1
	v_mfma_f32_16x16x32_bf16 v[120:123], v[148:151], v[164:167], v[120:123]
	v_mfma_f32_16x16x32_bf16 v[116:119], v[156:159], v[164:167], v[116:119]
	v_mfma_f32_16x16x32_bf16 v[104:107], v[148:151], v[172:175], v[104:107]
	v_mfma_f32_16x16x32_bf16 v[100:103], v[156:159], v[172:175], v[100:103]
	v_mfma_f32_16x16x32_bf16 v[88:91], v[148:151], v[180:183], v[88:91]
	v_mfma_f32_16x16x32_bf16 v[84:87], v[156:159], v[180:183], v[84:87]
	v_mfma_f32_16x16x32_bf16 v[72:75], v[148:151], v[188:191], v[72:75]
	v_mfma_f32_16x16x32_bf16 v[68:71], v[156:159], v[188:191], v[68:71]
	v_mfma_f32_16x16x32_bf16 v[120:123], v[152:155], v[168:171], v[120:123]
	v_mfma_f32_16x16x32_bf16 v[116:119], v[160:163], v[168:171], v[116:119]
	v_mfma_f32_16x16x32_bf16 v[104:107], v[152:155], v[176:179], v[104:107]
	v_mfma_f32_16x16x32_bf16 v[100:103], v[160:163], v[176:179], v[100:103]
	v_mfma_f32_16x16x32_bf16 v[88:91], v[152:155], v[184:187], v[88:91]
	v_mfma_f32_16x16x32_bf16 v[84:87], v[160:163], v[184:187], v[84:87]
	v_mfma_f32_16x16x32_bf16 v[72:75], v[152:155], v[192:195], v[72:75]
	v_mfma_f32_16x16x32_bf16 v[68:71], v[160:163], v[192:195], v[68:71]
	s_barrier
	s_setprio 0
	s_mov_b32 m0, s0
	v_lshl_add_u64 v[198:199], v[198:199], 0, s[90:91]
	ds_read_b128 v[164:167], v236 offset:49152
	ds_read_b128 v[168:171], v236 offset:50176
	ds_read_b128 v[172:175], v236 offset:51200
	ds_read_b128 v[176:179], v236 offset:52224
	ds_read_b128 v[180:183], v236 offset:53248
	ds_read_b128 v[184:187], v236 offset:54272
	ds_read_b128 v[188:191], v236 offset:55296
	ds_read_b128 v[192:195], v236 offset:56320
	global_load_lds_dwordx4 v[198:199], off
	v_lshl_add_u64 v[198:199], v[212:213], 0, s[90:91]
	s_mov_b32 m0, s45
	s_nop 0
	global_load_lds_dwordx4 v[198:199], off
	v_lshl_add_u64 v[198:199], s[36:37], 0, v[204:205]
	s_mov_b32 m0, s82
	s_nop 0
	global_load_lds_dwordx4 v[198:199], off
	v_lshl_add_u64 v[198:199], s[36:37], 0, v[200:201]
	s_mov_b32 m0, s78
	s_nop 0
	global_load_lds_dwordx4 v[198:199], off
	v_lshl_add_u64 v[198:199], v[214:215], 0, s[90:91]
	s_mov_b32 m0, s40
	s_nop 0
	global_load_lds_dwordx4 v[198:199], off
	v_lshl_add_u64 v[198:199], v[216:217], 0, s[90:91]
	s_mov_b32 m0, s50
	s_nop 0
	global_load_lds_dwordx4 v[198:199], off
	s_setprio 1
	s_waitcnt vmcnt(8) lgkmcnt(0)
	s_barrier
	v_mfma_f32_16x16x32_bf16 v[64:67], v[132:135], v[164:167], v[64:67]
	v_mfma_f32_16x16x32_bf16 v[60:63], v[140:143], v[164:167], v[60:63]
	v_mfma_f32_16x16x32_bf16 v[48:51], v[132:135], v[172:175], v[48:51]
	v_mfma_f32_16x16x32_bf16 v[44:47], v[140:143], v[172:175], v[44:47]
	v_mfma_f32_16x16x32_bf16 v[32:35], v[132:135], v[180:183], v[32:35]
	v_mfma_f32_16x16x32_bf16 v[28:31], v[140:143], v[180:183], v[28:31]
	v_mfma_f32_16x16x32_bf16 v[16:19], v[132:135], v[188:191], v[16:19]
	v_mfma_f32_16x16x32_bf16 v[12:15], v[140:143], v[188:191], v[12:15]
	v_mfma_f32_16x16x32_bf16 v[64:67], v[136:139], v[168:171], v[64:67]
	v_mfma_f32_16x16x32_bf16 v[60:63], v[144:147], v[168:171], v[60:63]
	v_mfma_f32_16x16x32_bf16 v[48:51], v[136:139], v[176:179], v[48:51]
	v_mfma_f32_16x16x32_bf16 v[44:47], v[144:147], v[176:179], v[44:47]
	v_mfma_f32_16x16x32_bf16 v[32:35], v[136:139], v[184:187], v[32:35]
	v_mfma_f32_16x16x32_bf16 v[28:31], v[144:147], v[184:187], v[28:31]
	v_mfma_f32_16x16x32_bf16 v[16:19], v[136:139], v[192:195], v[16:19]
	v_mfma_f32_16x16x32_bf16 v[12:15], v[144:147], v[192:195], v[12:15]
	s_setprio 0
	s_setprio 1
	v_mfma_f32_16x16x32_bf16 v[56:59], v[148:151], v[164:167], v[56:59]
	v_mfma_f32_16x16x32_bf16 v[52:55], v[156:159], v[164:167], v[52:55]
	v_mfma_f32_16x16x32_bf16 v[40:43], v[148:151], v[172:175], v[40:43]
	v_mfma_f32_16x16x32_bf16 v[36:39], v[156:159], v[172:175], v[36:39]
	v_mfma_f32_16x16x32_bf16 v[24:27], v[148:151], v[180:183], v[24:27]
	v_mfma_f32_16x16x32_bf16 v[20:23], v[156:159], v[180:183], v[20:23]
	v_mfma_f32_16x16x32_bf16 v[8:11], v[148:151], v[188:191], v[8:11]
	v_mfma_f32_16x16x32_bf16 v[4:7], v[156:159], v[188:191], v[4:7]
	v_mfma_f32_16x16x32_bf16 v[56:59], v[152:155], v[168:171], v[56:59]
	v_mfma_f32_16x16x32_bf16 v[52:55], v[160:163], v[168:171], v[52:55]
	v_mfma_f32_16x16x32_bf16 v[40:43], v[152:155], v[176:179], v[40:43]
	v_mfma_f32_16x16x32_bf16 v[36:39], v[160:163], v[176:179], v[36:39]
	v_mfma_f32_16x16x32_bf16 v[24:27], v[152:155], v[184:187], v[24:27]
	v_mfma_f32_16x16x32_bf16 v[20:23], v[160:163], v[184:187], v[20:23]
	v_mfma_f32_16x16x32_bf16 v[8:11], v[152:155], v[192:195], v[8:11]
	v_mfma_f32_16x16x32_bf16 v[4:7], v[160:163], v[192:195], v[4:7]
	s_barrier
	s_setprio 0
	s_movk_i32 s30, 0x100
	s_andn2_b64 vcc, exec, s[80:81]
	s_mov_b64 s[36:37], -1
	s_mov_b64 s[80:81], 0
	s_cbranch_vccz .LBB0_1017
	s_and_b64 vcc, exec, s[42:43]
	s_cbranch_vccz .LBB0_1020
	s_barrier

.LBB0_1137:
	s_add_u32 s0, s36, 0xfff80080
	s_addc_u32 s6, s37, -1
	s_add_i32 s49, 0, 0x10000
	s_cmp_eq_u32 s66, 28
	s_cselect_b32 s35, s29, s6
	s_cselect_b32 s34, s64, s0
	v_add_u32_e32 v156, s49, v157
	s_cselect_b32 s31, s23, s39
	s_cselect_b32 s30, s65, s38
	s_add_i32 s0, 0, 0x14000
	ds_read_b128 v[144:147], v156
	ds_read_b128 v[148:151], v156 offset:1024
	ds_read_b128 v[152:155], v156 offset:2048
	ds_read_b128 v[162:165], v156 offset:3072
	v_add_u32_e32 v156, s0, v157
	ds_read_b128 v[166:169], v156
	ds_read_b128 v[170:173], v156 offset:1024
	ds_read_b128 v[174:177], v156 offset:2048
	ds_read_b128 v[178:181], v156 offset:3072
	v_lshl_add_u64 v[194:195], s[36:37], 0, v[140:141]
	s_add_i32 m0, s33, 0xc000
	ds_read_b128 v[182:185], v161
	ds_read_b128 v[186:189], v161 offset:1024
	ds_read_b128 v[190:193], v161 offset:2048
	ds_read_b128 v[200:203], v161 offset:3072
	ds_read_b128 v[204:207], v161 offset:4096
	ds_read_b128 v[208:211], v161 offset:5120
	ds_read_b128 v[212:215], v161 offset:6144
	ds_read_b128 v[216:219], v161 offset:7168
	global_load_lds_dwordx4 v[194:195], off
	v_lshl_add_u64 v[194:195], s[36:37], 0, v[142:143]
	s_add_i32 m0, s33, 0xe000
	s_nop 0
	global_load_lds_dwordx4 v[194:195], off
	s_setprio 1
	s_waitcnt vmcnt(8) lgkmcnt(0)
	s_barrier
	v_mfma_f32_16x16x32_bf16 v[128:131], v[144:147], v[182:185], v[128:131]
	v_mfma_f32_16x16x32_bf16 v[124:127], v[152:155], v[182:185], v[124:127]
	v_mfma_f32_16x16x32_bf16 v[112:115], v[144:147], v[190:193], v[112:115]
	v_mfma_f32_16x16x32_bf16 v[108:111], v[152:155], v[190:193], v[108:111]
	v_mfma_f32_16x16x32_bf16 v[96:99], v[144:147], v[204:207], v[96:99]
	v_mfma_f32_16x16x32_bf16 v[92:95], v[152:155], v[204:207], v[92:95]
	v_mfma_f32_16x16x32_bf16 v[80:83], v[144:147], v[212:215], v[80:83]
	v_mfma_f32_16x16x32_bf16 v[76:79], v[152:155], v[212:215], v[76:79]
	v_mfma_f32_16x16x32_bf16 v[128:131], v[148:151], v[186:189], v[128:131]
	v_mfma_f32_16x16x32_bf16 v[124:127], v[162:165], v[186:189], v[124:127]
	v_mfma_f32_16x16x32_bf16 v[112:115], v[148:151], v[200:203], v[112:115]
	v_mfma_f32_16x16x32_bf16 v[108:111], v[162:165], v[200:203], v[108:111]
	v_mfma_f32_16x16x32_bf16 v[96:99], v[148:151], v[208:211], v[96:99]
	v_mfma_f32_16x16x32_bf16 v[92:95], v[162:165], v[208:211], v[92:95]
	v_mfma_f32_16x16x32_bf16 v[80:83], v[148:151], v[216:219], v[80:83]
	v_mfma_f32_16x16x32_bf16 v[76:79], v[162:165], v[216:219], v[76:79]
	s_setprio 0
	s_setprio 1
	v_mfma_f32_16x16x32_bf16 v[120:123], v[166:169], v[182:185], v[120:123]
	v_mfma_f32_16x16x32_bf16 v[116:119], v[174:177], v[182:185], v[116:119]
	v_mfma_f32_16x16x32_bf16 v[104:107], v[166:169], v[190:193], v[104:107]
	v_mfma_f32_16x16x32_bf16 v[100:103], v[174:177], v[190:193], v[100:103]
	v_mfma_f32_16x16x32_bf16 v[88:91], v[166:169], v[204:207], v[88:91]
	v_mfma_f32_16x16x32_bf16 v[84:87], v[174:177], v[204:207], v[84:87]
	v_mfma_f32_16x16x32_bf16 v[72:75], v[166:169], v[212:215], v[72:75]
	v_mfma_f32_16x16x32_bf16 v[68:71], v[174:177], v[212:215], v[68:71]
	v_mfma_f32_16x16x32_bf16 v[120:123], v[170:173], v[186:189], v[120:123]
	v_mfma_f32_16x16x32_bf16 v[116:119], v[178:181], v[186:189], v[116:119]
	v_mfma_f32_16x16x32_bf16 v[104:107], v[170:173], v[200:203], v[104:107]
	v_mfma_f32_16x16x32_bf16 v[100:103], v[178:181], v[200:203], v[100:103]
	v_mfma_f32_16x16x32_bf16 v[88:91], v[170:173], v[208:211], v[88:91]
	v_mfma_f32_16x16x32_bf16 v[84:87], v[178:181], v[208:211], v[84:87]
	v_mfma_f32_16x16x32_bf16 v[72:75], v[170:173], v[216:219], v[72:75]
	v_mfma_f32_16x16x32_bf16 v[68:71], v[178:181], v[216:219], v[68:71]
	s_barrier
	s_setprio 0
	s_add_i32 s6, s49, s25
	v_lshl_add_u64 v[194:195], s[30:31], 0, v[136:137]
	s_mov_b32 m0, s6
	ds_read_b128 v[182:185], v161 offset:16384
	ds_read_b128 v[186:189], v161 offset:17408
	ds_read_b128 v[190:193], v161 offset:18432
	ds_read_b128 v[200:203], v161 offset:19456
	ds_read_b128 v[204:207], v161 offset:20480
	ds_read_b128 v[208:211], v161 offset:21504
	ds_read_b128 v[212:215], v161 offset:22528
	ds_read_b128 v[216:219], v161 offset:23552
	global_load_lds_dwordx4 v[194:195], off
	s_add_i32 m0, s6, 0x2000
	s_add_u32 s68, s30, 0x80000
	v_lshl_add_u64 v[198:199], s[30:31], 0, v[132:133]
	s_addc_u32 s69, s31, 0
	s_add_i32 s0, s0, s25
	global_load_lds_dwordx4 v[198:199], off
	v_lshl_add_u64 v[220:221], s[68:69], 0, v[136:137]
	s_mov_b32 m0, s0
	v_lshl_add_u64 v[222:223], s[34:35], 0, v[134:135]
	global_load_lds_dwordx4 v[220:221], off
	v_lshl_add_u64 v[220:221], s[68:69], 0, v[132:133]
	s_add_i32 m0, s0, 0x2000
	s_nop 0
	global_load_lds_dwordx4 v[220:221], off
	v_lshl_add_u64 v[220:221], s[34:35], 0, v[138:139]
	s_mov_b32 m0, s33
	s_nop 0
	global_load_lds_dwordx4 v[220:221], off
	s_mov_b32 m0, s40
	s_nop 0
	global_load_lds_dwordx4 v[222:223], off
	s_setprio 1
	s_waitcnt vmcnt(8) lgkmcnt(0)
	s_barrier
	v_mfma_f32_16x16x32_bf16 v[64:67], v[144:147], v[182:185], v[64:67]
	v_mfma_f32_16x16x32_bf16 v[60:63], v[152:155], v[182:185], v[60:63]
	v_mfma_f32_16x16x32_bf16 v[48:51], v[144:147], v[190:193], v[48:51]
	v_mfma_f32_16x16x32_bf16 v[44:47], v[152:155], v[190:193], v[44:47]
	v_mfma_f32_16x16x32_bf16 v[32:35], v[144:147], v[204:207], v[32:35]
	v_mfma_f32_16x16x32_bf16 v[28:31], v[152:155], v[204:207], v[28:31]
	v_mfma_f32_16x16x32_bf16 v[16:19], v[144:147], v[212:215], v[16:19]
	v_mfma_f32_16x16x32_bf16 v[12:15], v[152:155], v[212:215], v[12:15]
	v_mfma_f32_16x16x32_bf16 v[64:67], v[148:151], v[186:189], v[64:67]
	v_mfma_f32_16x16x32_bf16 v[60:63], v[162:165], v[186:189], v[60:63]
	v_mfma_f32_16x16x32_bf16 v[48:51], v[148:151], v[200:203], v[48:51]
	v_mfma_f32_16x16x32_bf16 v[44:47], v[162:165], v[200:203], v[44:47]
	v_mfma_f32_16x16x32_bf16 v[32:35], v[148:151], v[208:211], v[32:35]
	v_mfma_f32_16x16x32_bf16 v[28:31], v[162:165], v[208:211], v[28:31]
	v_mfma_f32_16x16x32_bf16 v[16:19], v[148:151], v[216:219], v[16:19]
	v_mfma_f32_16x16x32_bf16 v[12:15], v[162:165], v[216:219], v[12:15]
	s_setprio 0
	s_setprio 1
	v_mfma_f32_16x16x32_bf16 v[56:59], v[166:169], v[182:185], v[56:59]
	v_mfma_f32_16x16x32_bf16 v[52:55], v[174:177], v[182:185], v[52:55]
	v_mfma_f32_16x16x32_bf16 v[40:43], v[166:169], v[190:193], v[40:43]
	v_mfma_f32_16x16x32_bf16 v[36:39], v[174:177], v[190:193], v[36:39]
	v_mfma_f32_16x16x32_bf16 v[24:27], v[166:169], v[204:207], v[24:27]
	v_mfma_f32_16x16x32_bf16 v[20:23], v[174:177], v[204:207], v[20:23]
	v_mfma_f32_16x16x32_bf16 v[8:11], v[166:169], v[212:215], v[8:11]
	v_mfma_f32_16x16x32_bf16 v[4:7], v[174:177], v[212:215], v[4:7]
	v_mfma_f32_16x16x32_bf16 v[56:59], v[170:173], v[186:189], v[56:59]
	v_mfma_f32_16x16x32_bf16 v[52:55], v[178:181], v[186:189], v[52:55]
	v_mfma_f32_16x16x32_bf16 v[40:43], v[170:173], v[200:203], v[40:43]
	v_mfma_f32_16x16x32_bf16 v[36:39], v[178:181], v[200:203], v[36:39]
	v_mfma_f32_16x16x32_bf16 v[24:27], v[170:173], v[208:211], v[24:27]
	v_mfma_f32_16x16x32_bf16 v[20:23], v[178:181], v[208:211], v[20:23]
	v_mfma_f32_16x16x32_bf16 v[8:11], v[170:173], v[216:219], v[8:11]
	v_mfma_f32_16x16x32_bf16 v[4:7], v[178:181], v[216:219], v[4:7]
	s_barrier
	s_setprio 0
	s_add_i32 s0, 0, 0x18000
	v_add_u32_e32 v156, s0, v157
	s_add_i32 s6, 0, 0x1c000
	ds_read_b128 v[144:147], v156
	ds_read_b128 v[148:151], v156 offset:1024
	ds_read_b128 v[152:155], v156 offset:2048
	ds_read_b128 v[162:165], v156 offset:3072
	v_add_u32_e32 v156, s6, v157
	ds_read_b128 v[166:169], v156
	ds_read_b128 v[170:173], v156 offset:1024
	ds_read_b128 v[174:177], v156 offset:2048
	ds_read_b128 v[178:181], v156 offset:3072
	s_add_u32 s34, s34, 0x80000
	s_addc_u32 s35, s35, 0
	s_mov_b32 m0, s50
	v_lshl_add_u64 v[224:225], s[34:35], 0, v[138:139]
	ds_read_b128 v[182:185], v161 offset:32768
	ds_read_b128 v[186:189], v161 offset:33792
	ds_read_b128 v[190:193], v161 offset:34816
	ds_read_b128 v[200:203], v161 offset:35840
	ds_read_b128 v[204:207], v161 offset:36864
	ds_read_b128 v[208:211], v161 offset:37888
	ds_read_b128 v[212:215], v161 offset:38912
	ds_read_b128 v[216:219], v161 offset:39936
	global_load_lds_dwordx4 v[224:225], off
	v_lshl_add_u64 v[224:225], s[34:35], 0, v[134:135]
	s_mov_b32 m0, s51
	s_nop 0
	global_load_lds_dwordx4 v[224:225], off
	s_setprio 1
	s_waitcnt vmcnt(8) lgkmcnt(0)
	s_barrier
	v_mfma_f32_16x16x32_bf16 v[128:131], v[144:147], v[182:185], v[128:131]
	v_mfma_f32_16x16x32_bf16 v[124:127], v[152:155], v[182:185], v[124:127]
	v_mfma_f32_16x16x32_bf16 v[112:115], v[144:147], v[190:193], v[112:115]
	v_mfma_f32_16x16x32_bf16 v[108:111], v[152:155], v[190:193], v[108:111]
	v_mfma_f32_16x16x32_bf16 v[96:99], v[144:147], v[204:207], v[96:99]
	v_mfma_f32_16x16x32_bf16 v[92:95], v[152:155], v[204:207], v[92:95]
	v_mfma_f32_16x16x32_bf16 v[80:83], v[144:147], v[212:215], v[80:83]
	v_mfma_f32_16x16x32_bf16 v[76:79], v[152:155], v[212:215], v[76:79]
	v_mfma_f32_16x16x32_bf16 v[128:131], v[148:151], v[186:189], v[128:131]
	v_mfma_f32_16x16x32_bf16 v[124:127], v[162:165], v[186:189], v[124:127]
	v_mfma_f32_16x16x32_bf16 v[112:115], v[148:151], v[200:203], v[112:115]
	v_mfma_f32_16x16x32_bf16 v[108:111], v[162:165], v[200:203], v[108:111]
	v_mfma_f32_16x16x32_bf16 v[96:99], v[148:151], v[208:211], v[96:99]
	v_mfma_f32_16x16x32_bf16 v[92:95], v[162:165], v[208:211], v[92:95]
	v_mfma_f32_16x16x32_bf16 v[80:83], v[148:151], v[216:219], v[80:83]
	v_mfma_f32_16x16x32_bf16 v[76:79], v[162:165], v[216:219], v[76:79]
	s_setprio 0
	s_setprio 1
	v_mfma_f32_16x16x32_bf16 v[120:123], v[166:169], v[182:185], v[120:123]
	v_mfma_f32_16x16x32_bf16 v[116:119], v[174:177], v[182:185], v[116:119]
	v_mfma_f32_16x16x32_bf16 v[104:107], v[166:169], v[190:193], v[104:107]
	v_mfma_f32_16x16x32_bf16 v[100:103], v[174:177], v[190:193], v[100:103]
	v_mfma_f32_16x16x32_bf16 v[88:91], v[166:169], v[204:207], v[88:91]
	v_mfma_f32_16x16x32_bf16 v[84:87], v[174:177], v[204:207], v[84:87]
	v_mfma_f32_16x16x32_bf16 v[72:75], v[166:169], v[212:215], v[72:75]
	v_mfma_f32_16x16x32_bf16 v[68:71], v[174:177], v[212:215], v[68:71]
	v_mfma_f32_16x16x32_bf16 v[120:123], v[170:173], v[186:189], v[120:123]
	v_mfma_f32_16x16x32_bf16 v[116:119], v[178:181], v[186:189], v[116:119]
	v_mfma_f32_16x16x32_bf16 v[104:107], v[170:173], v[200:203], v[104:107]
	v_mfma_f32_16x16x32_bf16 v[100:103], v[178:181], v[200:203], v[100:103]
	v_mfma_f32_16x16x32_bf16 v[88:91], v[170:173], v[208:211], v[88:91]
	v_mfma_f32_16x16x32_bf16 v[84:87], v[178:181], v[208:211], v[84:87]
	v_mfma_f32_16x16x32_bf16 v[72:75], v[170:173], v[216:219], v[72:75]
	v_mfma_f32_16x16x32_bf16 v[68:71], v[178:181], v[216:219], v[68:71]
	s_barrier
	s_setprio 0
	s_add_i32 s0, s0, s25
	v_lshl_add_u64 v[194:195], v[194:195], 0, s[90:91]
	s_mov_b32 m0, s0
	ds_read_b128 v[182:185], v161 offset:49152
	ds_read_b128 v[186:189], v161 offset:50176
	ds_read_b128 v[190:193], v161 offset:51200
	ds_read_b128 v[200:203], v161 offset:52224
	ds_read_b128 v[204:207], v161 offset:53248
	ds_read_b128 v[208:211], v161 offset:54272
	ds_read_b128 v[212:215], v161 offset:55296
	ds_read_b128 v[216:219], v161 offset:56320
	global_load_lds_dwordx4 v[194:195], off
	s_add_i32 m0, s0, 0x2000
	s_add_u32 s30, s30, 0x80080
	v_lshl_add_u64 v[194:195], v[198:199], 0, s[90:91]
	s_addc_u32 s31, s31, 0
	s_add_i32 s0, s6, s25
	global_load_lds_dwordx4 v[194:195], off
	v_lshl_add_u64 v[194:195], s[30:31], 0, v[136:137]
	s_mov_b32 m0, s0
	s_nop 0
	global_load_lds_dwordx4 v[194:195], off
	v_lshl_add_u64 v[194:195], s[30:31], 0, v[132:133]
	s_add_i32 m0, s0, 0x2000
	s_nop 0
	global_load_lds_dwordx4 v[194:195], off
	v_lshl_add_u64 v[194:195], v[220:221], 0, s[90:91]
	s_mov_b32 m0, s55
	s_nop 0
	global_load_lds_dwordx4 v[194:195], off
	v_lshl_add_u64 v[194:195], v[222:223], 0, s[90:91]
	s_mov_b32 m0, s60
	s_nop 0
	global_load_lds_dwordx4 v[194:195], off
	s_setprio 1
	s_waitcnt vmcnt(8) lgkmcnt(0)
	s_barrier
	v_mfma_f32_16x16x32_bf16 v[64:67], v[144:147], v[182:185], v[64:67]
	v_mfma_f32_16x16x32_bf16 v[60:63], v[152:155], v[182:185], v[60:63]
	v_mfma_f32_16x16x32_bf16 v[48:51], v[144:147], v[190:193], v[48:51]
	v_mfma_f32_16x16x32_bf16 v[44:47], v[152:155], v[190:193], v[44:47]
	v_mfma_f32_16x16x32_bf16 v[32:35], v[144:147], v[204:207], v[32:35]
	v_mfma_f32_16x16x32_bf16 v[28:31], v[152:155], v[204:207], v[28:31]
	v_mfma_f32_16x16x32_bf16 v[16:19], v[144:147], v[212:215], v[16:19]
	v_mfma_f32_16x16x32_bf16 v[12:15], v[152:155], v[212:215], v[12:15]
	v_mfma_f32_16x16x32_bf16 v[64:67], v[148:151], v[186:189], v[64:67]
	v_mfma_f32_16x16x32_bf16 v[60:63], v[162:165], v[186:189], v[60:63]
	v_mfma_f32_16x16x32_bf16 v[48:51], v[148:151], v[200:203], v[48:51]
	v_mfma_f32_16x16x32_bf16 v[44:47], v[162:165], v[200:203], v[44:47]
	v_mfma_f32_16x16x32_bf16 v[32:35], v[148:151], v[208:211], v[32:35]
	v_mfma_f32_16x16x32_bf16 v[28:31], v[162:165], v[208:211], v[28:31]
	v_mfma_f32_16x16x32_bf16 v[16:19], v[148:151], v[216:219], v[16:19]
	v_mfma_f32_16x16x32_bf16 v[12:15], v[162:165], v[216:219], v[12:15]
	s_setprio 0
	s_setprio 1
	v_mfma_f32_16x16x32_bf16 v[56:59], v[166:169], v[182:185], v[56:59]
	v_mfma_f32_16x16x32_bf16 v[52:55], v[174:177], v[182:185], v[52:55]
	v_mfma_f32_16x16x32_bf16 v[40:43], v[166:169], v[190:193], v[40:43]
	v_mfma_f32_16x16x32_bf16 v[36:39], v[174:177], v[190:193], v[36:39]
	v_mfma_f32_16x16x32_bf16 v[24:27], v[166:169], v[204:207], v[24:27]
	v_mfma_f32_16x16x32_bf16 v[20:23], v[174:177], v[204:207], v[20:23]
	v_mfma_f32_16x16x32_bf16 v[8:11], v[166:169], v[212:215], v[8:11]
	v_mfma_f32_16x16x32_bf16 v[4:7], v[174:177], v[212:215], v[4:7]
	v_mfma_f32_16x16x32_bf16 v[56:59], v[170:173], v[186:189], v[56:59]
	v_mfma_f32_16x16x32_bf16 v[52:55], v[178:181], v[186:189], v[52:55]
	v_mfma_f32_16x16x32_bf16 v[40:43], v[170:173], v[200:203], v[40:43]
	v_mfma_f32_16x16x32_bf16 v[36:39], v[178:181], v[200:203], v[36:39]
	v_mfma_f32_16x16x32_bf16 v[24:27], v[170:173], v[208:211], v[24:27]
	v_mfma_f32_16x16x32_bf16 v[20:23], v[178:181], v[208:211], v[20:23]
	v_mfma_f32_16x16x32_bf16 v[8:11], v[170:173], v[216:219], v[8:11]
	v_mfma_f32_16x16x32_bf16 v[4:7], v[178:181], v[216:219], v[4:7]
	s_barrier
	s_setprio 0
	s_add_i32 s66, s66, 2
	s_add_u32 s36, s36, 0x100
	s_addc_u32 s37, s37, 0
	s_add_u32 s38, s38, 0x100
	s_addc_u32 s39, s39, 0
	s_cmp_gt_u32 s66, 29
	s_cbranch_scc0 .LBB0_1137
	s_and_b64 vcc, exec, s[20:21]
	s_cbranch_vccz .LBB0_1140
	s_barrier

.LBB0_1167:
	s_add_u32 s0, s36, 0xfff80080
	s_addc_u32 s6, s37, -1
	s_add_i32 s49, 0, 0x10000
	s_cmp_eq_u32 s67, 28
	s_cselect_b32 s35, s43, s6
	s_cselect_b32 s34, s65, s0
	v_add_u32_e32 v156, s49, v157
	s_cselect_b32 s31, s29, s39
	s_cselect_b32 s30, s66, s38
	s_add_i32 s0, 0, 0x14000
	ds_read_b128 v[144:147], v156
	ds_read_b128 v[148:151], v156 offset:1024
	ds_read_b128 v[152:155], v156 offset:2048
	ds_read_b128 v[162:165], v156 offset:3072
	v_add_u32_e32 v156, s0, v157
	ds_read_b128 v[166:169], v156
	ds_read_b128 v[170:173], v156 offset:1024
	ds_read_b128 v[174:177], v156 offset:2048
	ds_read_b128 v[178:181], v156 offset:3072
	v_lshl_add_u64 v[194:195], s[36:37], 0, v[140:141]
	s_add_i32 m0, s25, 0xc000
	ds_read_b128 v[182:185], v161
	ds_read_b128 v[186:189], v161 offset:1024
	ds_read_b128 v[190:193], v161 offset:2048
	ds_read_b128 v[200:203], v161 offset:3072
	ds_read_b128 v[204:207], v161 offset:4096
	ds_read_b128 v[208:211], v161 offset:5120
	ds_read_b128 v[212:215], v161 offset:6144
	ds_read_b128 v[216:219], v161 offset:7168
	global_load_lds_dwordx4 v[194:195], off
	v_lshl_add_u64 v[194:195], s[36:37], 0, v[142:143]
	s_add_i32 m0, s25, 0xe000
	s_nop 0
	global_load_lds_dwordx4 v[194:195], off
	s_setprio 1
	s_waitcnt vmcnt(8) lgkmcnt(0)
	s_barrier
	v_mfma_f32_16x16x32_bf16 v[128:131], v[144:147], v[182:185], v[128:131]
	v_mfma_f32_16x16x32_bf16 v[124:127], v[152:155], v[182:185], v[124:127]
	v_mfma_f32_16x16x32_bf16 v[112:115], v[144:147], v[190:193], v[112:115]
	v_mfma_f32_16x16x32_bf16 v[108:111], v[152:155], v[190:193], v[108:111]
	v_mfma_f32_16x16x32_bf16 v[96:99], v[144:147], v[204:207], v[96:99]
	v_mfma_f32_16x16x32_bf16 v[92:95], v[152:155], v[204:207], v[92:95]
	v_mfma_f32_16x16x32_bf16 v[80:83], v[144:147], v[212:215], v[80:83]
	v_mfma_f32_16x16x32_bf16 v[76:79], v[152:155], v[212:215], v[76:79]
	v_mfma_f32_16x16x32_bf16 v[128:131], v[148:151], v[186:189], v[128:131]
	v_mfma_f32_16x16x32_bf16 v[124:127], v[162:165], v[186:189], v[124:127]
	v_mfma_f32_16x16x32_bf16 v[112:115], v[148:151], v[200:203], v[112:115]
	v_mfma_f32_16x16x32_bf16 v[108:111], v[162:165], v[200:203], v[108:111]
	v_mfma_f32_16x16x32_bf16 v[96:99], v[148:151], v[208:211], v[96:99]
	v_mfma_f32_16x16x32_bf16 v[92:95], v[162:165], v[208:211], v[92:95]
	v_mfma_f32_16x16x32_bf16 v[80:83], v[148:151], v[216:219], v[80:83]
	v_mfma_f32_16x16x32_bf16 v[76:79], v[162:165], v[216:219], v[76:79]
	s_setprio 0
	s_setprio 1
	v_mfma_f32_16x16x32_bf16 v[120:123], v[166:169], v[182:185], v[120:123]
	v_mfma_f32_16x16x32_bf16 v[116:119], v[174:177], v[182:185], v[116:119]
	v_mfma_f32_16x16x32_bf16 v[104:107], v[166:169], v[190:193], v[104:107]
	v_mfma_f32_16x16x32_bf16 v[100:103], v[174:177], v[190:193], v[100:103]
	v_mfma_f32_16x16x32_bf16 v[88:91], v[166:169], v[204:207], v[88:91]
	v_mfma_f32_16x16x32_bf16 v[84:87], v[174:177], v[204:207], v[84:87]
	v_mfma_f32_16x16x32_bf16 v[72:75], v[166:169], v[212:215], v[72:75]
	v_mfma_f32_16x16x32_bf16 v[68:71], v[174:177], v[212:215], v[68:71]
	v_mfma_f32_16x16x32_bf16 v[120:123], v[170:173], v[186:189], v[120:123]
	v_mfma_f32_16x16x32_bf16 v[116:119], v[178:181], v[186:189], v[116:119]
	v_mfma_f32_16x16x32_bf16 v[104:107], v[170:173], v[200:203], v[104:107]
	v_mfma_f32_16x16x32_bf16 v[100:103], v[178:181], v[200:203], v[100:103]
	v_mfma_f32_16x16x32_bf16 v[88:91], v[170:173], v[208:211], v[88:91]
	v_mfma_f32_16x16x32_bf16 v[84:87], v[178:181], v[208:211], v[84:87]
	v_mfma_f32_16x16x32_bf16 v[72:75], v[170:173], v[216:219], v[72:75]
	v_mfma_f32_16x16x32_bf16 v[68:71], v[178:181], v[216:219], v[68:71]
	s_barrier
	s_setprio 0
	s_add_i32 s6, s49, s1
	v_lshl_add_u64 v[194:195], s[30:31], 0, v[136:137]
	s_mov_b32 m0, s6
	ds_read_b128 v[182:185], v161 offset:16384
	ds_read_b128 v[186:189], v161 offset:17408
	ds_read_b128 v[190:193], v161 offset:18432
	ds_read_b128 v[200:203], v161 offset:19456
	ds_read_b128 v[204:207], v161 offset:20480
	ds_read_b128 v[208:211], v161 offset:21504
	ds_read_b128 v[212:215], v161 offset:22528
	ds_read_b128 v[216:219], v161 offset:23552
	global_load_lds_dwordx4 v[194:195], off
	s_add_i32 m0, s6, 0x2000
	s_add_u32 s68, s30, 0x80000
	v_lshl_add_u64 v[198:199], s[30:31], 0, v[132:133]
	s_addc_u32 s69, s31, 0
	s_add_i32 s0, s0, s1
	global_load_lds_dwordx4 v[198:199], off
	v_lshl_add_u64 v[220:221], s[68:69], 0, v[136:137]
	s_mov_b32 m0, s0
	v_lshl_add_u64 v[222:223], s[34:35], 0, v[134:135]
	global_load_lds_dwordx4 v[220:221], off
	v_lshl_add_u64 v[220:221], s[68:69], 0, v[132:133]
	s_add_i32 m0, s0, 0x2000
	s_nop 0
	global_load_lds_dwordx4 v[220:221], off
	v_lshl_add_u64 v[220:221], s[34:35], 0, v[138:139]
	s_mov_b32 m0, s25
	s_nop 0
	global_load_lds_dwordx4 v[220:221], off
	s_mov_b32 m0, s33
	s_nop 0
	global_load_lds_dwordx4 v[222:223], off
	s_setprio 1
	s_waitcnt vmcnt(8) lgkmcnt(0)
	s_barrier
	v_mfma_f32_16x16x32_bf16 v[64:67], v[144:147], v[182:185], v[64:67]
	v_mfma_f32_16x16x32_bf16 v[60:63], v[152:155], v[182:185], v[60:63]
	v_mfma_f32_16x16x32_bf16 v[48:51], v[144:147], v[190:193], v[48:51]
	v_mfma_f32_16x16x32_bf16 v[44:47], v[152:155], v[190:193], v[44:47]
	v_mfma_f32_16x16x32_bf16 v[32:35], v[144:147], v[204:207], v[32:35]
	v_mfma_f32_16x16x32_bf16 v[28:31], v[152:155], v[204:207], v[28:31]
	v_mfma_f32_16x16x32_bf16 v[16:19], v[144:147], v[212:215], v[16:19]
	v_mfma_f32_16x16x32_bf16 v[12:15], v[152:155], v[212:215], v[12:15]
	v_mfma_f32_16x16x32_bf16 v[64:67], v[148:151], v[186:189], v[64:67]
	v_mfma_f32_16x16x32_bf16 v[60:63], v[162:165], v[186:189], v[60:63]
	v_mfma_f32_16x16x32_bf16 v[48:51], v[148:151], v[200:203], v[48:51]
	v_mfma_f32_16x16x32_bf16 v[44:47], v[162:165], v[200:203], v[44:47]
	v_mfma_f32_16x16x32_bf16 v[32:35], v[148:151], v[208:211], v[32:35]
	v_mfma_f32_16x16x32_bf16 v[28:31], v[162:165], v[208:211], v[28:31]
	v_mfma_f32_16x16x32_bf16 v[16:19], v[148:151], v[216:219], v[16:19]
	v_mfma_f32_16x16x32_bf16 v[12:15], v[162:165], v[216:219], v[12:15]
	s_setprio 0
	s_setprio 1
	v_mfma_f32_16x16x32_bf16 v[56:59], v[166:169], v[182:185], v[56:59]
	v_mfma_f32_16x16x32_bf16 v[52:55], v[174:177], v[182:185], v[52:55]
	v_mfma_f32_16x16x32_bf16 v[40:43], v[166:169], v[190:193], v[40:43]
	v_mfma_f32_16x16x32_bf16 v[36:39], v[174:177], v[190:193], v[36:39]
	v_mfma_f32_16x16x32_bf16 v[24:27], v[166:169], v[204:207], v[24:27]
	v_mfma_f32_16x16x32_bf16 v[20:23], v[174:177], v[204:207], v[20:23]
	v_mfma_f32_16x16x32_bf16 v[8:11], v[166:169], v[212:215], v[8:11]
	v_mfma_f32_16x16x32_bf16 v[4:7], v[174:177], v[212:215], v[4:7]
	v_mfma_f32_16x16x32_bf16 v[56:59], v[170:173], v[186:189], v[56:59]
	v_mfma_f32_16x16x32_bf16 v[52:55], v[178:181], v[186:189], v[52:55]
	v_mfma_f32_16x16x32_bf16 v[40:43], v[170:173], v[200:203], v[40:43]
	v_mfma_f32_16x16x32_bf16 v[36:39], v[178:181], v[200:203], v[36:39]
	v_mfma_f32_16x16x32_bf16 v[24:27], v[170:173], v[208:211], v[24:27]
	v_mfma_f32_16x16x32_bf16 v[20:23], v[178:181], v[208:211], v[20:23]
	v_mfma_f32_16x16x32_bf16 v[8:11], v[170:173], v[216:219], v[8:11]
	v_mfma_f32_16x16x32_bf16 v[4:7], v[178:181], v[216:219], v[4:7]
	s_barrier
	s_setprio 0
	s_add_i32 s0, 0, 0x18000
	v_add_u32_e32 v156, s0, v157
	s_add_i32 s6, 0, 0x1c000
	ds_read_b128 v[144:147], v156
	ds_read_b128 v[148:151], v156 offset:1024
	ds_read_b128 v[152:155], v156 offset:2048
	ds_read_b128 v[162:165], v156 offset:3072
	v_add_u32_e32 v156, s6, v157
	ds_read_b128 v[166:169], v156
	ds_read_b128 v[170:173], v156 offset:1024
	ds_read_b128 v[174:177], v156 offset:2048
	ds_read_b128 v[178:181], v156 offset:3072
	s_add_u32 s34, s34, 0x80000
	s_addc_u32 s35, s35, 0
	s_mov_b32 m0, s40
	v_lshl_add_u64 v[224:225], s[34:35], 0, v[138:139]
	ds_read_b128 v[182:185], v161 offset:32768
	ds_read_b128 v[186:189], v161 offset:33792
	ds_read_b128 v[190:193], v161 offset:34816
	ds_read_b128 v[200:203], v161 offset:35840
	ds_read_b128 v[204:207], v161 offset:36864
	ds_read_b128 v[208:211], v161 offset:37888
	ds_read_b128 v[212:215], v161 offset:38912
	ds_read_b128 v[216:219], v161 offset:39936
	global_load_lds_dwordx4 v[224:225], off
	v_lshl_add_u64 v[224:225], s[34:35], 0, v[134:135]
	s_mov_b32 m0, s50
	s_nop 0
	global_load_lds_dwordx4 v[224:225], off
	s_setprio 1
	s_waitcnt vmcnt(8) lgkmcnt(0)
	s_barrier
	v_mfma_f32_16x16x32_bf16 v[128:131], v[144:147], v[182:185], v[128:131]
	v_mfma_f32_16x16x32_bf16 v[124:127], v[152:155], v[182:185], v[124:127]
	v_mfma_f32_16x16x32_bf16 v[112:115], v[144:147], v[190:193], v[112:115]
	v_mfma_f32_16x16x32_bf16 v[108:111], v[152:155], v[190:193], v[108:111]
	v_mfma_f32_16x16x32_bf16 v[96:99], v[144:147], v[204:207], v[96:99]
	v_mfma_f32_16x16x32_bf16 v[92:95], v[152:155], v[204:207], v[92:95]
	v_mfma_f32_16x16x32_bf16 v[80:83], v[144:147], v[212:215], v[80:83]
	v_mfma_f32_16x16x32_bf16 v[76:79], v[152:155], v[212:215], v[76:79]
	v_mfma_f32_16x16x32_bf16 v[128:131], v[148:151], v[186:189], v[128:131]
	v_mfma_f32_16x16x32_bf16 v[124:127], v[162:165], v[186:189], v[124:127]
	v_mfma_f32_16x16x32_bf16 v[112:115], v[148:151], v[200:203], v[112:115]
	v_mfma_f32_16x16x32_bf16 v[108:111], v[162:165], v[200:203], v[108:111]
	v_mfma_f32_16x16x32_bf16 v[96:99], v[148:151], v[208:211], v[96:99]
	v_mfma_f32_16x16x32_bf16 v[92:95], v[162:165], v[208:211], v[92:95]
	v_mfma_f32_16x16x32_bf16 v[80:83], v[148:151], v[216:219], v[80:83]
	v_mfma_f32_16x16x32_bf16 v[76:79], v[162:165], v[216:219], v[76:79]
	s_setprio 0
	s_setprio 1
	v_mfma_f32_16x16x32_bf16 v[120:123], v[166:169], v[182:185], v[120:123]
	v_mfma_f32_16x16x32_bf16 v[116:119], v[174:177], v[182:185], v[116:119]
	v_mfma_f32_16x16x32_bf16 v[104:107], v[166:169], v[190:193], v[104:107]
	v_mfma_f32_16x16x32_bf16 v[100:103], v[174:177], v[190:193], v[100:103]
	v_mfma_f32_16x16x32_bf16 v[88:91], v[166:169], v[204:207], v[88:91]
	v_mfma_f32_16x16x32_bf16 v[84:87], v[174:177], v[204:207], v[84:87]
	v_mfma_f32_16x16x32_bf16 v[72:75], v[166:169], v[212:215], v[72:75]
	v_mfma_f32_16x16x32_bf16 v[68:71], v[174:177], v[212:215], v[68:71]
	v_mfma_f32_16x16x32_bf16 v[120:123], v[170:173], v[186:189], v[120:123]
	v_mfma_f32_16x16x32_bf16 v[116:119], v[178:181], v[186:189], v[116:119]
	v_mfma_f32_16x16x32_bf16 v[104:107], v[170:173], v[200:203], v[104:107]
	v_mfma_f32_16x16x32_bf16 v[100:103], v[178:181], v[200:203], v[100:103]
	v_mfma_f32_16x16x32_bf16 v[88:91], v[170:173], v[208:211], v[88:91]
	v_mfma_f32_16x16x32_bf16 v[84:87], v[178:181], v[208:211], v[84:87]
	v_mfma_f32_16x16x32_bf16 v[72:75], v[170:173], v[216:219], v[72:75]
	v_mfma_f32_16x16x32_bf16 v[68:71], v[178:181], v[216:219], v[68:71]
	s_barrier
	s_setprio 0
	s_add_i32 s0, s0, s1
	v_lshl_add_u64 v[194:195], v[194:195], 0, s[90:91]
	s_mov_b32 m0, s0
	ds_read_b128 v[182:185], v161 offset:49152
	ds_read_b128 v[186:189], v161 offset:50176
	ds_read_b128 v[190:193], v161 offset:51200
	ds_read_b128 v[200:203], v161 offset:52224
	ds_read_b128 v[204:207], v161 offset:53248
	ds_read_b128 v[208:211], v161 offset:54272
	ds_read_b128 v[212:215], v161 offset:55296
	ds_read_b128 v[216:219], v161 offset:56320
	global_load_lds_dwordx4 v[194:195], off
	s_add_i32 m0, s0, 0x2000
	s_add_u32 s30, s30, 0x80080
	v_lshl_add_u64 v[194:195], v[198:199], 0, s[90:91]
	s_addc_u32 s31, s31, 0
	s_add_i32 s0, s6, s1
	global_load_lds_dwordx4 v[194:195], off
	v_lshl_add_u64 v[194:195], s[30:31], 0, v[136:137]
	s_mov_b32 m0, s0
	s_nop 0
	global_load_lds_dwordx4 v[194:195], off
	v_lshl_add_u64 v[194:195], s[30:31], 0, v[132:133]
	s_add_i32 m0, s0, 0x2000
	s_nop 0
	global_load_lds_dwordx4 v[194:195], off
	v_lshl_add_u64 v[194:195], v[220:221], 0, s[90:91]
	s_mov_b32 m0, s51
	s_nop 0
	global_load_lds_dwordx4 v[194:195], off
	v_lshl_add_u64 v[194:195], v[222:223], 0, s[90:91]
	s_mov_b32 m0, s55
	s_nop 0
	global_load_lds_dwordx4 v[194:195], off
	s_setprio 1
	s_waitcnt vmcnt(8) lgkmcnt(0)
	s_barrier
	v_mfma_f32_16x16x32_bf16 v[64:67], v[144:147], v[182:185], v[64:67]
	v_mfma_f32_16x16x32_bf16 v[60:63], v[152:155], v[182:185], v[60:63]
	v_mfma_f32_16x16x32_bf16 v[48:51], v[144:147], v[190:193], v[48:51]
	v_mfma_f32_16x16x32_bf16 v[44:47], v[152:155], v[190:193], v[44:47]
	v_mfma_f32_16x16x32_bf16 v[32:35], v[144:147], v[204:207], v[32:35]
	v_mfma_f32_16x16x32_bf16 v[28:31], v[152:155], v[204:207], v[28:31]
	v_mfma_f32_16x16x32_bf16 v[16:19], v[144:147], v[212:215], v[16:19]
	v_mfma_f32_16x16x32_bf16 v[12:15], v[152:155], v[212:215], v[12:15]
	v_mfma_f32_16x16x32_bf16 v[64:67], v[148:151], v[186:189], v[64:67]
	v_mfma_f32_16x16x32_bf16 v[60:63], v[162:165], v[186:189], v[60:63]
	v_mfma_f32_16x16x32_bf16 v[48:51], v[148:151], v[200:203], v[48:51]
	v_mfma_f32_16x16x32_bf16 v[44:47], v[162:165], v[200:203], v[44:47]
	v_mfma_f32_16x16x32_bf16 v[32:35], v[148:151], v[208:211], v[32:35]
	v_mfma_f32_16x16x32_bf16 v[28:31], v[162:165], v[208:211], v[28:31]
	v_mfma_f32_16x16x32_bf16 v[16:19], v[148:151], v[216:219], v[16:19]
	v_mfma_f32_16x16x32_bf16 v[12:15], v[162:165], v[216:219], v[12:15]
	s_setprio 0
	s_setprio 1
	v_mfma_f32_16x16x32_bf16 v[56:59], v[166:169], v[182:185], v[56:59]
	v_mfma_f32_16x16x32_bf16 v[52:55], v[174:177], v[182:185], v[52:55]
	v_mfma_f32_16x16x32_bf16 v[40:43], v[166:169], v[190:193], v[40:43]
	v_mfma_f32_16x16x32_bf16 v[36:39], v[174:177], v[190:193], v[36:39]
	v_mfma_f32_16x16x32_bf16 v[24:27], v[166:169], v[204:207], v[24:27]
	v_mfma_f32_16x16x32_bf16 v[20:23], v[174:177], v[204:207], v[20:23]
	v_mfma_f32_16x16x32_bf16 v[8:11], v[166:169], v[212:215], v[8:11]
	v_mfma_f32_16x16x32_bf16 v[4:7], v[174:177], v[212:215], v[4:7]
	v_mfma_f32_16x16x32_bf16 v[56:59], v[170:173], v[186:189], v[56:59]
	v_mfma_f32_16x16x32_bf16 v[52:55], v[178:181], v[186:189], v[52:55]
	v_mfma_f32_16x16x32_bf16 v[40:43], v[170:173], v[200:203], v[40:43]
	v_mfma_f32_16x16x32_bf16 v[36:39], v[178:181], v[200:203], v[36:39]
	v_mfma_f32_16x16x32_bf16 v[24:27], v[170:173], v[208:211], v[24:27]
	v_mfma_f32_16x16x32_bf16 v[20:23], v[178:181], v[208:211], v[20:23]
	v_mfma_f32_16x16x32_bf16 v[8:11], v[170:173], v[216:219], v[8:11]
	v_mfma_f32_16x16x32_bf16 v[4:7], v[178:181], v[216:219], v[4:7]
	s_barrier
	s_setprio 0
	s_add_i32 s67, s67, 2
	s_add_u32 s36, s36, 0x100
	s_addc_u32 s37, s37, 0
	s_add_u32 s38, s38, 0x100
	s_addc_u32 s39, s39, 0
	s_cmp_gt_u32 s67, 29
	s_cbranch_scc0 .LBB0_1167
	s_and_b64 vcc, exec, s[20:21]
	s_cbranch_vccz .LBB0_1170
	s_barrier

.LBB0_1186:
	s_add_u32 s0, s64, s30
	s_addc_u32 s6, s65, 0
	s_add_u32 s31, s0, 0x100
	s_addc_u32 s38, s6, 0
	s_and_b64 s[34:35], s[36:37], exec
	s_cselect_b32 s69, s29, s38
	s_cselect_b32 s68, s77, s31
	s_add_u32 s30, s62, s30
	s_addc_u32 s31, s63, 0
	s_add_u32 s34, s30, 0x100
	s_addc_u32 s35, s31, 0
	s_add_i32 s82, 0, 0x10000
	s_and_b64 s[30:31], s[36:37], exec
	s_cselect_b32 s53, s23, s35
	s_cselect_b32 s52, s78, s34
	s_add_i32 s37, 0, 0x14000
	s_add_u32 s34, s0, 0x10080
	s_addc_u32 s35, s6, 0
	s_add_i32 s84, s82, s4
	s_add_i32 m0, s46, 0xc000
	s_add_i32 s85, s46, 0xe000
	s_add_i32 s6, s84, 0x2000
	v_add_u32_e32 v140, s82, v142
	s_add_u32 s30, s52, 0x10000
	ds_read_b128 v[146:149], v140
	ds_read_b128 v[150:153], v140 offset:1024
	ds_read_b128 v[154:157], v140 offset:2048
	ds_read_b128 v[158:161], v140 offset:3072
	v_add_u32_e32 v140, s37, v142
	s_addc_u32 s31, s53, 0
	s_add_i32 s49, s37, s4
	ds_read_b128 v[162:165], v140
	ds_read_b128 v[166:169], v140 offset:1024
	ds_read_b128 v[170:173], v140 offset:2048
	ds_read_b128 v[174:177], v140 offset:3072
	s_add_i32 s81, s49, 0x2000
	s_add_i32 s54, 0, 0x18000
	s_add_i32 s73, 0, 0x1c000
	s_add_u32 s38, s68, 0x10000
	s_addc_u32 s39, s69, 0
	s_add_i32 s0, s54, s4
	s_add_i32 s80, s0, 0x2000
	s_add_u32 s36, s52, 0x10080
	s_addc_u32 s37, s53, 0
	s_add_i32 s83, s73, s4
	s_add_i32 s82, s83, 0x2000
	v_lshl_add_u64 v[140:141], s[34:35], 0, v[138:139]
	ds_read_b128 v[178:181], v144
	ds_read_b128 v[182:185], v144 offset:1024
	ds_read_b128 v[186:189], v144 offset:2048
	ds_read_b128 v[190:193], v144 offset:3072
	ds_read_b128 v[200:203], v144 offset:4096
	ds_read_b128 v[204:207], v144 offset:5120
	ds_read_b128 v[208:211], v144 offset:6144
	ds_read_b128 v[212:215], v144 offset:7168
	global_load_lds_dwordx4 v[140:141], off
	v_lshl_add_u64 v[140:141], s[34:35], 0, v[134:135]
	s_mov_b32 m0, s85
	s_nop 0
	global_load_lds_dwordx4 v[140:141], off
	s_setprio 1
	s_waitcnt vmcnt(8) lgkmcnt(0)
	s_barrier
	v_mfma_f32_16x16x32_bf16 v[128:131], v[146:149], v[178:181], v[128:131]
	v_mfma_f32_16x16x32_bf16 v[124:127], v[154:157], v[178:181], v[124:127]
	v_mfma_f32_16x16x32_bf16 v[120:123], v[146:149], v[186:189], v[120:123]
	v_mfma_f32_16x16x32_bf16 v[112:115], v[154:157], v[186:189], v[112:115]
	v_mfma_f32_16x16x32_bf16 v[104:107], v[146:149], v[200:203], v[104:107]
	v_mfma_f32_16x16x32_bf16 v[96:99], v[154:157], v[200:203], v[96:99]
	v_mfma_f32_16x16x32_bf16 v[88:91], v[146:149], v[208:211], v[88:91]
	v_mfma_f32_16x16x32_bf16 v[80:83], v[154:157], v[208:211], v[80:83]
	v_mfma_f32_16x16x32_bf16 v[128:131], v[150:153], v[182:185], v[128:131]
	v_mfma_f32_16x16x32_bf16 v[124:127], v[158:161], v[182:185], v[124:127]
	v_mfma_f32_16x16x32_bf16 v[120:123], v[150:153], v[190:193], v[120:123]
	v_mfma_f32_16x16x32_bf16 v[112:115], v[158:161], v[190:193], v[112:115]
	v_mfma_f32_16x16x32_bf16 v[104:107], v[150:153], v[204:207], v[104:107]
	v_mfma_f32_16x16x32_bf16 v[96:99], v[158:161], v[204:207], v[96:99]
	v_mfma_f32_16x16x32_bf16 v[88:91], v[150:153], v[212:215], v[88:91]
	v_mfma_f32_16x16x32_bf16 v[80:83], v[158:161], v[212:215], v[80:83]
	s_setprio 0
	s_setprio 1
	v_mfma_f32_16x16x32_bf16 v[116:119], v[162:165], v[178:181], v[116:119]
	v_mfma_f32_16x16x32_bf16 v[108:111], v[170:173], v[178:181], v[108:111]
	v_mfma_f32_16x16x32_bf16 v[100:103], v[162:165], v[186:189], v[100:103]
	v_mfma_f32_16x16x32_bf16 v[92:95], v[170:173], v[186:189], v[92:95]
	v_mfma_f32_16x16x32_bf16 v[84:87], v[162:165], v[200:203], v[84:87]
	v_mfma_f32_16x16x32_bf16 v[76:79], v[170:173], v[200:203], v[76:79]
	v_mfma_f32_16x16x32_bf16 v[72:75], v[162:165], v[208:211], v[72:75]
	v_mfma_f32_16x16x32_bf16 v[68:71], v[170:173], v[208:211], v[68:71]
	v_mfma_f32_16x16x32_bf16 v[116:119], v[166:169], v[182:185], v[116:119]
	v_mfma_f32_16x16x32_bf16 v[108:111], v[174:177], v[182:185], v[108:111]
	v_mfma_f32_16x16x32_bf16 v[100:103], v[166:169], v[190:193], v[100:103]
	v_mfma_f32_16x16x32_bf16 v[92:95], v[174:177], v[190:193], v[92:95]
	v_mfma_f32_16x16x32_bf16 v[84:87], v[166:169], v[204:207], v[84:87]
	v_mfma_f32_16x16x32_bf16 v[76:79], v[174:177], v[204:207], v[76:79]
	v_mfma_f32_16x16x32_bf16 v[72:75], v[166:169], v[212:215], v[72:75]
	v_mfma_f32_16x16x32_bf16 v[68:71], v[174:177], v[212:215], v[68:71]
	s_barrier
	s_setprio 0
	s_mov_b32 m0, s84
	v_lshl_add_u64 v[140:141], s[52:53], 0, v[136:137]
	ds_read_b128 v[178:181], v144 offset:16384
	ds_read_b128 v[182:185], v144 offset:17408
	ds_read_b128 v[186:189], v144 offset:18432
	ds_read_b128 v[190:193], v144 offset:19456
	ds_read_b128 v[200:203], v144 offset:20480
	ds_read_b128 v[204:207], v144 offset:21504
	ds_read_b128 v[208:211], v144 offset:22528
	ds_read_b128 v[212:215], v144 offset:23552
	global_load_lds_dwordx4 v[140:141], off
	v_lshl_add_u64 v[194:195], s[52:53], 0, v[132:133]
	s_mov_b32 m0, s6
	v_lshl_add_u64 v[198:199], s[30:31], 0, v[136:137]
	global_load_lds_dwordx4 v[194:195], off
	s_mov_b32 m0, s49
	v_lshl_add_u64 v[216:217], s[68:69], 0, v[134:135]
	global_load_lds_dwordx4 v[198:199], off
	v_lshl_add_u64 v[198:199], s[30:31], 0, v[132:133]
	s_mov_b32 m0, s81
	s_nop 0
	global_load_lds_dwordx4 v[198:199], off
	v_lshl_add_u64 v[198:199], s[68:69], 0, v[138:139]
	s_mov_b32 m0, s46
	s_nop 0
	global_load_lds_dwordx4 v[198:199], off
	s_mov_b32 m0, s47
	s_nop 0
	global_load_lds_dwordx4 v[216:217], off
	s_setprio 1
	s_waitcnt vmcnt(8) lgkmcnt(0)
	s_barrier
	v_mfma_f32_16x16x32_bf16 v[64:67], v[146:149], v[178:181], v[64:67]
	v_mfma_f32_16x16x32_bf16 v[60:63], v[154:157], v[178:181], v[60:63]
	v_mfma_f32_16x16x32_bf16 v[56:59], v[146:149], v[186:189], v[56:59]
	v_mfma_f32_16x16x32_bf16 v[48:51], v[154:157], v[186:189], v[48:51]
	v_mfma_f32_16x16x32_bf16 v[40:43], v[146:149], v[200:203], v[40:43]
	v_mfma_f32_16x16x32_bf16 v[32:35], v[154:157], v[200:203], v[32:35]
	v_mfma_f32_16x16x32_bf16 v[24:27], v[146:149], v[208:211], v[24:27]
	v_mfma_f32_16x16x32_bf16 v[16:19], v[154:157], v[208:211], v[16:19]
	v_mfma_f32_16x16x32_bf16 v[64:67], v[150:153], v[182:185], v[64:67]
	v_mfma_f32_16x16x32_bf16 v[60:63], v[158:161], v[182:185], v[60:63]
	v_mfma_f32_16x16x32_bf16 v[56:59], v[150:153], v[190:193], v[56:59]
	v_mfma_f32_16x16x32_bf16 v[48:51], v[158:161], v[190:193], v[48:51]
	v_mfma_f32_16x16x32_bf16 v[40:43], v[150:153], v[204:207], v[40:43]
	v_mfma_f32_16x16x32_bf16 v[32:35], v[158:161], v[204:207], v[32:35]
	v_mfma_f32_16x16x32_bf16 v[24:27], v[150:153], v[212:215], v[24:27]
	v_mfma_f32_16x16x32_bf16 v[16:19], v[158:161], v[212:215], v[16:19]
	s_setprio 0
	s_setprio 1
	v_mfma_f32_16x16x32_bf16 v[52:55], v[162:165], v[178:181], v[52:55]
	v_mfma_f32_16x16x32_bf16 v[44:47], v[170:173], v[178:181], v[44:47]
	v_mfma_f32_16x16x32_bf16 v[36:39], v[162:165], v[186:189], v[36:39]
	v_mfma_f32_16x16x32_bf16 v[28:31], v[170:173], v[186:189], v[28:31]
	v_mfma_f32_16x16x32_bf16 v[20:23], v[162:165], v[200:203], v[20:23]
	v_mfma_f32_16x16x32_bf16 v[12:15], v[170:173], v[200:203], v[12:15]
	v_mfma_f32_16x16x32_bf16 v[8:11], v[162:165], v[208:211], v[8:11]
	v_mfma_f32_16x16x32_bf16 v[4:7], v[170:173], v[208:211], v[4:7]
	v_mfma_f32_16x16x32_bf16 v[52:55], v[166:169], v[182:185], v[52:55]
	v_mfma_f32_16x16x32_bf16 v[44:47], v[174:177], v[182:185], v[44:47]
	v_mfma_f32_16x16x32_bf16 v[36:39], v[166:169], v[190:193], v[36:39]
	v_mfma_f32_16x16x32_bf16 v[28:31], v[174:177], v[190:193], v[28:31]
	v_mfma_f32_16x16x32_bf16 v[20:23], v[166:169], v[204:207], v[20:23]
	v_mfma_f32_16x16x32_bf16 v[12:15], v[174:177], v[204:207], v[12:15]
	v_mfma_f32_16x16x32_bf16 v[8:11], v[166:169], v[212:215], v[8:11]
	v_mfma_f32_16x16x32_bf16 v[4:7], v[174:177], v[212:215], v[4:7]
	s_barrier
	s_setprio 0
	v_add_u32_e32 v145, s54, v142
	ds_read_b128 v[146:149], v145
	ds_read_b128 v[150:153], v145 offset:1024
	ds_read_b128 v[154:157], v145 offset:2048
	ds_read_b128 v[158:161], v145 offset:3072
	v_add_u32_e32 v145, s73, v142
	ds_read_b128 v[162:165], v145
	ds_read_b128 v[166:169], v145 offset:1024
	ds_read_b128 v[170:173], v145 offset:2048
	ds_read_b128 v[174:177], v145 offset:3072
	s_mov_b32 m0, s50
	v_lshl_add_u64 v[218:219], s[38:39], 0, v[138:139]
	ds_read_b128 v[178:181], v144 offset:32768
	ds_read_b128 v[182:185], v144 offset:33792
	ds_read_b128 v[186:189], v144 offset:34816
	ds_read_b128 v[190:193], v144 offset:35840
	ds_read_b128 v[200:203], v144 offset:36864
	ds_read_b128 v[204:207], v144 offset:37888
	ds_read_b128 v[208:211], v144 offset:38912
	ds_read_b128 v[212:215], v144 offset:39936
	global_load_lds_dwordx4 v[218:219], off
	v_lshl_add_u64 v[218:219], s[38:39], 0, v[134:135]
	s_mov_b32 m0, s51
	s_nop 0
	global_load_lds_dwordx4 v[218:219], off
	s_setprio 1
	s_waitcnt vmcnt(8) lgkmcnt(0)
	s_barrier
	v_mfma_f32_16x16x32_bf16 v[128:131], v[146:149], v[178:181], v[128:131]
	v_mfma_f32_16x16x32_bf16 v[124:127], v[154:157], v[178:181], v[124:127]
	v_mfma_f32_16x16x32_bf16 v[120:123], v[146:149], v[186:189], v[120:123]
	v_mfma_f32_16x16x32_bf16 v[112:115], v[154:157], v[186:189], v[112:115]
	v_mfma_f32_16x16x32_bf16 v[104:107], v[146:149], v[200:203], v[104:107]
	v_mfma_f32_16x16x32_bf16 v[96:99], v[154:157], v[200:203], v[96:99]
	v_mfma_f32_16x16x32_bf16 v[88:91], v[146:149], v[208:211], v[88:91]
	v_mfma_f32_16x16x32_bf16 v[80:83], v[154:157], v[208:211], v[80:83]
	v_mfma_f32_16x16x32_bf16 v[128:131], v[150:153], v[182:185], v[128:131]
	v_mfma_f32_16x16x32_bf16 v[124:127], v[158:161], v[182:185], v[124:127]
	v_mfma_f32_16x16x32_bf16 v[120:123], v[150:153], v[190:193], v[120:123]
	v_mfma_f32_16x16x32_bf16 v[112:115], v[158:161], v[190:193], v[112:115]
	v_mfma_f32_16x16x32_bf16 v[104:107], v[150:153], v[204:207], v[104:107]
	v_mfma_f32_16x16x32_bf16 v[96:99], v[158:161], v[204:207], v[96:99]
	v_mfma_f32_16x16x32_bf16 v[88:91], v[150:153], v[212:215], v[88:91]
	v_mfma_f32_16x16x32_bf16 v[80:83], v[158:161], v[212:215], v[80:83]
	s_setprio 0
	s_setprio 1
	v_mfma_f32_16x16x32_bf16 v[116:119], v[162:165], v[178:181], v[116:119]
	v_mfma_f32_16x16x32_bf16 v[108:111], v[170:173], v[178:181], v[108:111]
	v_mfma_f32_16x16x32_bf16 v[100:103], v[162:165], v[186:189], v[100:103]
	v_mfma_f32_16x16x32_bf16 v[92:95], v[170:173], v[186:189], v[92:95]
	v_mfma_f32_16x16x32_bf16 v[84:87], v[162:165], v[200:203], v[84:87]
	v_mfma_f32_16x16x32_bf16 v[76:79], v[170:173], v[200:203], v[76:79]
	v_mfma_f32_16x16x32_bf16 v[72:75], v[162:165], v[208:211], v[72:75]
	v_mfma_f32_16x16x32_bf16 v[68:71], v[170:173], v[208:211], v[68:71]
	v_mfma_f32_16x16x32_bf16 v[116:119], v[166:169], v[182:185], v[116:119]
	v_mfma_f32_16x16x32_bf16 v[108:111], v[174:177], v[182:185], v[108:111]
	v_mfma_f32_16x16x32_bf16 v[100:103], v[166:169], v[190:193], v[100:103]
	v_mfma_f32_16x16x32_bf16 v[92:95], v[174:177], v[190:193], v[92:95]
	v_mfma_f32_16x16x32_bf16 v[84:87], v[166:169], v[204:207], v[84:87]
	v_mfma_f32_16x16x32_bf16 v[76:79], v[174:177], v[204:207], v[76:79]
	v_mfma_f32_16x16x32_bf16 v[72:75], v[166:169], v[212:215], v[72:75]
	v_mfma_f32_16x16x32_bf16 v[68:71], v[174:177], v[212:215], v[68:71]
	s_barrier
	s_setprio 0
	s_mov_b32 m0, s0
	v_lshl_add_u64 v[140:141], v[140:141], 0, s[90:91]
	ds_read_b128 v[178:181], v144 offset:49152
	ds_read_b128 v[182:185], v144 offset:50176
	ds_read_b128 v[186:189], v144 offset:51200
	ds_read_b128 v[190:193], v144 offset:52224
	ds_read_b128 v[200:203], v144 offset:53248
	ds_read_b128 v[204:207], v144 offset:54272
	ds_read_b128 v[208:211], v144 offset:55296
	ds_read_b128 v[212:215], v144 offset:56320
	global_load_lds_dwordx4 v[140:141], off
	v_lshl_add_u64 v[140:141], v[194:195], 0, s[90:91]
	s_mov_b32 m0, s80
	s_nop 0
	global_load_lds_dwordx4 v[140:141], off
	v_lshl_add_u64 v[140:141], s[36:37], 0, v[136:137]
	s_mov_b32 m0, s83
	s_nop 0
	global_load_lds_dwordx4 v[140:141], off
	v_lshl_add_u64 v[140:141], s[36:37], 0, v[132:133]
	s_mov_b32 m0, s82
	s_nop 0
	global_load_lds_dwordx4 v[140:141], off
	v_lshl_add_u64 v[140:141], v[198:199], 0, s[90:91]
	s_mov_b32 m0, s61
	s_nop 0
	global_load_lds_dwordx4 v[140:141], off
	v_lshl_add_u64 v[140:141], v[216:217], 0, s[90:91]
	s_mov_b32 m0, s74
	s_nop 0
	global_load_lds_dwordx4 v[140:141], off
	s_setprio 1
	s_waitcnt vmcnt(8) lgkmcnt(0)
	s_barrier
	v_mfma_f32_16x16x32_bf16 v[64:67], v[146:149], v[178:181], v[64:67]
	v_mfma_f32_16x16x32_bf16 v[60:63], v[154:157], v[178:181], v[60:63]
	v_mfma_f32_16x16x32_bf16 v[56:59], v[146:149], v[186:189], v[56:59]
	v_mfma_f32_16x16x32_bf16 v[48:51], v[154:157], v[186:189], v[48:51]
	v_mfma_f32_16x16x32_bf16 v[40:43], v[146:149], v[200:203], v[40:43]
	v_mfma_f32_16x16x32_bf16 v[32:35], v[154:157], v[200:203], v[32:35]
	v_mfma_f32_16x16x32_bf16 v[24:27], v[146:149], v[208:211], v[24:27]
	v_mfma_f32_16x16x32_bf16 v[16:19], v[154:157], v[208:211], v[16:19]
	v_mfma_f32_16x16x32_bf16 v[64:67], v[150:153], v[182:185], v[64:67]
	v_mfma_f32_16x16x32_bf16 v[60:63], v[158:161], v[182:185], v[60:63]
	v_mfma_f32_16x16x32_bf16 v[56:59], v[150:153], v[190:193], v[56:59]
	v_mfma_f32_16x16x32_bf16 v[48:51], v[158:161], v[190:193], v[48:51]
	v_mfma_f32_16x16x32_bf16 v[40:43], v[150:153], v[204:207], v[40:43]
	v_mfma_f32_16x16x32_bf16 v[32:35], v[158:161], v[204:207], v[32:35]
	v_mfma_f32_16x16x32_bf16 v[24:27], v[150:153], v[212:215], v[24:27]
	v_mfma_f32_16x16x32_bf16 v[16:19], v[158:161], v[212:215], v[16:19]
	s_setprio 0
	s_setprio 1
	v_mfma_f32_16x16x32_bf16 v[52:55], v[162:165], v[178:181], v[52:55]
	v_mfma_f32_16x16x32_bf16 v[44:47], v[170:173], v[178:181], v[44:47]
	v_mfma_f32_16x16x32_bf16 v[36:39], v[162:165], v[186:189], v[36:39]
	v_mfma_f32_16x16x32_bf16 v[28:31], v[170:173], v[186:189], v[28:31]
	v_mfma_f32_16x16x32_bf16 v[20:23], v[162:165], v[200:203], v[20:23]
	v_mfma_f32_16x16x32_bf16 v[12:15], v[170:173], v[200:203], v[12:15]
	v_mfma_f32_16x16x32_bf16 v[8:11], v[162:165], v[208:211], v[8:11]
	v_mfma_f32_16x16x32_bf16 v[4:7], v[170:173], v[208:211], v[4:7]
	v_mfma_f32_16x16x32_bf16 v[52:55], v[166:169], v[182:185], v[52:55]
	v_mfma_f32_16x16x32_bf16 v[44:47], v[174:177], v[182:185], v[44:47]
	v_mfma_f32_16x16x32_bf16 v[36:39], v[166:169], v[190:193], v[36:39]
	v_mfma_f32_16x16x32_bf16 v[28:31], v[174:177], v[190:193], v[28:31]
	v_mfma_f32_16x16x32_bf16 v[20:23], v[166:169], v[204:207], v[20:23]
	v_mfma_f32_16x16x32_bf16 v[12:15], v[174:177], v[204:207], v[12:15]
	v_mfma_f32_16x16x32_bf16 v[8:11], v[166:169], v[212:215], v[8:11]
	v_mfma_f32_16x16x32_bf16 v[4:7], v[174:177], v[212:215], v[4:7]
	s_barrier
	s_setprio 0
	s_movk_i32 s30, 0x100
	s_andn2_b64 vcc, exec, s[66:67]
	s_mov_b64 s[36:37], -1
	s_mov_b64 s[66:67], 0
	s_cbranch_vccz .LBB0_1186
	s_and_b64 vcc, exec, s[20:21]
	s_cbranch_vccz .LBB0_1189
	s_barrier

.LBB0_1273:
	s_add_i32 s74, s30, 2
	s_add_u32 s62, s36, 0x100
	s_addc_u32 s63, s37, 0
	s_add_i32 s0, 0, 0x10000
	s_cmp_eq_u32 s29, s30
	s_cselect_b32 s35, s43, s63
	s_cselect_b32 s34, s42, s62
	s_cselect_b32 s31, s45, s72
	s_cselect_b32 s30, s44, s69
	s_add_i32 s6, 0, 0x14000
	v_add_u32_e32 v144, s0, v3
	v_add_u32_e32 v160, s6, v3
	ds_read_b128 v[124:127], v144
	ds_read_b128 v[128:131], v144 offset:1024
	ds_read_b128 v[140:143], v144 offset:2048
	ds_read_b128 v[144:147], v144 offset:3072
	ds_read_b128 v[148:151], v160
	ds_read_b128 v[152:155], v160 offset:1024
	ds_read_b128 v[156:159], v160 offset:2048
	ds_read_b128 v[160:163], v160 offset:3072
	v_lshl_add_u64 v[198:199], s[36:37], 0, v[212:213]
	s_add_i32 m0, s33, 0xc000
	ds_read_b128 v[164:167], v250
	ds_read_b128 v[168:171], v250 offset:1024
	ds_read_b128 v[172:175], v250 offset:2048
	ds_read_b128 v[176:179], v250 offset:3072
	ds_read_b128 v[180:183], v250 offset:4096
	ds_read_b128 v[184:187], v250 offset:5120
	ds_read_b128 v[188:191], v250 offset:6144
	ds_read_b128 v[192:195], v250 offset:7168
	global_load_lds_dwordx4 v[198:199], off
	v_lshl_add_u64 v[198:199], s[36:37], 0, v[214:215]
	s_add_i32 m0, s33, 0xe000
	s_nop 0
	global_load_lds_dwordx4 v[198:199], off
	s_setprio 1
	s_waitcnt vmcnt(8) lgkmcnt(0)
	s_barrier
	v_mfma_f32_16x16x32_bf16 v[136:139], v[124:127], v[164:167], v[136:139]
	v_mfma_f32_16x16x32_bf16 v[132:135], v[140:143], v[164:167], v[132:135]
	v_mfma_f32_16x16x32_bf16 v[112:115], v[124:127], v[172:175], v[112:115]
	v_mfma_f32_16x16x32_bf16 v[108:111], v[140:143], v[172:175], v[108:111]
	v_mfma_f32_16x16x32_bf16 v[96:99], v[124:127], v[180:183], v[96:99]
	v_mfma_f32_16x16x32_bf16 v[92:95], v[140:143], v[180:183], v[92:95]
	v_mfma_f32_16x16x32_bf16 v[80:83], v[124:127], v[188:191], v[80:83]
	v_mfma_f32_16x16x32_bf16 v[76:79], v[140:143], v[188:191], v[76:79]
	v_mfma_f32_16x16x32_bf16 v[136:139], v[128:131], v[168:171], v[136:139]
	v_mfma_f32_16x16x32_bf16 v[132:135], v[144:147], v[168:171], v[132:135]
	v_mfma_f32_16x16x32_bf16 v[112:115], v[128:131], v[176:179], v[112:115]
	v_mfma_f32_16x16x32_bf16 v[108:111], v[144:147], v[176:179], v[108:111]
	v_mfma_f32_16x16x32_bf16 v[96:99], v[128:131], v[184:187], v[96:99]
	v_mfma_f32_16x16x32_bf16 v[92:95], v[144:147], v[184:187], v[92:95]
	v_mfma_f32_16x16x32_bf16 v[80:83], v[128:131], v[192:195], v[80:83]
	v_mfma_f32_16x16x32_bf16 v[76:79], v[144:147], v[192:195], v[76:79]
	s_setprio 0
	s_setprio 1
	v_mfma_f32_16x16x32_bf16 v[120:123], v[148:151], v[164:167], v[120:123]
	v_mfma_f32_16x16x32_bf16 v[116:119], v[156:159], v[164:167], v[116:119]
	v_mfma_f32_16x16x32_bf16 v[104:107], v[148:151], v[172:175], v[104:107]
	v_mfma_f32_16x16x32_bf16 v[100:103], v[156:159], v[172:175], v[100:103]
	v_mfma_f32_16x16x32_bf16 v[88:91], v[148:151], v[180:183], v[88:91]
	v_mfma_f32_16x16x32_bf16 v[84:87], v[156:159], v[180:183], v[84:87]
	v_mfma_f32_16x16x32_bf16 v[72:75], v[148:151], v[188:191], v[72:75]
	v_mfma_f32_16x16x32_bf16 v[68:71], v[156:159], v[188:191], v[68:71]
	v_mfma_f32_16x16x32_bf16 v[120:123], v[152:155], v[168:171], v[120:123]
	v_mfma_f32_16x16x32_bf16 v[116:119], v[160:163], v[168:171], v[116:119]
	v_mfma_f32_16x16x32_bf16 v[104:107], v[152:155], v[176:179], v[104:107]
	v_mfma_f32_16x16x32_bf16 v[100:103], v[160:163], v[176:179], v[100:103]
	v_mfma_f32_16x16x32_bf16 v[88:91], v[152:155], v[184:187], v[88:91]
	v_mfma_f32_16x16x32_bf16 v[84:87], v[160:163], v[184:187], v[84:87]
	v_mfma_f32_16x16x32_bf16 v[72:75], v[152:155], v[192:195], v[72:75]
	v_mfma_f32_16x16x32_bf16 v[68:71], v[160:163], v[192:195], v[68:71]
	s_barrier
	s_setprio 0
	s_add_i32 s0, s0, s27
	v_lshl_add_u64 v[198:199], s[30:31], 0, v[202:203]
	s_mov_b32 m0, s0
	ds_read_b128 v[164:167], v250 offset:16384
	ds_read_b128 v[168:171], v250 offset:17408
	ds_read_b128 v[172:175], v250 offset:18432
	ds_read_b128 v[176:179], v250 offset:19456
	ds_read_b128 v[180:183], v250 offset:20480
	ds_read_b128 v[184:187], v250 offset:21504
	ds_read_b128 v[188:191], v250 offset:22528
	ds_read_b128 v[192:195], v250 offset:23552
	global_load_lds_dwordx4 v[198:199], off
	s_add_i32 m0, s0, 0x2000
	s_add_u32 s36, s30, 0x204000
	v_lshl_add_u64 v[216:217], s[30:31], 0, v[206:207]
	s_addc_u32 s37, s31, 0
	s_add_i32 s0, s6, s27
	global_load_lds_dwordx4 v[216:217], off
	v_lshl_add_u64 v[218:219], s[36:37], 0, v[202:203]
	s_mov_b32 m0, s0
	v_lshl_add_u64 v[220:221], s[34:35], 0, v[204:205]
	global_load_lds_dwordx4 v[218:219], off
	v_lshl_add_u64 v[218:219], s[36:37], 0, v[206:207]
	s_add_i32 m0, s0, 0x2000
	s_nop 0
	global_load_lds_dwordx4 v[218:219], off
	v_lshl_add_u64 v[218:219], s[34:35], 0, v[200:201]
	s_mov_b32 m0, s33
	s_nop 0
	global_load_lds_dwordx4 v[218:219], off
	s_mov_b32 m0, s38
	s_nop 0
	global_load_lds_dwordx4 v[220:221], off
	s_setprio 1
	s_waitcnt vmcnt(8) lgkmcnt(0)
	s_barrier
	v_mfma_f32_16x16x32_bf16 v[64:67], v[124:127], v[164:167], v[64:67]
	v_mfma_f32_16x16x32_bf16 v[60:63], v[140:143], v[164:167], v[60:63]
	v_mfma_f32_16x16x32_bf16 v[48:51], v[124:127], v[172:175], v[48:51]
	v_mfma_f32_16x16x32_bf16 v[44:47], v[140:143], v[172:175], v[44:47]
	v_mfma_f32_16x16x32_bf16 v[32:35], v[124:127], v[180:183], v[32:35]
	v_mfma_f32_16x16x32_bf16 v[28:31], v[140:143], v[180:183], v[28:31]
	v_mfma_f32_16x16x32_bf16 v[16:19], v[124:127], v[188:191], v[16:19]
	v_mfma_f32_16x16x32_bf16 v[12:15], v[140:143], v[188:191], v[12:15]
	v_mfma_f32_16x16x32_bf16 v[64:67], v[128:131], v[168:171], v[64:67]
	v_mfma_f32_16x16x32_bf16 v[60:63], v[144:147], v[168:171], v[60:63]
	v_mfma_f32_16x16x32_bf16 v[48:51], v[128:131], v[176:179], v[48:51]
	v_mfma_f32_16x16x32_bf16 v[44:47], v[144:147], v[176:179], v[44:47]
	v_mfma_f32_16x16x32_bf16 v[32:35], v[128:131], v[184:187], v[32:35]
	v_mfma_f32_16x16x32_bf16 v[28:31], v[144:147], v[184:187], v[28:31]
	v_mfma_f32_16x16x32_bf16 v[16:19], v[128:131], v[192:195], v[16:19]
	v_mfma_f32_16x16x32_bf16 v[12:15], v[144:147], v[192:195], v[12:15]
	s_setprio 0
	s_setprio 1
	v_mfma_f32_16x16x32_bf16 v[56:59], v[148:151], v[164:167], v[56:59]
	v_mfma_f32_16x16x32_bf16 v[52:55], v[156:159], v[164:167], v[52:55]
	v_mfma_f32_16x16x32_bf16 v[40:43], v[148:151], v[172:175], v[40:43]
	v_mfma_f32_16x16x32_bf16 v[36:39], v[156:159], v[172:175], v[36:39]
	v_mfma_f32_16x16x32_bf16 v[24:27], v[148:151], v[180:183], v[24:27]
	v_mfma_f32_16x16x32_bf16 v[20:23], v[156:159], v[180:183], v[20:23]
	v_mfma_f32_16x16x32_bf16 v[8:11], v[148:151], v[188:191], v[8:11]
	v_mfma_f32_16x16x32_bf16 v[4:7], v[156:159], v[188:191], v[4:7]
	v_mfma_f32_16x16x32_bf16 v[56:59], v[152:155], v[168:171], v[56:59]
	v_mfma_f32_16x16x32_bf16 v[52:55], v[160:163], v[168:171], v[52:55]
	v_mfma_f32_16x16x32_bf16 v[40:43], v[152:155], v[176:179], v[40:43]
	v_mfma_f32_16x16x32_bf16 v[36:39], v[160:163], v[176:179], v[36:39]
	v_mfma_f32_16x16x32_bf16 v[24:27], v[152:155], v[184:187], v[24:27]
	v_mfma_f32_16x16x32_bf16 v[20:23], v[160:163], v[184:187], v[20:23]
	v_mfma_f32_16x16x32_bf16 v[8:11], v[152:155], v[192:195], v[8:11]
	v_mfma_f32_16x16x32_bf16 v[4:7], v[160:163], v[192:195], v[4:7]
	s_barrier
	s_setprio 0
	s_add_i32 s0, 0, 0x18000
	s_add_i32 s6, 0, 0x1c000
	v_add_u32_e32 v144, s0, v3
	v_add_u32_e32 v160, s6, v3
	ds_read_b128 v[124:127], v144
	ds_read_b128 v[128:131], v144 offset:1024
	ds_read_b128 v[140:143], v144 offset:2048
	ds_read_b128 v[144:147], v144 offset:3072
	ds_read_b128 v[148:151], v160
	ds_read_b128 v[152:155], v160 offset:1024
	ds_read_b128 v[156:159], v160 offset:2048
	ds_read_b128 v[160:163], v160 offset:3072
	s_add_u32 s34, s34, 0x204000
	s_addc_u32 s35, s35, 0
	s_mov_b32 m0, s39
	v_lshl_add_u64 v[222:223], s[34:35], 0, v[200:201]
	ds_read_b128 v[164:167], v250 offset:32768
	ds_read_b128 v[168:171], v250 offset:33792
	ds_read_b128 v[172:175], v250 offset:34816
	ds_read_b128 v[176:179], v250 offset:35840
	ds_read_b128 v[180:183], v250 offset:36864
	ds_read_b128 v[184:187], v250 offset:37888
	ds_read_b128 v[188:191], v250 offset:38912
	ds_read_b128 v[192:195], v250 offset:39936
	global_load_lds_dwordx4 v[222:223], off
	v_lshl_add_u64 v[222:223], s[34:35], 0, v[204:205]
	s_mov_b32 m0, s40
	s_nop 0
	global_load_lds_dwordx4 v[222:223], off
	s_setprio 1
	s_waitcnt vmcnt(8) lgkmcnt(0)
	s_barrier
	v_mfma_f32_16x16x32_bf16 v[136:139], v[124:127], v[164:167], v[136:139]
	v_mfma_f32_16x16x32_bf16 v[132:135], v[140:143], v[164:167], v[132:135]
	v_mfma_f32_16x16x32_bf16 v[112:115], v[124:127], v[172:175], v[112:115]
	v_mfma_f32_16x16x32_bf16 v[108:111], v[140:143], v[172:175], v[108:111]
	v_mfma_f32_16x16x32_bf16 v[96:99], v[124:127], v[180:183], v[96:99]
	v_mfma_f32_16x16x32_bf16 v[92:95], v[140:143], v[180:183], v[92:95]
	v_mfma_f32_16x16x32_bf16 v[80:83], v[124:127], v[188:191], v[80:83]
	v_mfma_f32_16x16x32_bf16 v[76:79], v[140:143], v[188:191], v[76:79]
	v_mfma_f32_16x16x32_bf16 v[136:139], v[128:131], v[168:171], v[136:139]
	v_mfma_f32_16x16x32_bf16 v[132:135], v[144:147], v[168:171], v[132:135]
	v_mfma_f32_16x16x32_bf16 v[112:115], v[128:131], v[176:179], v[112:115]
	v_mfma_f32_16x16x32_bf16 v[108:111], v[144:147], v[176:179], v[108:111]
	v_mfma_f32_16x16x32_bf16 v[96:99], v[128:131], v[184:187], v[96:99]
	v_mfma_f32_16x16x32_bf16 v[92:95], v[144:147], v[184:187], v[92:95]
	v_mfma_f32_16x16x32_bf16 v[80:83], v[128:131], v[192:195], v[80:83]
	v_mfma_f32_16x16x32_bf16 v[76:79], v[144:147], v[192:195], v[76:79]
	s_setprio 0
	s_setprio 1
	v_mfma_f32_16x16x32_bf16 v[120:123], v[148:151], v[164:167], v[120:123]
	v_mfma_f32_16x16x32_bf16 v[116:119], v[156:159], v[164:167], v[116:119]
	v_mfma_f32_16x16x32_bf16 v[104:107], v[148:151], v[172:175], v[104:107]
	v_mfma_f32_16x16x32_bf16 v[100:103], v[156:159], v[172:175], v[100:103]
	v_mfma_f32_16x16x32_bf16 v[88:91], v[148:151], v[180:183], v[88:91]
	v_mfma_f32_16x16x32_bf16 v[84:87], v[156:159], v[180:183], v[84:87]
	v_mfma_f32_16x16x32_bf16 v[72:75], v[148:151], v[188:191], v[72:75]
	v_mfma_f32_16x16x32_bf16 v[68:71], v[156:159], v[188:191], v[68:71]
	v_mfma_f32_16x16x32_bf16 v[120:123], v[152:155], v[168:171], v[120:123]
	v_mfma_f32_16x16x32_bf16 v[116:119], v[160:163], v[168:171], v[116:119]
	v_mfma_f32_16x16x32_bf16 v[104:107], v[152:155], v[176:179], v[104:107]
	v_mfma_f32_16x16x32_bf16 v[100:103], v[160:163], v[176:179], v[100:103]
	v_mfma_f32_16x16x32_bf16 v[88:91], v[152:155], v[184:187], v[88:91]
	v_mfma_f32_16x16x32_bf16 v[84:87], v[160:163], v[184:187], v[84:87]
	v_mfma_f32_16x16x32_bf16 v[72:75], v[152:155], v[192:195], v[72:75]
	v_mfma_f32_16x16x32_bf16 v[68:71], v[160:163], v[192:195], v[68:71]
	s_barrier
	s_setprio 0
	s_add_i32 s0, s0, s27
	v_lshl_add_u64 v[198:199], v[198:199], 0, s[90:91]
	s_mov_b32 m0, s0
	ds_read_b128 v[164:167], v250 offset:49152
	ds_read_b128 v[168:171], v250 offset:50176
	ds_read_b128 v[172:175], v250 offset:51200
	ds_read_b128 v[176:179], v250 offset:52224
	ds_read_b128 v[180:183], v250 offset:53248
	ds_read_b128 v[184:187], v250 offset:54272
	ds_read_b128 v[188:191], v250 offset:55296
	ds_read_b128 v[192:195], v250 offset:56320
	global_load_lds_dwordx4 v[198:199], off
	s_add_i32 m0, s0, 0x2000
	s_add_u32 s30, s30, 0x204080
	v_lshl_add_u64 v[198:199], v[216:217], 0, s[90:91]
	s_addc_u32 s31, s31, 0
	s_add_i32 s0, s6, s27
	global_load_lds_dwordx4 v[198:199], off
	v_lshl_add_u64 v[198:199], s[30:31], 0, v[202:203]
	s_mov_b32 m0, s0
	s_nop 0
	global_load_lds_dwordx4 v[198:199], off
	v_lshl_add_u64 v[198:199], s[30:31], 0, v[206:207]
	s_add_i32 m0, s0, 0x2000
	s_nop 0
	global_load_lds_dwordx4 v[198:199], off
	v_lshl_add_u64 v[198:199], v[218:219], 0, s[90:91]
	s_mov_b32 m0, s50
	s_nop 0
	global_load_lds_dwordx4 v[198:199], off
	v_lshl_add_u64 v[198:199], v[220:221], 0, s[90:91]
	s_mov_b32 m0, s51
	s_nop 0
	global_load_lds_dwordx4 v[198:199], off
	s_setprio 1
	s_waitcnt vmcnt(8) lgkmcnt(0)
	s_barrier
	v_mfma_f32_16x16x32_bf16 v[64:67], v[124:127], v[164:167], v[64:67]
	v_mfma_f32_16x16x32_bf16 v[60:63], v[140:143], v[164:167], v[60:63]
	v_mfma_f32_16x16x32_bf16 v[48:51], v[124:127], v[172:175], v[48:51]
	v_mfma_f32_16x16x32_bf16 v[44:47], v[140:143], v[172:175], v[44:47]
	v_mfma_f32_16x16x32_bf16 v[32:35], v[124:127], v[180:183], v[32:35]
	v_mfma_f32_16x16x32_bf16 v[28:31], v[140:143], v[180:183], v[28:31]
	v_mfma_f32_16x16x32_bf16 v[16:19], v[124:127], v[188:191], v[16:19]
	v_mfma_f32_16x16x32_bf16 v[12:15], v[140:143], v[188:191], v[12:15]
	v_mfma_f32_16x16x32_bf16 v[64:67], v[128:131], v[168:171], v[64:67]
	v_mfma_f32_16x16x32_bf16 v[60:63], v[144:147], v[168:171], v[60:63]
	v_mfma_f32_16x16x32_bf16 v[48:51], v[128:131], v[176:179], v[48:51]
	v_mfma_f32_16x16x32_bf16 v[44:47], v[144:147], v[176:179], v[44:47]
	v_mfma_f32_16x16x32_bf16 v[32:35], v[128:131], v[184:187], v[32:35]
	v_mfma_f32_16x16x32_bf16 v[28:31], v[144:147], v[184:187], v[28:31]
	v_mfma_f32_16x16x32_bf16 v[16:19], v[128:131], v[192:195], v[16:19]
	v_mfma_f32_16x16x32_bf16 v[12:15], v[144:147], v[192:195], v[12:15]
	s_setprio 0
	s_setprio 1
	v_mfma_f32_16x16x32_bf16 v[56:59], v[148:151], v[164:167], v[56:59]
	v_mfma_f32_16x16x32_bf16 v[52:55], v[156:159], v[164:167], v[52:55]
	v_mfma_f32_16x16x32_bf16 v[40:43], v[148:151], v[172:175], v[40:43]
	v_mfma_f32_16x16x32_bf16 v[36:39], v[156:159], v[172:175], v[36:39]
	v_mfma_f32_16x16x32_bf16 v[24:27], v[148:151], v[180:183], v[24:27]
	v_mfma_f32_16x16x32_bf16 v[20:23], v[156:159], v[180:183], v[20:23]
	v_mfma_f32_16x16x32_bf16 v[8:11], v[148:151], v[188:191], v[8:11]
	v_mfma_f32_16x16x32_bf16 v[4:7], v[156:159], v[188:191], v[4:7]
	v_mfma_f32_16x16x32_bf16 v[56:59], v[152:155], v[168:171], v[56:59]
	v_mfma_f32_16x16x32_bf16 v[52:55], v[160:163], v[168:171], v[52:55]
	v_mfma_f32_16x16x32_bf16 v[40:43], v[152:155], v[176:179], v[40:43]
	v_mfma_f32_16x16x32_bf16 v[36:39], v[160:163], v[176:179], v[36:39]
	v_mfma_f32_16x16x32_bf16 v[24:27], v[152:155], v[184:187], v[24:27]
	v_mfma_f32_16x16x32_bf16 v[20:23], v[160:163], v[184:187], v[20:23]
	v_mfma_f32_16x16x32_bf16 v[8:11], v[152:155], v[192:195], v[8:11]
	v_mfma_f32_16x16x32_bf16 v[4:7], v[160:163], v[192:195], v[4:7]
	s_barrier
	s_setprio 0
	s_add_u32 s69, s69, 0x100
	s_addc_u32 s72, s72, 0
	s_cmp_ge_i32 s74, s61
	s_mov_b64 s[36:37], s[62:63]
	s_mov_b32 s30, s74
	s_cbranch_scc0 .LBB0_1273
	s_and_b64 vcc, exec, s[22:23]
	s_cbranch_vccz .LBB0_1276
	s_barrier

.LBB0_1395:
	s_add_u32 s0, s36, 0xfff80080
	s_addc_u32 s6, s37, -1
	s_add_i32 s49, 0, 0x10000
	s_cmp_eq_u32 s67, 28
	s_cselect_b32 s35, s25, s6
	s_cselect_b32 s34, s33, s0
	s_cselect_b32 s31, s43, s39
	s_cselect_b32 s30, s45, s38
	s_add_i32 s0, 0, 0x14000
	v_add_u32_e32 v144, s49, v3
	v_add_u32_e32 v176, s0, v3
	ds_read_b128 v[132:135], v144
	ds_read_b128 v[136:139], v144 offset:1024
	ds_read_b128 v[140:143], v144 offset:2048
	ds_read_b128 v[144:147], v144 offset:3072
	ds_read_b128 v[164:167], v176
	ds_read_b128 v[168:171], v176 offset:1024
	ds_read_b128 v[172:175], v176 offset:2048
	ds_read_b128 v[176:179], v176 offset:3072
	v_lshl_add_u64 v[198:199], s[36:37], 0, v[160:161]
	s_add_i32 m0, s47, 0xc000
	ds_read_b128 v[180:183], v190
	ds_read_b128 v[184:187], v190 offset:1024
	ds_read_b128 v[192:195], v190 offset:2048
	ds_read_b128 v[200:203], v190 offset:3072
	ds_read_b128 v[204:207], v190 offset:4096
	ds_read_b128 v[208:211], v190 offset:5120
	ds_read_b128 v[212:215], v190 offset:6144
	ds_read_b128 v[216:219], v190 offset:7168
	global_load_lds_dwordx4 v[198:199], off
	v_lshl_add_u64 v[198:199], s[36:37], 0, v[162:163]
	s_add_i32 m0, s47, 0xe000
	s_nop 0
	global_load_lds_dwordx4 v[198:199], off
	s_setprio 1
	s_waitcnt vmcnt(8) lgkmcnt(0)
	s_barrier
	v_mfma_f32_16x16x32_bf16 v[128:131], v[132:135], v[180:183], v[128:131]
	v_mfma_f32_16x16x32_bf16 v[124:127], v[140:143], v[180:183], v[124:127]
	v_mfma_f32_16x16x32_bf16 v[112:115], v[132:135], v[192:195], v[112:115]
	v_mfma_f32_16x16x32_bf16 v[108:111], v[140:143], v[192:195], v[108:111]
	v_mfma_f32_16x16x32_bf16 v[96:99], v[132:135], v[204:207], v[96:99]
	v_mfma_f32_16x16x32_bf16 v[92:95], v[140:143], v[204:207], v[92:95]
	v_mfma_f32_16x16x32_bf16 v[80:83], v[132:135], v[212:215], v[80:83]
	v_mfma_f32_16x16x32_bf16 v[76:79], v[140:143], v[212:215], v[76:79]
	v_mfma_f32_16x16x32_bf16 v[128:131], v[136:139], v[184:187], v[128:131]
	v_mfma_f32_16x16x32_bf16 v[124:127], v[144:147], v[184:187], v[124:127]
	v_mfma_f32_16x16x32_bf16 v[112:115], v[136:139], v[200:203], v[112:115]
	v_mfma_f32_16x16x32_bf16 v[108:111], v[144:147], v[200:203], v[108:111]
	v_mfma_f32_16x16x32_bf16 v[96:99], v[136:139], v[208:211], v[96:99]
	v_mfma_f32_16x16x32_bf16 v[92:95], v[144:147], v[208:211], v[92:95]
	v_mfma_f32_16x16x32_bf16 v[80:83], v[136:139], v[216:219], v[80:83]
	v_mfma_f32_16x16x32_bf16 v[76:79], v[144:147], v[216:219], v[76:79]
	s_setprio 0
	s_setprio 1
	v_mfma_f32_16x16x32_bf16 v[120:123], v[164:167], v[180:183], v[120:123]
	v_mfma_f32_16x16x32_bf16 v[116:119], v[172:175], v[180:183], v[116:119]
	v_mfma_f32_16x16x32_bf16 v[104:107], v[164:167], v[192:195], v[104:107]
	v_mfma_f32_16x16x32_bf16 v[100:103], v[172:175], v[192:195], v[100:103]
	v_mfma_f32_16x16x32_bf16 v[88:91], v[164:167], v[204:207], v[88:91]
	v_mfma_f32_16x16x32_bf16 v[84:87], v[172:175], v[204:207], v[84:87]
	v_mfma_f32_16x16x32_bf16 v[72:75], v[164:167], v[212:215], v[72:75]
	v_mfma_f32_16x16x32_bf16 v[68:71], v[172:175], v[212:215], v[68:71]
	v_mfma_f32_16x16x32_bf16 v[120:123], v[168:171], v[184:187], v[120:123]
	v_mfma_f32_16x16x32_bf16 v[116:119], v[176:179], v[184:187], v[116:119]
	v_mfma_f32_16x16x32_bf16 v[104:107], v[168:171], v[200:203], v[104:107]
	v_mfma_f32_16x16x32_bf16 v[100:103], v[176:179], v[200:203], v[100:103]
	v_mfma_f32_16x16x32_bf16 v[88:91], v[168:171], v[208:211], v[88:91]
	v_mfma_f32_16x16x32_bf16 v[84:87], v[176:179], v[208:211], v[84:87]
	v_mfma_f32_16x16x32_bf16 v[72:75], v[168:171], v[216:219], v[72:75]
	v_mfma_f32_16x16x32_bf16 v[68:71], v[176:179], v[216:219], v[68:71]
	s_barrier
	s_setprio 0
	s_add_i32 s6, s49, s4
	v_lshl_add_u64 v[198:199], s[30:31], 0, v[152:153]
	s_mov_b32 m0, s6
	ds_read_b128 v[180:183], v190 offset:16384
	ds_read_b128 v[184:187], v190 offset:17408
	ds_read_b128 v[192:195], v190 offset:18432
	ds_read_b128 v[200:203], v190 offset:19456
	ds_read_b128 v[204:207], v190 offset:20480
	ds_read_b128 v[208:211], v190 offset:21504
	ds_read_b128 v[212:215], v190 offset:22528
	ds_read_b128 v[216:219], v190 offset:23552
	global_load_lds_dwordx4 v[198:199], off
	s_add_i32 m0, s6, 0x2000
	s_add_u32 s68, s30, 0x80000
	v_lshl_add_u64 v[220:221], s[30:31], 0, v[148:149]
	s_addc_u32 s69, s31, 0
	s_add_i32 s0, s0, s4
	global_load_lds_dwordx4 v[220:221], off
	v_lshl_add_u64 v[222:223], s[68:69], 0, v[152:153]
	s_mov_b32 m0, s0
	v_lshl_add_u64 v[224:225], s[34:35], 0, v[150:151]
	global_load_lds_dwordx4 v[222:223], off
	v_lshl_add_u64 v[222:223], s[68:69], 0, v[148:149]
	s_add_i32 m0, s0, 0x2000
	s_nop 0
	global_load_lds_dwordx4 v[222:223], off
	v_lshl_add_u64 v[222:223], s[34:35], 0, v[154:155]
	s_mov_b32 m0, s47
	s_nop 0
	global_load_lds_dwordx4 v[222:223], off
	s_mov_b32 m0, s52
	s_nop 0
	global_load_lds_dwordx4 v[224:225], off
	s_setprio 1
	s_waitcnt vmcnt(8) lgkmcnt(0)
	s_barrier
	v_mfma_f32_16x16x32_bf16 v[64:67], v[132:135], v[180:183], v[64:67]
	v_mfma_f32_16x16x32_bf16 v[60:63], v[140:143], v[180:183], v[60:63]
	v_mfma_f32_16x16x32_bf16 v[48:51], v[132:135], v[192:195], v[48:51]
	v_mfma_f32_16x16x32_bf16 v[44:47], v[140:143], v[192:195], v[44:47]
	v_mfma_f32_16x16x32_bf16 v[32:35], v[132:135], v[204:207], v[32:35]
	v_mfma_f32_16x16x32_bf16 v[28:31], v[140:143], v[204:207], v[28:31]
	v_mfma_f32_16x16x32_bf16 v[16:19], v[132:135], v[212:215], v[16:19]
	v_mfma_f32_16x16x32_bf16 v[12:15], v[140:143], v[212:215], v[12:15]
	v_mfma_f32_16x16x32_bf16 v[64:67], v[136:139], v[184:187], v[64:67]
	v_mfma_f32_16x16x32_bf16 v[60:63], v[144:147], v[184:187], v[60:63]
	v_mfma_f32_16x16x32_bf16 v[48:51], v[136:139], v[200:203], v[48:51]
	v_mfma_f32_16x16x32_bf16 v[44:47], v[144:147], v[200:203], v[44:47]
	v_mfma_f32_16x16x32_bf16 v[32:35], v[136:139], v[208:211], v[32:35]
	v_mfma_f32_16x16x32_bf16 v[28:31], v[144:147], v[208:211], v[28:31]
	v_mfma_f32_16x16x32_bf16 v[16:19], v[136:139], v[216:219], v[16:19]
	v_mfma_f32_16x16x32_bf16 v[12:15], v[144:147], v[216:219], v[12:15]
	s_setprio 0
	s_setprio 1
	v_mfma_f32_16x16x32_bf16 v[56:59], v[164:167], v[180:183], v[56:59]
	v_mfma_f32_16x16x32_bf16 v[52:55], v[172:175], v[180:183], v[52:55]
	v_mfma_f32_16x16x32_bf16 v[40:43], v[164:167], v[192:195], v[40:43]
	v_mfma_f32_16x16x32_bf16 v[36:39], v[172:175], v[192:195], v[36:39]
	v_mfma_f32_16x16x32_bf16 v[24:27], v[164:167], v[204:207], v[24:27]
	v_mfma_f32_16x16x32_bf16 v[20:23], v[172:175], v[204:207], v[20:23]
	v_mfma_f32_16x16x32_bf16 v[8:11], v[164:167], v[212:215], v[8:11]
	v_mfma_f32_16x16x32_bf16 v[4:7], v[172:175], v[212:215], v[4:7]
	v_mfma_f32_16x16x32_bf16 v[56:59], v[168:171], v[184:187], v[56:59]
	v_mfma_f32_16x16x32_bf16 v[52:55], v[176:179], v[184:187], v[52:55]
	v_mfma_f32_16x16x32_bf16 v[40:43], v[168:171], v[200:203], v[40:43]
	v_mfma_f32_16x16x32_bf16 v[36:39], v[176:179], v[200:203], v[36:39]
	v_mfma_f32_16x16x32_bf16 v[24:27], v[168:171], v[208:211], v[24:27]
	v_mfma_f32_16x16x32_bf16 v[20:23], v[176:179], v[208:211], v[20:23]
	v_mfma_f32_16x16x32_bf16 v[8:11], v[168:171], v[216:219], v[8:11]
	v_mfma_f32_16x16x32_bf16 v[4:7], v[176:179], v[216:219], v[4:7]
	s_barrier
	s_setprio 0
	s_add_i32 s0, 0, 0x18000
	s_add_i32 s6, 0, 0x1c000
	v_add_u32_e32 v144, s0, v3
	v_add_u32_e32 v176, s6, v3
	ds_read_b128 v[132:135], v144
	ds_read_b128 v[136:139], v144 offset:1024
	ds_read_b128 v[140:143], v144 offset:2048
	ds_read_b128 v[144:147], v144 offset:3072
	ds_read_b128 v[164:167], v176
	ds_read_b128 v[168:171], v176 offset:1024
	ds_read_b128 v[172:175], v176 offset:2048
	ds_read_b128 v[176:179], v176 offset:3072
	s_add_u32 s34, s34, 0x80000
	s_addc_u32 s35, s35, 0
	s_mov_b32 m0, s53
	v_lshl_add_u64 v[226:227], s[34:35], 0, v[154:155]
	ds_read_b128 v[180:183], v190 offset:32768
	ds_read_b128 v[184:187], v190 offset:33792
	ds_read_b128 v[192:195], v190 offset:34816
	ds_read_b128 v[200:203], v190 offset:35840
	ds_read_b128 v[204:207], v190 offset:36864
	ds_read_b128 v[208:211], v190 offset:37888
	ds_read_b128 v[212:215], v190 offset:38912
	ds_read_b128 v[216:219], v190 offset:39936
	global_load_lds_dwordx4 v[226:227], off
	v_lshl_add_u64 v[226:227], s[34:35], 0, v[150:151]
	s_mov_b32 m0, s59
	s_nop 0
	global_load_lds_dwordx4 v[226:227], off
	s_setprio 1
	s_waitcnt vmcnt(8) lgkmcnt(0)
	s_barrier
	v_mfma_f32_16x16x32_bf16 v[128:131], v[132:135], v[180:183], v[128:131]
	v_mfma_f32_16x16x32_bf16 v[124:127], v[140:143], v[180:183], v[124:127]
	v_mfma_f32_16x16x32_bf16 v[112:115], v[132:135], v[192:195], v[112:115]
	v_mfma_f32_16x16x32_bf16 v[108:111], v[140:143], v[192:195], v[108:111]
	v_mfma_f32_16x16x32_bf16 v[96:99], v[132:135], v[204:207], v[96:99]
	v_mfma_f32_16x16x32_bf16 v[92:95], v[140:143], v[204:207], v[92:95]
	v_mfma_f32_16x16x32_bf16 v[80:83], v[132:135], v[212:215], v[80:83]
	v_mfma_f32_16x16x32_bf16 v[76:79], v[140:143], v[212:215], v[76:79]
	v_mfma_f32_16x16x32_bf16 v[128:131], v[136:139], v[184:187], v[128:131]
	v_mfma_f32_16x16x32_bf16 v[124:127], v[144:147], v[184:187], v[124:127]
	v_mfma_f32_16x16x32_bf16 v[112:115], v[136:139], v[200:203], v[112:115]
	v_mfma_f32_16x16x32_bf16 v[108:111], v[144:147], v[200:203], v[108:111]
	v_mfma_f32_16x16x32_bf16 v[96:99], v[136:139], v[208:211], v[96:99]
	v_mfma_f32_16x16x32_bf16 v[92:95], v[144:147], v[208:211], v[92:95]
	v_mfma_f32_16x16x32_bf16 v[80:83], v[136:139], v[216:219], v[80:83]
	v_mfma_f32_16x16x32_bf16 v[76:79], v[144:147], v[216:219], v[76:79]
	s_setprio 0
	s_setprio 1
	v_mfma_f32_16x16x32_bf16 v[120:123], v[164:167], v[180:183], v[120:123]
	v_mfma_f32_16x16x32_bf16 v[116:119], v[172:175], v[180:183], v[116:119]
	v_mfma_f32_16x16x32_bf16 v[104:107], v[164:167], v[192:195], v[104:107]
	v_mfma_f32_16x16x32_bf16 v[100:103], v[172:175], v[192:195], v[100:103]
	v_mfma_f32_16x16x32_bf16 v[88:91], v[164:167], v[204:207], v[88:91]
	v_mfma_f32_16x16x32_bf16 v[84:87], v[172:175], v[204:207], v[84:87]
	v_mfma_f32_16x16x32_bf16 v[72:75], v[164:167], v[212:215], v[72:75]
	v_mfma_f32_16x16x32_bf16 v[68:71], v[172:175], v[212:215], v[68:71]
	v_mfma_f32_16x16x32_bf16 v[120:123], v[168:171], v[184:187], v[120:123]
	v_mfma_f32_16x16x32_bf16 v[116:119], v[176:179], v[184:187], v[116:119]
	v_mfma_f32_16x16x32_bf16 v[104:107], v[168:171], v[200:203], v[104:107]
	v_mfma_f32_16x16x32_bf16 v[100:103], v[176:179], v[200:203], v[100:103]
	v_mfma_f32_16x16x32_bf16 v[88:91], v[168:171], v[208:211], v[88:91]
	v_mfma_f32_16x16x32_bf16 v[84:87], v[176:179], v[208:211], v[84:87]
	v_mfma_f32_16x16x32_bf16 v[72:75], v[168:171], v[216:219], v[72:75]
	v_mfma_f32_16x16x32_bf16 v[68:71], v[176:179], v[216:219], v[68:71]
	s_barrier
	s_setprio 0
	s_add_i32 s0, s0, s4
	v_lshl_add_u64 v[198:199], v[198:199], 0, s[90:91]
	s_mov_b32 m0, s0
	ds_read_b128 v[180:183], v190 offset:49152
	ds_read_b128 v[184:187], v190 offset:50176
	ds_read_b128 v[192:195], v190 offset:51200
	ds_read_b128 v[200:203], v190 offset:52224
	ds_read_b128 v[204:207], v190 offset:53248
	ds_read_b128 v[208:211], v190 offset:54272
	ds_read_b128 v[212:215], v190 offset:55296
	ds_read_b128 v[216:219], v190 offset:56320
	global_load_lds_dwordx4 v[198:199], off
	s_add_i32 m0, s0, 0x2000
	s_add_u32 s30, s30, 0x80080
	v_lshl_add_u64 v[198:199], v[220:221], 0, s[90:91]
	s_addc_u32 s31, s31, 0
	s_add_i32 s0, s6, s4
	global_load_lds_dwordx4 v[198:199], off
	v_lshl_add_u64 v[198:199], s[30:31], 0, v[152:153]
	s_mov_b32 m0, s0
	s_nop 0
	global_load_lds_dwordx4 v[198:199], off
	v_lshl_add_u64 v[198:199], s[30:31], 0, v[148:149]
	s_add_i32 m0, s0, 0x2000
	s_nop 0
	global_load_lds_dwordx4 v[198:199], off
	v_lshl_add_u64 v[198:199], v[222:223], 0, s[90:91]
	s_mov_b32 m0, s40
	s_nop 0
	global_load_lds_dwordx4 v[198:199], off
	v_lshl_add_u64 v[198:199], v[224:225], 0, s[90:91]
	s_mov_b32 m0, s66
	s_nop 0
	global_load_lds_dwordx4 v[198:199], off
	s_setprio 1
	s_waitcnt vmcnt(8) lgkmcnt(0)
	s_barrier
	v_mfma_f32_16x16x32_bf16 v[64:67], v[132:135], v[180:183], v[64:67]
	v_mfma_f32_16x16x32_bf16 v[60:63], v[140:143], v[180:183], v[60:63]
	v_mfma_f32_16x16x32_bf16 v[48:51], v[132:135], v[192:195], v[48:51]
	v_mfma_f32_16x16x32_bf16 v[44:47], v[140:143], v[192:195], v[44:47]
	v_mfma_f32_16x16x32_bf16 v[32:35], v[132:135], v[204:207], v[32:35]
	v_mfma_f32_16x16x32_bf16 v[28:31], v[140:143], v[204:207], v[28:31]
	v_mfma_f32_16x16x32_bf16 v[16:19], v[132:135], v[212:215], v[16:19]
	v_mfma_f32_16x16x32_bf16 v[12:15], v[140:143], v[212:215], v[12:15]
	v_mfma_f32_16x16x32_bf16 v[64:67], v[136:139], v[184:187], v[64:67]
	v_mfma_f32_16x16x32_bf16 v[60:63], v[144:147], v[184:187], v[60:63]
	v_mfma_f32_16x16x32_bf16 v[48:51], v[136:139], v[200:203], v[48:51]
	v_mfma_f32_16x16x32_bf16 v[44:47], v[144:147], v[200:203], v[44:47]
	v_mfma_f32_16x16x32_bf16 v[32:35], v[136:139], v[208:211], v[32:35]
	v_mfma_f32_16x16x32_bf16 v[28:31], v[144:147], v[208:211], v[28:31]
	v_mfma_f32_16x16x32_bf16 v[16:19], v[136:139], v[216:219], v[16:19]
	v_mfma_f32_16x16x32_bf16 v[12:15], v[144:147], v[216:219], v[12:15]
	s_setprio 0
	s_setprio 1
	v_mfma_f32_16x16x32_bf16 v[56:59], v[164:167], v[180:183], v[56:59]
	v_mfma_f32_16x16x32_bf16 v[52:55], v[172:175], v[180:183], v[52:55]
	v_mfma_f32_16x16x32_bf16 v[40:43], v[164:167], v[192:195], v[40:43]
	v_mfma_f32_16x16x32_bf16 v[36:39], v[172:175], v[192:195], v[36:39]
	v_mfma_f32_16x16x32_bf16 v[24:27], v[164:167], v[204:207], v[24:27]
	v_mfma_f32_16x16x32_bf16 v[20:23], v[172:175], v[204:207], v[20:23]
	v_mfma_f32_16x16x32_bf16 v[8:11], v[164:167], v[212:215], v[8:11]
	v_mfma_f32_16x16x32_bf16 v[4:7], v[172:175], v[212:215], v[4:7]
	v_mfma_f32_16x16x32_bf16 v[56:59], v[168:171], v[184:187], v[56:59]
	v_mfma_f32_16x16x32_bf16 v[52:55], v[176:179], v[184:187], v[52:55]
	v_mfma_f32_16x16x32_bf16 v[40:43], v[168:171], v[200:203], v[40:43]
	v_mfma_f32_16x16x32_bf16 v[36:39], v[176:179], v[200:203], v[36:39]
	v_mfma_f32_16x16x32_bf16 v[24:27], v[168:171], v[208:211], v[24:27]
	v_mfma_f32_16x16x32_bf16 v[20:23], v[176:179], v[208:211], v[20:23]
	v_mfma_f32_16x16x32_bf16 v[8:11], v[168:171], v[216:219], v[8:11]
	v_mfma_f32_16x16x32_bf16 v[4:7], v[176:179], v[216:219], v[4:7]
	s_barrier
	s_setprio 0
	s_add_i32 s67, s67, 2
	s_add_u32 s36, s36, 0x100
	s_addc_u32 s37, s37, 0
	s_add_u32 s38, s38, 0x100
	s_addc_u32 s39, s39, 0
	s_cmp_gt_u32 s67, 29
	s_cbranch_scc0 .LBB0_1395
	s_and_b64 vcc, exec, s[28:29]
	s_cbranch_vccz .LBB0_1398
	s_barrier

.LBB0_1441:
	s_add_u32 s0, s62, s30
	s_addc_u32 s6, s63, 0
	s_add_u32 s31, s0, 0x100
	s_addc_u32 s46, s6, 0
	s_and_b64 s[34:35], s[38:39], exec
	s_cselect_b32 s53, s43, s46
	s_cselect_b32 s52, s75, s31
	s_add_u32 s30, s66, s30
	s_addc_u32 s31, s67, 0
	s_add_u32 s34, s30, 0x100
	s_addc_u32 s35, s31, 0
	s_add_i32 s83, 0, 0x10000
	s_and_b64 s[30:31], s[38:39], exec
	s_cselect_b32 s31, s45, s35
	s_cselect_b32 s30, s81, s34
	s_add_i32 s39, 0, 0x14000
	s_add_u32 s46, s0, 0x80080
	s_addc_u32 s47, s6, 0
	s_add_i32 s49, s83, s4
	s_add_i32 m0, s59, 0xc000
	s_add_i32 s97, s59, 0xe000
	s_add_i32 s82, s49, 0x2000
	s_add_u32 s34, s30, 0x80000
	v_add_u32_e32 v144, s83, v3
	v_add_u32_e32 v172, s39, v3
	s_addc_u32 s35, s31, 0
	s_add_i32 s85, s39, s4
	ds_read_b128 v[132:135], v144
	ds_read_b128 v[136:139], v144 offset:1024
	ds_read_b128 v[140:143], v144 offset:2048
	ds_read_b128 v[144:147], v144 offset:3072
	ds_read_b128 v[160:163], v172
	ds_read_b128 v[164:167], v172 offset:1024
	ds_read_b128 v[168:171], v172 offset:2048
	ds_read_b128 v[172:175], v172 offset:3072
	s_add_i32 s84, s85, 0x2000
	s_add_i32 s0, 0, 0x18000
	s_add_i32 s54, 0, 0x1c000
	s_add_u32 vcc_lo, s52, 0x80000
	s_addc_u32 vcc_hi, s53, 0
	s_add_i32 s73, s0, s4
	s_add_i32 s6, s73, 0x2000
	s_add_u32 s38, s30, 0x80080
	s_addc_u32 s39, s31, 0
	s_add_i32 s83, s54, s4
	s_add_i32 s96, s83, 0x2000
	v_lshl_add_u64 v[198:199], s[46:47], 0, v[154:155]
	ds_read_b128 v[176:179], v186
	ds_read_b128 v[180:183], v186 offset:1024
	ds_read_b128 v[188:191], v186 offset:2048
	ds_read_b128 v[192:195], v186 offset:3072
	ds_read_b128 v[200:203], v186 offset:4096
	ds_read_b128 v[204:207], v186 offset:5120
	ds_read_b128 v[208:211], v186 offset:6144
	ds_read_b128 v[212:215], v186 offset:7168
	global_load_lds_dwordx4 v[198:199], off
	v_lshl_add_u64 v[198:199], s[46:47], 0, v[150:151]
	s_mov_b32 m0, s97
	s_nop 0
	global_load_lds_dwordx4 v[198:199], off
	s_setprio 1
	s_waitcnt vmcnt(8) lgkmcnt(0)
	s_barrier
	v_mfma_f32_16x16x32_bf16 v[128:131], v[132:135], v[176:179], v[128:131]
	v_mfma_f32_16x16x32_bf16 v[124:127], v[140:143], v[176:179], v[124:127]
	v_mfma_f32_16x16x32_bf16 v[112:115], v[132:135], v[188:191], v[112:115]
	v_mfma_f32_16x16x32_bf16 v[108:111], v[140:143], v[188:191], v[108:111]
	v_mfma_f32_16x16x32_bf16 v[96:99], v[132:135], v[200:203], v[96:99]
	v_mfma_f32_16x16x32_bf16 v[92:95], v[140:143], v[200:203], v[92:95]
	v_mfma_f32_16x16x32_bf16 v[80:83], v[132:135], v[208:211], v[80:83]
	v_mfma_f32_16x16x32_bf16 v[76:79], v[140:143], v[208:211], v[76:79]
	v_mfma_f32_16x16x32_bf16 v[128:131], v[136:139], v[180:183], v[128:131]
	v_mfma_f32_16x16x32_bf16 v[124:127], v[144:147], v[180:183], v[124:127]
	v_mfma_f32_16x16x32_bf16 v[112:115], v[136:139], v[192:195], v[112:115]
	v_mfma_f32_16x16x32_bf16 v[108:111], v[144:147], v[192:195], v[108:111]
	v_mfma_f32_16x16x32_bf16 v[96:99], v[136:139], v[204:207], v[96:99]
	v_mfma_f32_16x16x32_bf16 v[92:95], v[144:147], v[204:207], v[92:95]
	v_mfma_f32_16x16x32_bf16 v[80:83], v[136:139], v[212:215], v[80:83]
	v_mfma_f32_16x16x32_bf16 v[76:79], v[144:147], v[212:215], v[76:79]
	s_setprio 0
	s_setprio 1
	v_mfma_f32_16x16x32_bf16 v[120:123], v[160:163], v[176:179], v[120:123]
	v_mfma_f32_16x16x32_bf16 v[116:119], v[168:171], v[176:179], v[116:119]
	v_mfma_f32_16x16x32_bf16 v[104:107], v[160:163], v[188:191], v[104:107]
	v_mfma_f32_16x16x32_bf16 v[100:103], v[168:171], v[188:191], v[100:103]
	v_mfma_f32_16x16x32_bf16 v[88:91], v[160:163], v[200:203], v[88:91]
	v_mfma_f32_16x16x32_bf16 v[84:87], v[168:171], v[200:203], v[84:87]
	v_mfma_f32_16x16x32_bf16 v[72:75], v[160:163], v[208:211], v[72:75]
	v_mfma_f32_16x16x32_bf16 v[68:71], v[168:171], v[208:211], v[68:71]
	v_mfma_f32_16x16x32_bf16 v[120:123], v[164:167], v[180:183], v[120:123]
	v_mfma_f32_16x16x32_bf16 v[116:119], v[172:175], v[180:183], v[116:119]
	v_mfma_f32_16x16x32_bf16 v[104:107], v[164:167], v[192:195], v[104:107]
	v_mfma_f32_16x16x32_bf16 v[100:103], v[172:175], v[192:195], v[100:103]
	v_mfma_f32_16x16x32_bf16 v[88:91], v[164:167], v[204:207], v[88:91]
	v_mfma_f32_16x16x32_bf16 v[84:87], v[172:175], v[204:207], v[84:87]
	v_mfma_f32_16x16x32_bf16 v[72:75], v[164:167], v[212:215], v[72:75]
	v_mfma_f32_16x16x32_bf16 v[68:71], v[172:175], v[212:215], v[68:71]
	s_barrier
	s_setprio 0
	s_mov_b32 m0, s49
	v_lshl_add_u64 v[198:199], s[30:31], 0, v[152:153]
	ds_read_b128 v[176:179], v186 offset:16384
	ds_read_b128 v[180:183], v186 offset:17408
	ds_read_b128 v[188:191], v186 offset:18432
	ds_read_b128 v[192:195], v186 offset:19456
	ds_read_b128 v[200:203], v186 offset:20480
	ds_read_b128 v[204:207], v186 offset:21504
	ds_read_b128 v[208:211], v186 offset:22528
	ds_read_b128 v[212:215], v186 offset:23552
	global_load_lds_dwordx4 v[198:199], off
	v_lshl_add_u64 v[216:217], s[30:31], 0, v[148:149]
	s_mov_b32 m0, s82
	v_lshl_add_u64 v[218:219], s[34:35], 0, v[152:153]
	global_load_lds_dwordx4 v[216:217], off
	s_mov_b32 m0, s85
	v_lshl_add_u64 v[220:221], s[52:53], 0, v[150:151]
	global_load_lds_dwordx4 v[218:219], off
	v_lshl_add_u64 v[218:219], s[34:35], 0, v[148:149]
	s_mov_b32 m0, s84
	s_nop 0
	global_load_lds_dwordx4 v[218:219], off
	v_lshl_add_u64 v[218:219], s[52:53], 0, v[154:155]
	s_mov_b32 m0, s59
	s_nop 0
	global_load_lds_dwordx4 v[218:219], off
	s_mov_b32 m0, s40
	s_nop 0
	global_load_lds_dwordx4 v[220:221], off
	s_setprio 1
	s_waitcnt vmcnt(8) lgkmcnt(0)
	s_barrier
	v_mfma_f32_16x16x32_bf16 v[64:67], v[132:135], v[176:179], v[64:67]
	v_mfma_f32_16x16x32_bf16 v[60:63], v[140:143], v[176:179], v[60:63]
	v_mfma_f32_16x16x32_bf16 v[48:51], v[132:135], v[188:191], v[48:51]
	v_mfma_f32_16x16x32_bf16 v[44:47], v[140:143], v[188:191], v[44:47]
	v_mfma_f32_16x16x32_bf16 v[32:35], v[132:135], v[200:203], v[32:35]
	v_mfma_f32_16x16x32_bf16 v[28:31], v[140:143], v[200:203], v[28:31]
	v_mfma_f32_16x16x32_bf16 v[16:19], v[132:135], v[208:211], v[16:19]
	v_mfma_f32_16x16x32_bf16 v[12:15], v[140:143], v[208:211], v[12:15]
	v_mfma_f32_16x16x32_bf16 v[64:67], v[136:139], v[180:183], v[64:67]
	v_mfma_f32_16x16x32_bf16 v[60:63], v[144:147], v[180:183], v[60:63]
	v_mfma_f32_16x16x32_bf16 v[48:51], v[136:139], v[192:195], v[48:51]
	v_mfma_f32_16x16x32_bf16 v[44:47], v[144:147], v[192:195], v[44:47]
	v_mfma_f32_16x16x32_bf16 v[32:35], v[136:139], v[204:207], v[32:35]
	v_mfma_f32_16x16x32_bf16 v[28:31], v[144:147], v[204:207], v[28:31]
	v_mfma_f32_16x16x32_bf16 v[16:19], v[136:139], v[212:215], v[16:19]
	v_mfma_f32_16x16x32_bf16 v[12:15], v[144:147], v[212:215], v[12:15]
	s_setprio 0
	s_setprio 1
	v_mfma_f32_16x16x32_bf16 v[56:59], v[160:163], v[176:179], v[56:59]
	v_mfma_f32_16x16x32_bf16 v[52:55], v[168:171], v[176:179], v[52:55]
	v_mfma_f32_16x16x32_bf16 v[40:43], v[160:163], v[188:191], v[40:43]
	v_mfma_f32_16x16x32_bf16 v[36:39], v[168:171], v[188:191], v[36:39]
	v_mfma_f32_16x16x32_bf16 v[24:27], v[160:163], v[200:203], v[24:27]
	v_mfma_f32_16x16x32_bf16 v[20:23], v[168:171], v[200:203], v[20:23]
	v_mfma_f32_16x16x32_bf16 v[8:11], v[160:163], v[208:211], v[8:11]
	v_mfma_f32_16x16x32_bf16 v[4:7], v[168:171], v[208:211], v[4:7]
	v_mfma_f32_16x16x32_bf16 v[56:59], v[164:167], v[180:183], v[56:59]
	v_mfma_f32_16x16x32_bf16 v[52:55], v[172:175], v[180:183], v[52:55]
	v_mfma_f32_16x16x32_bf16 v[40:43], v[164:167], v[192:195], v[40:43]
	v_mfma_f32_16x16x32_bf16 v[36:39], v[172:175], v[192:195], v[36:39]
	v_mfma_f32_16x16x32_bf16 v[24:27], v[164:167], v[204:207], v[24:27]
	v_mfma_f32_16x16x32_bf16 v[20:23], v[172:175], v[204:207], v[20:23]
	v_mfma_f32_16x16x32_bf16 v[8:11], v[164:167], v[212:215], v[8:11]
	v_mfma_f32_16x16x32_bf16 v[4:7], v[172:175], v[212:215], v[4:7]
	s_barrier
	s_setprio 0
	v_add_u32_e32 v144, s0, v3
	v_add_u32_e32 v172, s54, v3
	ds_read_b128 v[132:135], v144
	ds_read_b128 v[136:139], v144 offset:1024
	ds_read_b128 v[140:143], v144 offset:2048
	ds_read_b128 v[144:147], v144 offset:3072
	ds_read_b128 v[160:163], v172
	ds_read_b128 v[164:167], v172 offset:1024
	ds_read_b128 v[168:171], v172 offset:2048
	ds_read_b128 v[172:175], v172 offset:3072
	s_mov_b32 m0, s55
	v_lshl_add_u64 v[222:223], vcc, 0, v[154:155]
	ds_read_b128 v[176:179], v186 offset:32768
	ds_read_b128 v[180:183], v186 offset:33792
	ds_read_b128 v[188:191], v186 offset:34816
	ds_read_b128 v[192:195], v186 offset:35840
	ds_read_b128 v[200:203], v186 offset:36864
	ds_read_b128 v[204:207], v186 offset:37888
	ds_read_b128 v[208:211], v186 offset:38912
	ds_read_b128 v[212:215], v186 offset:39936
	global_load_lds_dwordx4 v[222:223], off
	v_lshl_add_u64 v[222:223], vcc, 0, v[150:151]
	s_mov_b32 m0, s50
	s_nop 0
	global_load_lds_dwordx4 v[222:223], off
	s_setprio 1
	s_waitcnt vmcnt(8) lgkmcnt(0)
	s_barrier
	v_mfma_f32_16x16x32_bf16 v[128:131], v[132:135], v[176:179], v[128:131]
	v_mfma_f32_16x16x32_bf16 v[124:127], v[140:143], v[176:179], v[124:127]
	v_mfma_f32_16x16x32_bf16 v[112:115], v[132:135], v[188:191], v[112:115]
	v_mfma_f32_16x16x32_bf16 v[108:111], v[140:143], v[188:191], v[108:111]
	v_mfma_f32_16x16x32_bf16 v[96:99], v[132:135], v[200:203], v[96:99]
	v_mfma_f32_16x16x32_bf16 v[92:95], v[140:143], v[200:203], v[92:95]
	v_mfma_f32_16x16x32_bf16 v[80:83], v[132:135], v[208:211], v[80:83]
	v_mfma_f32_16x16x32_bf16 v[76:79], v[140:143], v[208:211], v[76:79]
	v_mfma_f32_16x16x32_bf16 v[128:131], v[136:139], v[180:183], v[128:131]
	v_mfma_f32_16x16x32_bf16 v[124:127], v[144:147], v[180:183], v[124:127]
	v_mfma_f32_16x16x32_bf16 v[112:115], v[136:139], v[192:195], v[112:115]
	v_mfma_f32_16x16x32_bf16 v[108:111], v[144:147], v[192:195], v[108:111]
	v_mfma_f32_16x16x32_bf16 v[96:99], v[136:139], v[204:207], v[96:99]
	v_mfma_f32_16x16x32_bf16 v[92:95], v[144:147], v[204:207], v[92:95]
	v_mfma_f32_16x16x32_bf16 v[80:83], v[136:139], v[212:215], v[80:83]
	v_mfma_f32_16x16x32_bf16 v[76:79], v[144:147], v[212:215], v[76:79]
	s_setprio 0
	s_setprio 1
	v_mfma_f32_16x16x32_bf16 v[120:123], v[160:163], v[176:179], v[120:123]
	v_mfma_f32_16x16x32_bf16 v[116:119], v[168:171], v[176:179], v[116:119]
	v_mfma_f32_16x16x32_bf16 v[104:107], v[160:163], v[188:191], v[104:107]
	v_mfma_f32_16x16x32_bf16 v[100:103], v[168:171], v[188:191], v[100:103]
	v_mfma_f32_16x16x32_bf16 v[88:91], v[160:163], v[200:203], v[88:91]
	v_mfma_f32_16x16x32_bf16 v[84:87], v[168:171], v[200:203], v[84:87]
	v_mfma_f32_16x16x32_bf16 v[72:75], v[160:163], v[208:211], v[72:75]
	v_mfma_f32_16x16x32_bf16 v[68:71], v[168:171], v[208:211], v[68:71]
	v_mfma_f32_16x16x32_bf16 v[120:123], v[164:167], v[180:183], v[120:123]
	v_mfma_f32_16x16x32_bf16 v[116:119], v[172:175], v[180:183], v[116:119]
	v_mfma_f32_16x16x32_bf16 v[104:107], v[164:167], v[192:195], v[104:107]
	v_mfma_f32_16x16x32_bf16 v[100:103], v[172:175], v[192:195], v[100:103]
	v_mfma_f32_16x16x32_bf16 v[88:91], v[164:167], v[204:207], v[88:91]
	v_mfma_f32_16x16x32_bf16 v[84:87], v[172:175], v[204:207], v[84:87]
	v_mfma_f32_16x16x32_bf16 v[72:75], v[164:167], v[212:215], v[72:75]
	v_mfma_f32_16x16x32_bf16 v[68:71], v[172:175], v[212:215], v[68:71]
	s_barrier
	s_setprio 0
	s_mov_b32 m0, s73
	v_lshl_add_u64 v[198:199], v[198:199], 0, s[90:91]
	ds_read_b128 v[176:179], v186 offset:49152
	ds_read_b128 v[180:183], v186 offset:50176
	ds_read_b128 v[188:191], v186 offset:51200
	ds_read_b128 v[192:195], v186 offset:52224
	ds_read_b128 v[200:203], v186 offset:53248
	ds_read_b128 v[204:207], v186 offset:54272
	ds_read_b128 v[208:211], v186 offset:55296
	ds_read_b128 v[212:215], v186 offset:56320
	global_load_lds_dwordx4 v[198:199], off
	v_lshl_add_u64 v[198:199], v[216:217], 0, s[90:91]
	s_mov_b32 m0, s6
	s_nop 0
	global_load_lds_dwordx4 v[198:199], off
	v_lshl_add_u64 v[198:199], s[38:39], 0, v[152:153]
	s_mov_b32 m0, s83
	s_nop 0
	global_load_lds_dwordx4 v[198:199], off
	v_lshl_add_u64 v[198:199], s[38:39], 0, v[148:149]
	s_mov_b32 m0, s96
	s_nop 0
	global_load_lds_dwordx4 v[198:199], off
	v_lshl_add_u64 v[198:199], v[218:219], 0, s[90:91]
	s_mov_b32 m0, s1
	s_nop 0
	global_load_lds_dwordx4 v[198:199], off
	v_lshl_add_u64 v[198:199], v[220:221], 0, s[90:91]
	s_mov_b32 m0, s24
	s_nop 0
	global_load_lds_dwordx4 v[198:199], off
	s_setprio 1
	s_waitcnt vmcnt(8) lgkmcnt(0)
	s_barrier
	v_mfma_f32_16x16x32_bf16 v[64:67], v[132:135], v[176:179], v[64:67]
	v_mfma_f32_16x16x32_bf16 v[60:63], v[140:143], v[176:179], v[60:63]
	v_mfma_f32_16x16x32_bf16 v[48:51], v[132:135], v[188:191], v[48:51]
	v_mfma_f32_16x16x32_bf16 v[44:47], v[140:143], v[188:191], v[44:47]
	v_mfma_f32_16x16x32_bf16 v[32:35], v[132:135], v[200:203], v[32:35]
	v_mfma_f32_16x16x32_bf16 v[28:31], v[140:143], v[200:203], v[28:31]
	v_mfma_f32_16x16x32_bf16 v[16:19], v[132:135], v[208:211], v[16:19]
	v_mfma_f32_16x16x32_bf16 v[12:15], v[140:143], v[208:211], v[12:15]
	v_mfma_f32_16x16x32_bf16 v[64:67], v[136:139], v[180:183], v[64:67]
	v_mfma_f32_16x16x32_bf16 v[60:63], v[144:147], v[180:183], v[60:63]
	v_mfma_f32_16x16x32_bf16 v[48:51], v[136:139], v[192:195], v[48:51]
	v_mfma_f32_16x16x32_bf16 v[44:47], v[144:147], v[192:195], v[44:47]
	v_mfma_f32_16x16x32_bf16 v[32:35], v[136:139], v[204:207], v[32:35]
	v_mfma_f32_16x16x32_bf16 v[28:31], v[144:147], v[204:207], v[28:31]
	v_mfma_f32_16x16x32_bf16 v[16:19], v[136:139], v[212:215], v[16:19]
	v_mfma_f32_16x16x32_bf16 v[12:15], v[144:147], v[212:215], v[12:15]
	s_setprio 0
	s_setprio 1
	v_mfma_f32_16x16x32_bf16 v[56:59], v[160:163], v[176:179], v[56:59]
	v_mfma_f32_16x16x32_bf16 v[52:55], v[168:171], v[176:179], v[52:55]
	v_mfma_f32_16x16x32_bf16 v[40:43], v[160:163], v[188:191], v[40:43]
	v_mfma_f32_16x16x32_bf16 v[36:39], v[168:171], v[188:191], v[36:39]
	v_mfma_f32_16x16x32_bf16 v[24:27], v[160:163], v[200:203], v[24:27]
	v_mfma_f32_16x16x32_bf16 v[20:23], v[168:171], v[200:203], v[20:23]
	v_mfma_f32_16x16x32_bf16 v[8:11], v[160:163], v[208:211], v[8:11]
	v_mfma_f32_16x16x32_bf16 v[4:7], v[168:171], v[208:211], v[4:7]
	v_mfma_f32_16x16x32_bf16 v[56:59], v[164:167], v[180:183], v[56:59]
	v_mfma_f32_16x16x32_bf16 v[52:55], v[172:175], v[180:183], v[52:55]
	v_mfma_f32_16x16x32_bf16 v[40:43], v[164:167], v[192:195], v[40:43]
	v_mfma_f32_16x16x32_bf16 v[36:39], v[172:175], v[192:195], v[36:39]
	v_mfma_f32_16x16x32_bf16 v[24:27], v[164:167], v[204:207], v[24:27]
	v_mfma_f32_16x16x32_bf16 v[20:23], v[172:175], v[204:207], v[20:23]
	v_mfma_f32_16x16x32_bf16 v[8:11], v[164:167], v[212:215], v[8:11]
	v_mfma_f32_16x16x32_bf16 v[4:7], v[172:175], v[212:215], v[4:7]
	s_barrier
	s_setprio 0
	s_movk_i32 s30, 0x100
	s_andn2_b64 vcc, exec, s[36:37]
	s_mov_b64 s[38:39], -1
	s_mov_b64 s[36:37], 0
	s_cbranch_vccz .LBB0_1441
	s_and_b64 vcc, exec, s[28:29]
	s_cbranch_vccz .LBB0_1444
	s_barrier
